# removed store-drain vmcnt(0) at GEMM mainloop starts (stores overlap first operand DMAs)
# speedup vs baseline: 1.0648x; 1.0034x over previous
.LBB0_119:
	s_abs_i32 s10, s23
	s_mul_hi_u32 s11, s10, s21
	s_mul_i32 s11, s11, s14
	s_sub_i32 s10, s10, s11
	s_ashr_i32 s2, s23, 31
	s_sub_i32 s11, s10, s14
	s_cmp_ge_u32 s10, s14
	s_cselect_b32 s10, s11, s10
	s_sub_i32 s11, s10, s14
	s_cmp_ge_u32 s10, s14
	s_cselect_b32 s10, s11, s10
	s_xor_b32 s10, s10, s2
	s_sub_i32 s12, s10, s2
	s_cmpk_gt_i32 s12, 0x3ff
	s_mov_b64 s[10:11], -1
	s_cbranch_scc0 .LBB0_123
	s_lshl_b32 s2, s12, 4
	s_add_i32 s2, s2, 0x7fffc000
	s_and_b32 s2, s2, 0x7fffff80
	v_mov_b32_e32 v14, v196
	s_add_i32 s2, s2, 0x8000
	s_lshl_b32 s10, s23, 7
	s_and_b32 s13, s10, 0x380
	v_lshrrev_b32_e32 v0, 2, v14
	s_mul_i32 s10, s2, 0x1600
	v_and_b32_e32 v0, 12, v0
	s_mul_hi_u32 s11, s2, 0x1600
	s_add_u32 s10, s15, s10
	v_lshrrev_b32_e64 v16, v0, s57
	s_addc_u32 s11, s16, s11
	s_mul_i32 s26, s13, 0x1600
	v_xor_b32_e32 v0, v16, v14
	s_add_u32 s36, s17, s26
	v_lshlrev_b32_e32 v0, 4, v0
	s_addc_u32 s37, s18, 0
	v_ashrrev_i32_e32 v15, 2, v14
	v_and_b32_e32 v0, 48, v0
	v_lshl_add_u64 v[2:3], s[10:11], 0, v[0:1]
	v_add_u32_e32 v8, 64, v15
	v_mov_b64_e32 v[6:7], s[36:37]
	v_mad_i64_i32 v[4:5], s[10:11], v15, s29, v[2:3]
	v_mad_i64_i32 v[2:3], s[10:11], v8, s29, v[2:3]
	v_mad_i64_i32 v[8:9], s[10:11], v8, s29, v[6:7]
	v_and_b32_e32 v11, 15, v14
	v_lshl_add_u32 v80, v14, 4, 0
	v_lshrrev_b32_e32 v12, 1, v14
	s_mov_b32 s10, 0x3ffffc0
	v_and_or_b32 v17, v12, s10, v11
	v_readfirstlane_b32 s10, v80
	v_add_u32_e32 v12, 0x1000, v80
	s_mov_b32 m0, s10
	v_readfirstlane_b32 s10, v12
	global_load_lds_dwordx4 v[4:5], off
	s_mov_b32 m0, s10
	v_mad_i64_i32 v[6:7], s[10:11], v15, s29, v[6:7]
	v_lshl_add_u64 v[6:7], v[6:7], 0, v[0:1]
	v_lshl_add_u64 v[8:9], v[8:9], 0, v[0:1]
	v_add_u32_e32 v0, 0x2000, v80
	v_and_b32_e32 v11, 12, v14
	v_readfirstlane_b32 s10, v0
	v_add_u32_e32 v0, 0x3000, v80
	global_load_lds_dwordx4 v[2:3], off
	s_mov_b32 m0, s10
	v_readfirstlane_b32 s10, v0
	v_add_u32_e32 v0, 0x4000, v80
	v_lshrrev_b32_e32 v10, 4, v14
	v_lshrrev_b32_e64 v11, v11, s57
	global_load_lds_dwordx4 v[6:7], off
	s_mov_b32 m0, s10
	v_readfirstlane_b32 s10, v0
	v_add_u32_e32 v0, 0x5000, v80
	v_xor_b32_e32 v18, v11, v10
	v_lshl_add_u64 v[10:11], v[4:5], 0, 64
	global_load_lds_dwordx4 v[8:9], off
	s_mov_b32 m0, s10
	v_readfirstlane_b32 s10, v0
	v_add_u32_e32 v0, 0x6000, v80
	v_lshl_add_u64 v[12:13], v[2:3], 0, 64
	global_load_lds_dwordx4 v[10:11], off
	s_mov_b32 m0, s10
	v_readfirstlane_b32 s10, v0
	v_add_u32_e32 v0, 0x7000, v80
	v_lshl_add_u64 v[6:7], v[6:7], 0, 64
	global_load_lds_dwordx4 v[12:13], off
	s_mov_b32 m0, s10
	v_readfirstlane_b32 s10, v0
	v_lshl_add_u64 v[8:9], v[8:9], 0, 64
	global_load_lds_dwordx4 v[6:7], off
	s_mov_b32 m0, s10
	s_mov_b32 s27, s3
	global_load_lds_dwordx4 v[8:9], off
	v_lshl_add_u64 v[66:67], v[2:3], 0, s[78:79]
	v_mov_b64_e32 v[2:3], s[26:27]
	v_lshl_add_u64 v[68:69], v[4:5], 0, s[78:79]
	v_mad_i64_i32 v[2:3], s[10:11], v15, s29, v[2:3]
	v_bitop3_b32 v4, v16, 3, v14 bitop3:0x48
	v_lshl_or_b32 v2, v4, 4, v2
	v_lshlrev_b32_e32 v0, 4, v18
	v_lshlrev_b32_e32 v6, 6, v14
	v_lshl_add_u64 v[70:71], s[0:1], 0, v[2:3]
	v_mov_b32_e32 v2, 0
	s_mov_b32 s24, 2
	s_mov_b64 s[36:37], 0x1d00080
	v_and_b32_e32 v82, 0x13c0, v6
	v_and_b32_e32 v0, 48, v0
	v_lshlrev_b32_e32 v81, 6, v17
	s_mov_b32 s25, 0
	s_mov_b64 s[10:11], 0
	v_mov_b32_e32 v3, v2
	v_mov_b32_e32 v4, v2
	v_mov_b32_e32 v5, v2
	v_mov_b32_e32 v6, v2
	v_mov_b32_e32 v7, v2
	v_mov_b32_e32 v8, v2
	v_mov_b32_e32 v9, v2
	v_mov_b32_e32 v10, v2
	v_mov_b32_e32 v11, v2
	v_mov_b32_e32 v12, v2
	v_mov_b32_e32 v13, v2
	v_mov_b32_e32 v14, v2
	v_mov_b32_e32 v15, v2
	v_mov_b32_e32 v16, v2
	v_mov_b32_e32 v17, v2
	v_mov_b32_e32 v18, v2
	v_mov_b32_e32 v19, v2
	v_mov_b32_e32 v20, v2
	v_mov_b32_e32 v21, v2
	v_mov_b32_e32 v22, v2
	v_mov_b32_e32 v23, v2
	v_mov_b32_e32 v24, v2
	v_mov_b32_e32 v25, v2
	v_mov_b32_e32 v26, v2
	v_mov_b32_e32 v27, v2
	v_mov_b32_e32 v28, v2
	v_mov_b32_e32 v29, v2
	v_mov_b32_e32 v30, v2
	v_mov_b32_e32 v31, v2
	v_mov_b32_e32 v32, v2
	v_mov_b32_e32 v33, v2
	v_mov_b32_e32 v34, v2
	v_mov_b32_e32 v35, v2
	v_mov_b32_e32 v36, v2
	v_mov_b32_e32 v37, v2
	v_mov_b32_e32 v38, v2
	v_mov_b32_e32 v39, v2
	v_mov_b32_e32 v40, v2
	v_mov_b32_e32 v41, v2
	v_mov_b32_e32 v42, v2
	v_mov_b32_e32 v43, v2
	v_mov_b32_e32 v44, v2
	v_mov_b32_e32 v45, v2
	v_mov_b32_e32 v46, v2
	v_mov_b32_e32 v47, v2
	v_mov_b32_e32 v48, v2
	v_mov_b32_e32 v49, v2
	v_mov_b32_e32 v50, v2
	v_mov_b32_e32 v51, v2
	v_mov_b32_e32 v52, v2
	v_mov_b32_e32 v53, v2
	v_mov_b32_e32 v54, v2
	v_mov_b32_e32 v55, v2
	v_mov_b32_e32 v56, v2
	v_mov_b32_e32 v57, v2
	v_mov_b32_e32 v58, v2
	v_mov_b32_e32 v59, v2
	v_mov_b32_e32 v60, v2
	v_mov_b32_e32 v61, v2
	v_mov_b32_e32 v62, v2
	v_mov_b32_e32 v63, v2
	v_mov_b32_e32 v64, v2
	v_mov_b32_e32 v65, v2

.LBB0_123:
	s_and_b64 vcc, exec, s[10:11]
	s_cbranch_vccz .LBB0_118
	s_lshr_b32 s10, s12, 3
	s_and_b32 s2, s23, 7
	s_and_b32 s10, s10, 0xfffff8
	v_mov_b32_e32 v22, v196
	s_or_b32 s2, s10, s2
	s_lshl_b32 s10, s2, 8
	v_lshrrev_b32_e32 v0, 2, v22
	s_lshl_b32 s11, s12, 4
	v_and_b32_e32 v0, 12, v0
	s_and_b32 s24, s11, 0x380
	s_ashr_i32 s11, s10, 31
	s_mul_i32 s2, s2, 0x160000
	v_lshrrev_b32_e64 v24, v0, s57
	s_mul_hi_i32 s13, s10, 0x1600
	s_add_u32 s12, s15, s2
	v_xor_b32_e32 v0, v24, v22
	s_addc_u32 s13, s16, s13
	s_mul_i32 s2, s24, 0x1600
	v_lshlrev_b32_e32 v0, 4, v0
	s_add_u32 s26, s17, s2
	v_ashrrev_i32_e32 v23, 2, v22
	v_and_b32_e32 v0, 48, v0
	s_addc_u32 s27, s18, 0
	v_lshl_add_u64 v[2:3], s[12:13], 0, v[0:1]
	v_add_u32_e32 v12, 64, v23
	v_add_u32_e32 v8, 0x80, v23
	v_add_u32_e32 v10, 0xc0, v23
	v_mad_i64_i32 v[4:5], s[12:13], v23, s29, v[2:3]
	v_mad_i64_i32 v[6:7], s[12:13], v12, s29, v[2:3]
	v_mad_i64_i32 v[8:9], s[12:13], v8, s29, v[2:3]
	v_mad_i64_i32 v[2:3], s[12:13], v10, s29, v[2:3]
	v_mov_b64_e32 v[10:11], s[26:27]
	v_mad_i64_i32 v[12:13], s[12:13], v12, s29, v[10:11]
	v_lshl_add_u32 v156, v22, 4, 0
	v_add_u32_e32 v16, 0x1000, v156
	v_readfirstlane_b32 s12, v156
	v_and_b32_e32 v15, 12, v22
	s_mov_b32 m0, s12
	v_readfirstlane_b32 s12, v16
	v_add_u32_e32 v18, 0x2000, v156
	v_lshrrev_b32_e32 v14, 4, v22
	v_lshrrev_b32_e64 v15, v15, s57
	global_load_lds_dwordx4 v[4:5], off
	s_mov_b32 m0, s12
	v_readfirstlane_b32 s12, v18
	v_add_u32_e32 v20, 0x3000, v156
	v_xor_b32_e32 v14, v15, v14
	global_load_lds_dwordx4 v[6:7], off
	s_mov_b32 m0, s12
	v_readfirstlane_b32 s12, v20
	v_lshlrev_b32_e32 v26, 4, v14
	global_load_lds_dwordx4 v[8:9], off
	s_mov_b32 m0, s12
	v_mad_i64_i32 v[10:11], s[12:13], v23, s29, v[10:11]
	v_lshl_add_u64 v[10:11], v[10:11], 0, v[0:1]
	v_lshl_add_u64 v[12:13], v[12:13], 0, v[0:1]
	v_and_b32_e32 v0, 48, v26
	v_add_u32_e32 v26, 0x4000, v156
	global_load_lds_dwordx4 v[2:3], off
	v_readfirstlane_b32 s12, v26
	v_add_u32_e32 v26, 0x5000, v156
	s_mov_b32 m0, s12
	v_readfirstlane_b32 s12, v26
	v_add_u32_e32 v26, 0x6000, v156
	global_load_lds_dwordx4 v[10:11], off
	s_mov_b32 m0, s12
	v_readfirstlane_b32 s12, v26
	v_lshl_add_u64 v[14:15], v[4:5], 0, 64
	global_load_lds_dwordx4 v[12:13], off
	s_mov_b32 m0, s12
	v_lshl_add_u64 v[16:17], v[6:7], 0, 64
	global_load_lds_dwordx4 v[14:15], off
	v_add_u32_e32 v14, 0x7000, v156
	v_lshl_add_u64 v[18:19], v[8:9], 0, 64
	v_readfirstlane_b32 s12, v14
	v_add_u32_e32 v14, 0x8000, v156
	s_mov_b32 m0, s12
	v_readfirstlane_b32 s12, v14
	v_add_u32_e32 v14, 0x9000, v156
	global_load_lds_dwordx4 v[16:17], off
	s_mov_b32 m0, s12
	v_readfirstlane_b32 s12, v14
	v_add_u32_e32 v14, 0xa000, v156
	v_lshl_add_u64 v[20:21], v[2:3], 0, 64
	global_load_lds_dwordx4 v[18:19], off
	s_mov_b32 m0, s12
	v_readfirstlane_b32 s12, v14
	v_lshl_add_u64 v[10:11], v[10:11], 0, 64
	global_load_lds_dwordx4 v[20:21], off
	s_mov_b32 m0, s12
	v_lshl_add_u64 v[12:13], v[12:13], 0, 64
	global_load_lds_dwordx4 v[10:11], off
	v_add_u32_e32 v10, 0xb000, v156
	v_lshl_add_u64 v[146:147], v[2:3], 0, s[78:79]
	v_readfirstlane_b32 s12, v10
	s_mov_b32 m0, s12
	v_mov_b64_e32 v[2:3], s[2:3]
	global_load_lds_dwordx4 v[12:13], off
	v_lshl_add_u64 v[148:149], v[4:5], 0, s[78:79]
	v_mad_i64_i32 v[2:3], s[12:13], v23, s29, v[2:3]
	v_bitop3_b32 v4, v24, 3, v22 bitop3:0x48
	v_lshl_or_b32 v2, v4, 4, v2
	v_lshlrev_b32_e32 v25, 6, v22
	v_lshl_add_u64 v[154:155], s[0:1], 0, v[2:3]
	v_mov_b32_e32 v2, 0
	s_mov_b32 s25, 2
	v_and_b32_e32 v157, 0x13c0, v25
	v_and_b32_e32 v158, 0xffffe3c0, v25
	v_lshl_add_u64 v[150:151], v[6:7], 0, s[78:79]
	v_lshl_add_u64 v[152:153], v[8:9], 0, s[78:79]
	s_mov_b32 s2, 0
	s_mov_b64 s[12:13], 0
	v_mov_b32_e32 v3, v2
	v_mov_b32_e32 v4, v2
	v_mov_b32_e32 v5, v2
	v_mov_b32_e32 v6, v2
	v_mov_b32_e32 v7, v2
	v_mov_b32_e32 v8, v2
	v_mov_b32_e32 v9, v2
	v_mov_b32_e32 v10, v2
	v_mov_b32_e32 v11, v2
	v_mov_b32_e32 v12, v2
	v_mov_b32_e32 v13, v2
	v_mov_b32_e32 v14, v2
	v_mov_b32_e32 v15, v2
	v_mov_b32_e32 v16, v2
	v_mov_b32_e32 v17, v2
	v_mov_b32_e32 v18, v2
	v_mov_b32_e32 v19, v2
	v_mov_b32_e32 v20, v2
	v_mov_b32_e32 v21, v2
	v_mov_b32_e32 v22, v2
	v_mov_b32_e32 v23, v2
	v_mov_b32_e32 v24, v2
	v_mov_b32_e32 v25, v2
	v_mov_b32_e32 v26, v2
	v_mov_b32_e32 v27, v2
	v_mov_b32_e32 v28, v2
	v_mov_b32_e32 v29, v2
	v_mov_b32_e32 v30, v2
	v_mov_b32_e32 v31, v2
	v_mov_b32_e32 v32, v2
	v_mov_b32_e32 v33, v2
	v_mov_b32_e32 v34, v2
	v_mov_b32_e32 v35, v2
	v_mov_b32_e32 v36, v2
	v_mov_b32_e32 v37, v2
	v_mov_b32_e32 v38, v2
	v_mov_b32_e32 v39, v2
	v_mov_b32_e32 v40, v2
	v_mov_b32_e32 v41, v2
	v_mov_b32_e32 v42, v2
	v_mov_b32_e32 v43, v2
	v_mov_b32_e32 v44, v2
	v_mov_b32_e32 v45, v2
	v_mov_b32_e32 v46, v2
	v_mov_b32_e32 v47, v2
	v_mov_b32_e32 v48, v2
	v_mov_b32_e32 v49, v2
	v_mov_b32_e32 v50, v2
	v_mov_b32_e32 v51, v2
	v_mov_b32_e32 v52, v2
	v_mov_b32_e32 v53, v2
	v_mov_b32_e32 v54, v2
	v_mov_b32_e32 v55, v2
	v_mov_b32_e32 v56, v2
	v_mov_b32_e32 v57, v2
	v_mov_b32_e32 v58, v2
	v_mov_b32_e32 v59, v2
	v_mov_b32_e32 v60, v2
	v_mov_b32_e32 v61, v2
	v_mov_b32_e32 v62, v2
	v_mov_b32_e32 v63, v2
	v_mov_b32_e32 v64, v2
	v_mov_b32_e32 v65, v2
	v_mov_b32_e32 v66, v2
	v_mov_b32_e32 v67, v2
	v_mov_b32_e32 v68, v2
	v_mov_b32_e32 v69, v2
	v_mov_b32_e32 v70, v2
	v_mov_b32_e32 v71, v2
	v_mov_b32_e32 v72, v2
	v_mov_b32_e32 v73, v2
	v_mov_b32_e32 v74, v2
	v_mov_b32_e32 v75, v2
	v_mov_b32_e32 v76, v2
	v_mov_b32_e32 v77, v2
	v_mov_b32_e32 v78, v2
	v_mov_b32_e32 v79, v2
	v_mov_b32_e32 v80, v2
	v_mov_b32_e32 v81, v2
	v_mov_b32_e32 v82, v2
	v_mov_b32_e32 v83, v2
	v_mov_b32_e32 v84, v2
	v_mov_b32_e32 v85, v2
	v_mov_b32_e32 v86, v2
	v_mov_b32_e32 v87, v2
	v_mov_b32_e32 v88, v2
	v_mov_b32_e32 v89, v2
	v_mov_b32_e32 v90, v2
	v_mov_b32_e32 v91, v2
	v_mov_b32_e32 v92, v2
	v_mov_b32_e32 v93, v2
	v_mov_b32_e32 v94, v2
	v_mov_b32_e32 v95, v2
	v_mov_b32_e32 v96, v2
	v_mov_b32_e32 v97, v2
	v_mov_b32_e32 v98, v2
	v_mov_b32_e32 v99, v2
	v_mov_b32_e32 v100, v2
	v_mov_b32_e32 v101, v2
	v_mov_b32_e32 v102, v2
	v_mov_b32_e32 v103, v2
	v_mov_b32_e32 v104, v2
	v_mov_b32_e32 v105, v2
	v_mov_b32_e32 v106, v2
	v_mov_b32_e32 v107, v2
	v_mov_b32_e32 v108, v2
	v_mov_b32_e32 v109, v2
	v_mov_b32_e32 v110, v2
	v_mov_b32_e32 v111, v2
	v_mov_b32_e32 v112, v2
	v_mov_b32_e32 v113, v2
	v_mov_b32_e32 v114, v2
	v_mov_b32_e32 v115, v2
	v_mov_b32_e32 v116, v2
	v_mov_b32_e32 v117, v2
	v_mov_b32_e32 v118, v2
	v_mov_b32_e32 v119, v2
	v_mov_b32_e32 v120, v2
	v_mov_b32_e32 v121, v2
	v_mov_b32_e32 v122, v2
	v_mov_b32_e32 v123, v2
	v_mov_b32_e32 v124, v2
	v_mov_b32_e32 v125, v2
	v_mov_b32_e32 v126, v2
	v_mov_b32_e32 v127, v2
	v_mov_b32_e32 v128, v2
	v_mov_b32_e32 v129, v2

.LBB0_141:
	s_mulk_i32 s40, 0xfe
	v_mov_b32_e32 v21, v196
	s_add_i32 s0, s40, s39
	s_add_i32 s0, s0, -1
	v_lshrrev_b32_e32 v0, 2, v21
	v_and_b32_e32 v0, 12, v0
	s_movk_i32 s54, 0x1320
	s_ashr_i32 s1, s0, 31
	v_lshrrev_b32_e64 v32, v0, s54
	s_lshl_b64 s[0:1], s[0:1], 11
	v_xor_b32_e32 v0, v32, v21
	s_add_u32 s44, s23, s0
	v_ashrrev_i32_e32 v2, 2, v21
	v_lshlrev_b32_e32 v0, 4, v0
	s_addc_u32 s45, s24, s1
	v_and_b32_e32 v0, 48, v0
	v_ashrrev_i32_e32 v3, 31, v2
	v_add_u32_e32 v8, s40, v147
	v_lshl_add_u64 v[4:5], s[44:45], 0, v[0:1]
	v_lshlrev_b64 v[2:3], 11, v[2:3]
	v_add_u32_e32 v9, 64, v8
	s_lshl_b32 s0, s41, 7
	v_lshl_add_u64 v[6:7], v[4:5], 0, v[2:3]
	v_cmp_gt_u32_e32 vcc, s38, v8
	v_mov_b32_e32 v23, s36
	v_mov_b32_e32 v24, s27
	v_lshl_add_u64 v[12:13], v[2:3], 0, s[76:77]
	v_add_u32_e32 v15, 0x80, v8
	v_add_u32_e32 v19, 0xc0, v8
	s_ashr_i32 s1, s0, 31
	v_cndmask_b32_e64 v8, 0, 32, vcc
	v_cndmask_b32_e32 v11, v23, v7, vcc
	v_cndmask_b32_e32 v10, v24, v6, vcc
	v_lshl_add_u64 v[4:5], v[4:5], 0, v[12:13]
	v_cmp_gt_u32_e32 vcc, s38, v9
	s_mov_b64 s[44:45], 0x40000
	s_lshl_b64 s[0:1], s[0:1], 11
	v_cndmask_b32_e64 v14, 0, 32, vcc
	v_cndmask_b32_e32 v5, v23, v5, vcc
	v_cndmask_b32_e32 v4, v24, v4, vcc
	v_lshl_add_u64 v[16:17], v[6:7], 0, s[44:45]
	v_cmp_gt_u32_e32 vcc, s38, v15
	s_mov_b64 s[44:45], 0x60000
	v_lshl_add_u32 v151, v21, 4, 0
	s_add_u32 s46, s25, s0
	v_cndmask_b32_e64 v18, 0, 32, vcc
	v_cndmask_b32_e32 v17, v23, v17, vcc
	v_cndmask_b32_e32 v16, v24, v16, vcc
	v_lshl_add_u64 v[6:7], v[6:7], 0, s[44:45]
	v_cmp_gt_u32_e32 vcc, s38, v19
	v_readfirstlane_b32 s44, v151
	v_add_u32_e32 v19, 0x1000, v151
	s_addc_u32 s47, s26, s1
	s_mov_b32 m0, s44
	v_readfirstlane_b32 s44, v19
	v_add_u32_e32 v19, 0x2000, v151
	v_lshl_add_u64 v[12:13], s[46:47], 0, v[12:13]
	global_load_lds_dwordx4 v[10:11], off
	s_mov_b32 m0, s44
	v_readfirstlane_b32 s44, v19
	v_add_u32_e32 v19, 0x3000, v151
	v_lshl_add_u64 v[30:31], s[46:47], 0, v[2:3]
	global_load_lds_dwordx4 v[4:5], off
	s_mov_b32 m0, s44
	v_readfirstlane_b32 s44, v19
	v_lshl_add_u64 v[30:31], v[30:31], 0, v[0:1]
	v_lshl_add_u64 v[12:13], v[12:13], 0, v[0:1]
	v_add_u32_e32 v0, 0x4000, v151
	v_cndmask_b32_e32 v7, v23, v7, vcc
	v_cndmask_b32_e32 v6, v24, v6, vcc
	v_and_b32_e32 v15, 12, v21
	global_load_lds_dwordx4 v[16:17], off
	s_mov_b32 m0, s44
	v_readfirstlane_b32 s44, v0
	v_add_u32_e32 v0, 0x5000, v151
	v_lshrrev_b32_e32 v22, 4, v21
	v_lshrrev_b32_e64 v15, v15, s54
	global_load_lds_dwordx4 v[6:7], off
	s_mov_b32 m0, s44
	v_readfirstlane_b32 s44, v0
	v_add_u32_e32 v0, 0x6000, v151
	v_xor_b32_e32 v15, v15, v22
	v_lshlrev_b32_e32 v22, 1, v8
	v_mov_b32_e32 v23, v1
	global_load_lds_dwordx4 v[30:31], off
	s_mov_b32 m0, s44
	v_readfirstlane_b32 s44, v0
	v_add_u32_e32 v0, 0x7000, v151
	v_lshl_add_u64 v[10:11], v[10:11], 0, v[22:23]
	v_lshlrev_b32_e32 v24, 1, v14
	v_mov_b32_e32 v25, v1
	global_load_lds_dwordx4 v[12:13], off
	s_mov_b32 m0, s44
	v_readfirstlane_b32 s44, v0
	v_add_u32_e32 v0, 0x8000, v151
	v_cndmask_b32_e64 v20, 0, 32, vcc
	v_lshl_add_u64 v[4:5], v[4:5], 0, v[24:25]
	v_lshlrev_b32_e32 v26, 1, v18
	v_mov_b32_e32 v27, v1
	global_load_lds_dwordx4 v[10:11], off
	s_mov_b32 m0, s44
	v_readfirstlane_b32 s44, v0
	v_add_u32_e32 v0, 0x9000, v151
	v_lshl_add_u64 v[16:17], v[16:17], 0, v[26:27]
	v_lshlrev_b32_e32 v28, 1, v20
	v_mov_b32_e32 v29, v1
	global_load_lds_dwordx4 v[4:5], off
	s_mov_b32 m0, s44
	v_readfirstlane_b32 s44, v0
	v_add_u32_e32 v0, 0xa000, v151
	v_lshl_add_u64 v[6:7], v[6:7], 0, v[28:29]
	global_load_lds_dwordx4 v[16:17], off
	s_mov_b32 m0, s44
	v_readfirstlane_b32 s44, v0
	v_add_u32_e32 v0, 0xb000, v151
	v_lshl_add_u64 v[30:31], v[30:31], 0, 64
	global_load_lds_dwordx4 v[6:7], off
	s_mov_b32 m0, s44
	v_readfirstlane_b32 s44, v0
	v_lshl_add_u64 v[12:13], v[12:13], 0, 64
	global_load_lds_dwordx4 v[30:31], off
	s_mov_b32 m0, s44
	v_lshl_add_u64 v[2:3], v[2:3], 0, s[0:1]
	global_load_lds_dwordx4 v[12:13], off
	v_bitop3_b32 v0, v32, 3, v21 bitop3:0x48
	v_lshl_or_b32 v2, v0, 4, v2
	v_lshlrev_b32_e32 v9, 6, v21
	v_lshlrev_b32_e32 v15, 4, v15
	v_lshl_add_u64 v[152:153], s[20:21], 0, v[2:3]
	v_mov_b32_e32 v2, 0
	s_mov_b32 s42, 2
	s_mov_b32 s43, 0
	v_and_b32_e32 v172, 0x13c0, v9
	v_and_b32_e32 v173, 48, v15
	v_and_b32_e32 v174, 0xffffe3c0, v9
	v_lshl_add_u64 v[160:161], v[6:7], 0, v[28:29]
	v_lshl_add_u64 v[162:163], v[10:11], 0, v[22:23]
	v_lshl_add_u64 v[164:165], v[4:5], 0, v[24:25]
	v_lshl_add_u64 v[166:167], v[16:17], 0, v[26:27]
	s_mov_b64 s[0:1], 0
	v_lshlrev_b32_e32 v0, 1, v8
	v_lshlrev_b32_e32 v154, 1, v14
	v_lshlrev_b32_e32 v156, 1, v18
	v_lshlrev_b32_e32 v158, 1, v20
	v_mov_b32_e32 v3, v2
	v_mov_b32_e32 v4, v2
	v_mov_b32_e32 v5, v2
	v_mov_b32_e32 v6, v2
	v_mov_b32_e32 v7, v2
	v_mov_b32_e32 v8, v2
	v_mov_b32_e32 v9, v2
	v_mov_b32_e32 v10, v2
	v_mov_b32_e32 v11, v2
	v_mov_b32_e32 v12, v2
	v_mov_b32_e32 v13, v2
	v_mov_b32_e32 v14, v2
	v_mov_b32_e32 v15, v2
	v_mov_b32_e32 v16, v2
	v_mov_b32_e32 v17, v2
	v_mov_b32_e32 v18, v2
	v_mov_b32_e32 v19, v2
	v_mov_b32_e32 v20, v2
	v_mov_b32_e32 v21, v2
	v_mov_b32_e32 v22, v2
	v_mov_b32_e32 v23, v2
	v_mov_b32_e32 v24, v2
	v_mov_b32_e32 v25, v2
	v_mov_b32_e32 v26, v2
	v_mov_b32_e32 v27, v2
	v_mov_b32_e32 v28, v2
	v_mov_b32_e32 v29, v2
	v_mov_b32_e32 v30, v2
	v_mov_b32_e32 v31, v2
	v_mov_b32_e32 v32, v2
	v_mov_b32_e32 v33, v2
	v_mov_b32_e32 v34, v2
	v_mov_b32_e32 v35, v2
	v_mov_b32_e32 v36, v2
	v_mov_b32_e32 v37, v2
	v_mov_b32_e32 v38, v2
	v_mov_b32_e32 v39, v2
	v_mov_b32_e32 v40, v2
	v_mov_b32_e32 v41, v2
	v_mov_b32_e32 v42, v2
	v_mov_b32_e32 v43, v2
	v_mov_b32_e32 v44, v2
	v_mov_b32_e32 v45, v2
	v_mov_b32_e32 v46, v2
	v_mov_b32_e32 v47, v2
	v_mov_b32_e32 v48, v2
	v_mov_b32_e32 v49, v2
	v_mov_b32_e32 v50, v2
	v_mov_b32_e32 v51, v2
	v_mov_b32_e32 v52, v2
	v_mov_b32_e32 v53, v2
	v_mov_b32_e32 v54, v2
	v_mov_b32_e32 v55, v2
	v_mov_b32_e32 v56, v2
	v_mov_b32_e32 v57, v2
	v_mov_b32_e32 v58, v2
	v_mov_b32_e32 v59, v2
	v_mov_b32_e32 v60, v2
	v_mov_b32_e32 v61, v2
	v_mov_b32_e32 v62, v2
	v_mov_b32_e32 v63, v2
	v_mov_b32_e32 v64, v2
	v_mov_b32_e32 v65, v2
	v_mov_b32_e32 v66, v2
	v_mov_b32_e32 v67, v2
	v_mov_b32_e32 v68, v2
	v_mov_b32_e32 v69, v2
	v_mov_b32_e32 v70, v2
	v_mov_b32_e32 v71, v2
	v_mov_b32_e32 v72, v2
	v_mov_b32_e32 v73, v2
	v_mov_b32_e32 v74, v2
	v_mov_b32_e32 v75, v2
	v_mov_b32_e32 v76, v2
	v_mov_b32_e32 v77, v2
	v_mov_b32_e32 v78, v2
	v_mov_b32_e32 v79, v2
	v_mov_b32_e32 v80, v2
	v_mov_b32_e32 v81, v2
	v_mov_b32_e32 v82, v2
	v_mov_b32_e32 v83, v2
	v_mov_b32_e32 v84, v2
	v_mov_b32_e32 v85, v2
	v_mov_b32_e32 v86, v2
	v_mov_b32_e32 v87, v2
	v_mov_b32_e32 v88, v2
	v_mov_b32_e32 v89, v2
	v_mov_b32_e32 v90, v2
	v_mov_b32_e32 v91, v2
	v_mov_b32_e32 v92, v2
	v_mov_b32_e32 v93, v2
	v_mov_b32_e32 v94, v2
	v_mov_b32_e32 v95, v2
	v_mov_b32_e32 v96, v2
	v_mov_b32_e32 v97, v2
	v_mov_b32_e32 v98, v2
	v_mov_b32_e32 v99, v2
	v_mov_b32_e32 v100, v2
	v_mov_b32_e32 v101, v2
	v_mov_b32_e32 v102, v2
	v_mov_b32_e32 v103, v2
	v_mov_b32_e32 v104, v2
	v_mov_b32_e32 v105, v2
	v_mov_b32_e32 v106, v2
	v_mov_b32_e32 v107, v2
	v_mov_b32_e32 v108, v2
	v_mov_b32_e32 v109, v2
	v_mov_b32_e32 v110, v2
	v_mov_b32_e32 v111, v2
	v_mov_b32_e32 v112, v2
	v_mov_b32_e32 v113, v2
	v_mov_b32_e32 v114, v2
	v_mov_b32_e32 v115, v2
	v_mov_b32_e32 v116, v2
	v_mov_b32_e32 v117, v2
	v_mov_b32_e32 v118, v2
	v_mov_b32_e32 v119, v2
	v_mov_b32_e32 v120, v2
	v_mov_b32_e32 v121, v2
	v_mov_b32_e32 v122, v2
	v_mov_b32_e32 v123, v2
	v_mov_b32_e32 v124, v2
	v_mov_b32_e32 v125, v2
	v_mov_b32_e32 v126, v2
	v_mov_b32_e32 v127, v2
	v_mov_b32_e32 v128, v2
	v_mov_b32_e32 v129, v2

.LBB0_173:
	s_abs_i32 s10, s23
	s_mul_hi_u32 s11, s10, s21
	s_mul_i32 s11, s11, s14
	s_sub_i32 s10, s10, s11
	s_ashr_i32 s2, s23, 31
	s_sub_i32 s11, s10, s14
	s_cmp_ge_u32 s10, s14
	s_cselect_b32 s10, s11, s10
	s_sub_i32 s11, s10, s14
	s_cmp_ge_u32 s10, s14
	s_cselect_b32 s10, s11, s10
	s_xor_b32 s10, s10, s2
	s_sub_i32 s24, s10, s2
	s_cmpk_gt_i32 s24, 0x3ff
	s_mov_b64 s[10:11], -1
	s_cbranch_scc0 .LBB0_177
	s_lshl_b32 s2, s24, 4
	s_add_i32 s2, s2, 0x7fffc000
	v_mov_b32_e32 v16, v196
	s_and_b32 s2, s2, 0x7fffff80
	s_add_i32 s2, s2, 0x8000
	v_lshrrev_b32_e32 v0, 2, v16
	s_lshl_b32 s10, s23, 7
	v_and_b32_e32 v0, 12, v0
	s_and_b32 s25, s10, 0x380
	s_lshl_b64 s[10:11], s[2:3], 11
	v_lshrrev_b32_e64 v18, v0, s57
	s_add_u32 s12, s15, s10
	v_ashrrev_i32_e32 v2, 2, v16
	v_xor_b32_e32 v0, v18, v16
	s_addc_u32 s13, s16, s11
	s_lshl_b32 s2, s25, 11
	v_lshlrev_b32_e32 v0, 4, v0
	v_ashrrev_i32_e32 v3, 31, v2
	s_add_u32 s36, s17, s2
	v_and_b32_e32 v0, 48, v0
	v_lshlrev_b64 v[2:3], 11, v[2:3]
	s_mov_b64 s[40:41], 0x20000
	s_addc_u32 s37, s18, 0
	v_lshl_add_u64 v[4:5], s[12:13], 0, v[0:1]
	v_lshl_add_u64 v[8:9], v[2:3], 0, s[40:41]
	v_and_b32_e32 v10, 15, v16
	v_lshl_add_u32 v126, v16, 4, 0
	v_lshrrev_b32_e32 v11, 1, v16
	s_mov_b32 s12, 0x3ffffc0
	v_lshl_add_u64 v[6:7], v[4:5], 0, v[2:3]
	v_lshl_add_u64 v[4:5], v[4:5], 0, v[8:9]
	v_lshl_add_u64 v[8:9], s[36:37], 0, v[8:9]
	v_and_or_b32 v19, v11, s12, v10
	v_readfirstlane_b32 s12, v126
	v_add_u32_e32 v12, 0x1000, v126
	v_lshl_add_u64 v[14:15], s[36:37], 0, v[2:3]
	s_mov_b32 m0, s12
	v_readfirstlane_b32 s12, v12
	v_lshl_add_u64 v[14:15], v[14:15], 0, v[0:1]
	v_lshl_add_u64 v[8:9], v[8:9], 0, v[0:1]
	v_add_u32_e32 v0, 0x2000, v126
	global_load_lds_dwordx4 v[6:7], off
	s_mov_b32 m0, s12
	v_readfirstlane_b32 s12, v0
	v_add_u32_e32 v0, 0x3000, v126
	global_load_lds_dwordx4 v[4:5], off
	s_mov_b32 m0, s12
	v_readfirstlane_b32 s12, v0
	v_add_u32_e32 v0, 0x4000, v126
	global_load_lds_dwordx4 v[14:15], off
	s_mov_b32 m0, s12
	v_readfirstlane_b32 s12, v0
	v_add_u32_e32 v0, 0x5000, v126
	v_lshl_add_u64 v[10:11], v[6:7], 0, 64
	global_load_lds_dwordx4 v[8:9], off
	s_mov_b32 m0, s12
	v_readfirstlane_b32 s12, v0
	v_add_u32_e32 v0, 0x6000, v126
	v_lshl_add_u64 v[12:13], v[4:5], 0, 64
	global_load_lds_dwordx4 v[10:11], off
	s_mov_b32 m0, s12
	v_readfirstlane_b32 s12, v0
	v_add_u32_e32 v0, 0x7000, v126
	v_lshl_add_u64 v[14:15], v[14:15], 0, 64
	global_load_lds_dwordx4 v[12:13], off
	s_mov_b32 m0, s12
	v_readfirstlane_b32 s12, v0
	v_lshl_add_u64 v[8:9], v[8:9], 0, 64
	global_load_lds_dwordx4 v[14:15], off
	s_mov_b32 m0, s12
	v_and_b32_e32 v20, 12, v16
	global_load_lds_dwordx4 v[8:9], off
	v_lshrrev_b32_e32 v17, 4, v16
	v_lshrrev_b32_e64 v0, v20, s57
	v_lshl_add_u64 v[114:115], v[4:5], 0, s[78:79]
	v_lshl_add_u64 v[2:3], s[2:3], 0, v[2:3]
	v_bitop3_b32 v4, v18, 3, v16 bitop3:0x48
	v_xor_b32_e32 v0, v0, v17
	v_lshl_or_b32 v2, v4, 4, v2
	v_lshlrev_b32_e32 v0, 4, v0
	v_lshlrev_b32_e32 v8, 6, v16
	v_lshl_add_u64 v[118:119], s[0:1], 0, v[2:3]
	v_mov_b32_e32 v2, 0
	s_mov_b32 s26, 2
	v_and_b32_e32 v128, 0x13c0, v8
	v_and_b32_e32 v0, 48, v0
	v_lshlrev_b32_e32 v127, 6, v19
	v_lshl_add_u64 v[116:117], v[6:7], 0, s[78:79]
	s_mov_b32 s27, 0
	s_mov_b64 s[12:13], 0
	v_mov_b32_e32 v3, v2
	v_mov_b32_e32 v4, v2
	v_mov_b32_e32 v5, v2
	v_mov_b32_e32 v6, v2
	v_mov_b32_e32 v7, v2
	v_mov_b32_e32 v8, v2
	v_mov_b32_e32 v9, v2
	v_mov_b32_e32 v18, v2
	v_mov_b32_e32 v19, v2
	v_mov_b32_e32 v20, v2
	v_mov_b32_e32 v21, v2
	v_mov_b32_e32 v22, v2
	v_mov_b32_e32 v23, v2
	v_mov_b32_e32 v24, v2
	v_mov_b32_e32 v25, v2
	v_mov_b32_e32 v26, v2
	v_mov_b32_e32 v27, v2
	v_mov_b32_e32 v28, v2
	v_mov_b32_e32 v29, v2
	v_mov_b32_e32 v34, v2
	v_mov_b32_e32 v35, v2
	v_mov_b32_e32 v36, v2
	v_mov_b32_e32 v37, v2
	v_mov_b32_e32 v38, v2
	v_mov_b32_e32 v39, v2
	v_mov_b32_e32 v40, v2
	v_mov_b32_e32 v41, v2
	v_mov_b32_e32 v42, v2
	v_mov_b32_e32 v43, v2
	v_mov_b32_e32 v44, v2
	v_mov_b32_e32 v45, v2
	v_mov_b32_e32 v46, v2
	v_mov_b32_e32 v47, v2
	v_mov_b32_e32 v48, v2
	v_mov_b32_e32 v49, v2
	v_mov_b32_e32 v50, v2
	v_mov_b32_e32 v51, v2
	v_mov_b32_e32 v52, v2
	v_mov_b32_e32 v53, v2
	v_mov_b32_e32 v54, v2
	v_mov_b32_e32 v55, v2
	v_mov_b32_e32 v56, v2
	v_mov_b32_e32 v57, v2
	v_mov_b32_e32 v58, v2
	v_mov_b32_e32 v59, v2
	v_mov_b32_e32 v60, v2
	v_mov_b32_e32 v61, v2
	v_mov_b32_e32 v62, v2
	v_mov_b32_e32 v63, v2
	v_mov_b32_e32 v64, v2
	v_mov_b32_e32 v65, v2
	v_mov_b32_e32 v66, v2
	v_mov_b32_e32 v67, v2
	v_mov_b32_e32 v68, v2
	v_mov_b32_e32 v69, v2
	v_mov_b32_e32 v70, v2
	v_mov_b32_e32 v71, v2
	v_mov_b32_e32 v72, v2
	v_mov_b32_e32 v73, v2
	v_mov_b32_e32 v74, v2
	v_mov_b32_e32 v75, v2
	v_mov_b32_e32 v76, v2
	v_mov_b32_e32 v77, v2
	s_mov_b64 s[36:37], 0x20040
	s_mov_b64 s[50:51], 0x20080

.LBB0_177:
	s_and_b64 vcc, exec, s[10:11]
	s_cbranch_vccz .LBB0_172
	s_lshr_b32 s10, s24, 3
	s_and_b32 s2, s23, 7
	s_and_b32 s10, s10, 0xfffff8
	v_mov_b32_e32 v20, v196
	s_or_b32 s2, s10, s2
	s_lshl_b32 s10, s2, 8
	v_lshrrev_b32_e32 v0, 2, v20
	v_and_b32_e32 v0, 12, v0
	s_lshl_b32 s2, s24, 4
	s_ashr_i32 s11, s10, 31
	v_lshrrev_b32_e64 v21, v0, s57
	s_and_b32 s24, s2, 0x380
	s_lshl_b64 s[10:11], s[10:11], 11
	v_ashrrev_i32_e32 v2, 2, v20
	v_xor_b32_e32 v0, v21, v20
	s_add_u32 s12, s15, s10
	v_lshlrev_b32_e32 v0, 4, v0
	v_ashrrev_i32_e32 v3, 31, v2
	s_addc_u32 s13, s16, s11
	v_and_b32_e32 v0, 48, v0
	v_lshlrev_b64 v[2:3], 11, v[2:3]
	v_lshl_add_u64 v[4:5], s[12:13], 0, v[0:1]
	v_lshl_add_u64 v[6:7], v[2:3], 0, s[76:77]
	v_lshl_add_u64 v[8:9], v[4:5], 0, v[6:7]
	v_lshl_add_u64 v[4:5], v[4:5], 0, v[2:3]
	s_mov_b64 s[12:13], 0x40000
	v_lshl_add_u64 v[10:11], v[4:5], 0, s[12:13]
	s_mov_b64 s[12:13], 0x60000
	v_lshl_add_u32 v156, v20, 4, 0
	v_lshl_add_u64 v[12:13], v[4:5], 0, s[12:13]
	v_readfirstlane_b32 s12, v156
	v_add_u32_e32 v16, 0x1000, v156
	s_lshl_b32 s2, s24, 11
	v_and_b32_e32 v15, 12, v20
	s_mov_b32 m0, s12
	v_readfirstlane_b32 s12, v16
	v_add_u32_e32 v18, 0x2000, v156
	s_add_u32 s26, s17, s2
	v_lshrrev_b32_e32 v14, 4, v20
	v_lshrrev_b32_e64 v15, v15, s57
	global_load_lds_dwordx4 v[4:5], off
	s_mov_b32 m0, s12
	v_readfirstlane_b32 s12, v18
	s_addc_u32 s27, s18, 0
	v_xor_b32_e32 v14, v15, v14
	global_load_lds_dwordx4 v[8:9], off
	s_mov_b32 m0, s12
	s_mov_b64 s[12:13], 0x40040
	v_add_u32_e32 v18, 0x3000, v156
	v_lshl_add_u64 v[6:7], s[26:27], 0, v[6:7]
	v_lshlrev_b32_e32 v23, 4, v14
	global_load_lds_dwordx4 v[10:11], off
	v_lshl_add_u64 v[10:11], v[4:5], 0, s[12:13]
	v_readfirstlane_b32 s12, v18
	v_lshl_add_u64 v[18:19], s[26:27], 0, v[2:3]
	s_mov_b32 m0, s12
	s_mov_b64 s[12:13], 0x60040
	v_lshl_add_u64 v[18:19], v[18:19], 0, v[0:1]
	v_lshl_add_u64 v[6:7], v[6:7], 0, v[0:1]
	v_and_b32_e32 v0, 48, v23
	v_add_u32_e32 v23, 0x4000, v156
	global_load_lds_dwordx4 v[12:13], off
	v_lshl_add_u64 v[12:13], v[4:5], 0, s[12:13]
	v_readfirstlane_b32 s12, v23
	v_add_u32_e32 v23, 0x5000, v156
	s_mov_b32 m0, s12
	v_readfirstlane_b32 s12, v23
	v_add_u32_e32 v23, 0x6000, v156
	global_load_lds_dwordx4 v[18:19], off
	s_mov_b32 m0, s12
	v_readfirstlane_b32 s12, v23
	v_lshl_add_u64 v[14:15], v[4:5], 0, 64
	global_load_lds_dwordx4 v[6:7], off
	s_mov_b32 m0, s12
	v_lshl_add_u64 v[16:17], v[8:9], 0, 64
	global_load_lds_dwordx4 v[14:15], off
	v_add_u32_e32 v14, 0x7000, v156
	v_lshl_add_u64 v[18:19], v[18:19], 0, 64
	v_readfirstlane_b32 s12, v14
	v_add_u32_e32 v14, 0x8000, v156
	s_mov_b32 m0, s12
	v_readfirstlane_b32 s12, v14
	global_load_lds_dwordx4 v[16:17], off
	s_mov_b32 m0, s12
	v_lshl_add_u64 v[6:7], v[6:7], 0, 64
	global_load_lds_dwordx4 v[10:11], off
	v_add_u32_e32 v10, 0x9000, v156
	v_lshl_add_u64 v[148:149], v[4:5], 0, s[78:79]
	v_readfirstlane_b32 s12, v10
	v_add_u32_e32 v10, 0xa000, v156
	s_mov_b32 m0, s12
	v_readfirstlane_b32 s12, v10
	v_add_u32_e32 v10, 0xb000, v156
	global_load_lds_dwordx4 v[12:13], off
	s_mov_b32 m0, s12
	v_readfirstlane_b32 s12, v10
	global_load_lds_dwordx4 v[18:19], off
	s_mov_b32 m0, s12
	s_mov_b64 s[12:13], 0x60080
	global_load_lds_dwordx4 v[6:7], off
	v_lshl_add_u64 v[146:147], v[4:5], 0, s[12:13]
	s_mov_b64 s[12:13], 0x40080
	v_lshl_add_u64 v[152:153], v[4:5], 0, s[12:13]
	v_lshl_add_u64 v[2:3], s[2:3], 0, v[2:3]
	v_bitop3_b32 v4, v21, 3, v20 bitop3:0x48
	v_lshl_or_b32 v2, v4, 4, v2
	v_lshlrev_b32_e32 v22, 6, v20
	v_lshl_add_u64 v[154:155], s[8:9], 0, v[2:3]
	v_mov_b32_e32 v2, 0
	s_mov_b32 s25, 2
	v_and_b32_e32 v157, 0x13c0, v22
	v_and_b32_e32 v158, 0xffffe3c0, v22
	v_lshl_add_u64 v[150:151], v[8:9], 0, s[78:79]
	s_mov_b32 s2, 0
	s_mov_b64 s[12:13], 0
	v_mov_b32_e32 v3, v2
	v_mov_b32_e32 v4, v2
	v_mov_b32_e32 v5, v2
	v_mov_b32_e32 v6, v2
	v_mov_b32_e32 v7, v2
	v_mov_b32_e32 v8, v2
	v_mov_b32_e32 v9, v2
	v_mov_b32_e32 v10, v2
	v_mov_b32_e32 v11, v2
	v_mov_b32_e32 v12, v2
	v_mov_b32_e32 v13, v2
	v_mov_b32_e32 v14, v2
	v_mov_b32_e32 v15, v2
	v_mov_b32_e32 v16, v2
	v_mov_b32_e32 v17, v2
	v_mov_b32_e32 v18, v2
	v_mov_b32_e32 v19, v2
	v_mov_b32_e32 v20, v2
	v_mov_b32_e32 v21, v2
	v_mov_b32_e32 v22, v2
	v_mov_b32_e32 v23, v2
	v_mov_b32_e32 v24, v2
	v_mov_b32_e32 v25, v2
	v_mov_b32_e32 v26, v2
	v_mov_b32_e32 v27, v2
	v_mov_b32_e32 v28, v2
	v_mov_b32_e32 v29, v2
	v_mov_b32_e32 v30, v2
	v_mov_b32_e32 v31, v2
	v_mov_b32_e32 v32, v2
	v_mov_b32_e32 v33, v2
	v_mov_b32_e32 v34, v2
	v_mov_b32_e32 v35, v2
	v_mov_b32_e32 v36, v2
	v_mov_b32_e32 v37, v2
	v_mov_b32_e32 v38, v2
	v_mov_b32_e32 v39, v2
	v_mov_b32_e32 v40, v2
	v_mov_b32_e32 v41, v2
	v_mov_b32_e32 v42, v2
	v_mov_b32_e32 v43, v2
	v_mov_b32_e32 v44, v2
	v_mov_b32_e32 v45, v2
	v_mov_b32_e32 v46, v2
	v_mov_b32_e32 v47, v2
	v_mov_b32_e32 v48, v2
	v_mov_b32_e32 v49, v2
	v_mov_b32_e32 v50, v2
	v_mov_b32_e32 v51, v2
	v_mov_b32_e32 v52, v2
	v_mov_b32_e32 v53, v2
	v_mov_b32_e32 v54, v2
	v_mov_b32_e32 v55, v2
	v_mov_b32_e32 v56, v2
	v_mov_b32_e32 v57, v2
	v_mov_b32_e32 v58, v2
	v_mov_b32_e32 v59, v2
	v_mov_b32_e32 v60, v2
	v_mov_b32_e32 v61, v2
	v_mov_b32_e32 v62, v2
	v_mov_b32_e32 v63, v2
	v_mov_b32_e32 v64, v2
	v_mov_b32_e32 v65, v2
	v_mov_b32_e32 v66, v2
	v_mov_b32_e32 v67, v2
	v_mov_b32_e32 v68, v2
	v_mov_b32_e32 v69, v2
	v_mov_b32_e32 v70, v2
	v_mov_b32_e32 v71, v2
	v_mov_b32_e32 v72, v2
	v_mov_b32_e32 v73, v2
	v_mov_b32_e32 v74, v2
	v_mov_b32_e32 v75, v2
	v_mov_b32_e32 v76, v2
	v_mov_b32_e32 v77, v2
	v_mov_b32_e32 v78, v2
	v_mov_b32_e32 v79, v2
	v_mov_b32_e32 v80, v2
	v_mov_b32_e32 v81, v2
	v_mov_b32_e32 v82, v2
	v_mov_b32_e32 v83, v2
	v_mov_b32_e32 v84, v2
	v_mov_b32_e32 v85, v2
	v_mov_b32_e32 v86, v2
	v_mov_b32_e32 v87, v2
	v_mov_b32_e32 v88, v2
	v_mov_b32_e32 v89, v2
	v_mov_b32_e32 v90, v2
	v_mov_b32_e32 v91, v2
	v_mov_b32_e32 v92, v2
	v_mov_b32_e32 v93, v2
	v_mov_b32_e32 v94, v2
	v_mov_b32_e32 v95, v2
	v_mov_b32_e32 v96, v2
	v_mov_b32_e32 v97, v2
	v_mov_b32_e32 v98, v2
	v_mov_b32_e32 v99, v2
	v_mov_b32_e32 v100, v2
	v_mov_b32_e32 v101, v2
	v_mov_b32_e32 v102, v2
	v_mov_b32_e32 v103, v2
	v_mov_b32_e32 v104, v2
	v_mov_b32_e32 v105, v2
	v_mov_b32_e32 v106, v2
	v_mov_b32_e32 v107, v2
	v_mov_b32_e32 v108, v2
	v_mov_b32_e32 v109, v2
	v_mov_b32_e32 v110, v2
	v_mov_b32_e32 v111, v2
	v_mov_b32_e32 v112, v2
	v_mov_b32_e32 v113, v2
	v_mov_b32_e32 v114, v2
	v_mov_b32_e32 v115, v2
	v_mov_b32_e32 v116, v2
	v_mov_b32_e32 v117, v2
	v_mov_b32_e32 v118, v2
	v_mov_b32_e32 v119, v2
	v_mov_b32_e32 v120, v2
	v_mov_b32_e32 v121, v2
	v_mov_b32_e32 v122, v2
	v_mov_b32_e32 v123, v2
	v_mov_b32_e32 v124, v2
	v_mov_b32_e32 v125, v2
	v_mov_b32_e32 v126, v2
	v_mov_b32_e32 v127, v2
	v_mov_b32_e32 v128, v2
	v_mov_b32_e32 v129, v2

.LBB0_190:
	v_mov_b32_e32 v16, v196
	s_lshl_b32 s2, s26, 21
	v_lshrrev_b32_e32 v0, 2, v16
	v_and_b32_e32 v0, 12, v0
	v_lshrrev_b32_e64 v18, v0, s57
	v_ashrrev_i32_e32 v2, 2, v16
	v_xor_b32_e32 v0, v18, v16
	s_or_b32 s2, s2, s27
	v_lshlrev_b32_e32 v0, 4, v0
	v_ashrrev_i32_e32 v3, 31, v2
	s_add_u32 s12, s17, s2
	v_and_b32_e32 v0, 48, v0
	v_lshlrev_b64 v[2:3], 11, v[2:3]
	s_addc_u32 s13, s18, 0
	v_lshl_add_u64 v[4:5], s[8:9], 0, v[0:1]
	v_lshl_add_u64 v[8:9], v[2:3], 0, s[54:55]
	v_and_b32_e32 v10, 15, v16
	v_lshl_add_u32 v159, v16, 4, 0
	v_lshrrev_b32_e32 v11, 1, v16
	s_mov_b32 s36, 0x3ffffc0
	v_lshl_add_u64 v[6:7], v[4:5], 0, v[2:3]
	v_lshl_add_u64 v[4:5], v[4:5], 0, v[8:9]
	v_lshl_add_u64 v[8:9], s[12:13], 0, v[8:9]
	v_and_or_b32 v19, v11, s36, v10
	v_readfirstlane_b32 s36, v159
	v_add_u32_e32 v12, 0x1000, v159
	v_lshl_add_u64 v[14:15], s[12:13], 0, v[2:3]
	s_mov_b32 m0, s36
	v_readfirstlane_b32 s36, v12
	v_lshl_add_u64 v[14:15], v[14:15], 0, v[0:1]
	v_lshl_add_u64 v[8:9], v[8:9], 0, v[0:1]
	v_add_u32_e32 v0, 0x2000, v159
	global_load_lds_dwordx4 v[6:7], off
	s_mov_b32 m0, s36
	v_readfirstlane_b32 s12, v0
	v_add_u32_e32 v0, 0x3000, v159
	global_load_lds_dwordx4 v[4:5], off
	s_mov_b32 m0, s12
	v_readfirstlane_b32 s12, v0
	v_add_u32_e32 v0, 0x4000, v159
	global_load_lds_dwordx4 v[14:15], off
	s_mov_b32 m0, s12
	v_readfirstlane_b32 s12, v0
	v_add_u32_e32 v0, 0x5000, v159
	v_lshl_add_u64 v[10:11], v[6:7], 0, 64
	global_load_lds_dwordx4 v[8:9], off
	s_mov_b32 m0, s12
	v_readfirstlane_b32 s12, v0
	v_add_u32_e32 v0, 0x6000, v159
	v_lshl_add_u64 v[12:13], v[4:5], 0, 64
	global_load_lds_dwordx4 v[10:11], off
	s_mov_b32 m0, s12
	v_readfirstlane_b32 s12, v0
	v_add_u32_e32 v0, 0x7000, v159
	v_lshl_add_u64 v[14:15], v[14:15], 0, 64
	global_load_lds_dwordx4 v[12:13], off
	s_mov_b32 m0, s12
	v_readfirstlane_b32 s12, v0
	v_lshl_add_u64 v[8:9], v[8:9], 0, 64
	global_load_lds_dwordx4 v[14:15], off
	s_mov_b32 m0, s12
	v_and_b32_e32 v0, 12, v16
	global_load_lds_dwordx4 v[8:9], off
	v_lshrrev_b32_e32 v17, 4, v16
	v_lshrrev_b32_e64 v0, v0, s57
	v_xor_b32_e32 v0, v0, v17
	v_lshl_add_u64 v[144:145], v[4:5], 0, s[78:79]
	v_bitop3_b32 v4, v18, 3, v16 bitop3:0x48
	v_lshlrev_b32_e32 v0, 4, v0
	v_lshlrev_b32_e32 v8, 6, v16
	v_lshl_or_b32 v2, v4, 4, v2
	s_mov_b32 s2, 2
	v_and_b32_e32 v158, 0x13c0, v8
	v_and_b32_e32 v0, 48, v0
	v_lshlrev_b32_e32 v77, 6, v19
	v_lshl_add_u64 v[146:147], v[6:7], 0, s[78:79]
	v_lshl_add_u64 v[148:149], s[10:11], 0, v[2:3]
	s_mov_b64 s[12:13], 0
	s_mov_b32 s36, 0
	v_mov_b32_e32 v2, 0
	v_mov_b32_e32 v3, v75
	v_mov_b32_e32 v4, v75
	v_mov_b32_e32 v5, v75
	v_mov_b32_e32 v6, 0
	v_mov_b32_e32 v7, v75
	v_mov_b32_e32 v8, v75
	v_mov_b32_e32 v9, v75
	v_mov_b32_e32 v10, 0
	v_mov_b32_e32 v11, v75
	v_mov_b32_e32 v12, v75
	v_mov_b32_e32 v13, v75
	v_mov_b32_e32 v14, 0
	v_mov_b32_e32 v15, v75
	v_mov_b32_e32 v16, v75
	v_mov_b32_e32 v17, v75
	v_mov_b32_e32 v18, 0
	v_mov_b32_e32 v19, v75
	v_mov_b32_e32 v20, v75
	v_mov_b32_e32 v21, v75
	v_mov_b32_e32 v22, 0
	v_mov_b32_e32 v23, v75
	v_mov_b32_e32 v24, v75
	v_mov_b32_e32 v25, v75
	v_mov_b32_e32 v26, 0
	v_mov_b32_e32 v27, v75
	v_mov_b32_e32 v28, v75
	v_mov_b32_e32 v29, v75
	v_mov_b32_e32 v34, 0
	v_mov_b32_e32 v35, v75
	v_mov_b32_e32 v36, v75
	v_mov_b32_e32 v37, v75
	v_mov_b32_e32 v30, 0
	v_mov_b32_e32 v31, v75
	v_mov_b32_e32 v32, v75
	v_mov_b32_e32 v33, v75
	v_mov_b32_e32 v38, 0
	v_mov_b32_e32 v39, v75
	v_mov_b32_e32 v40, v75
	v_mov_b32_e32 v41, v75
	v_mov_b32_e32 v42, 0
	v_mov_b32_e32 v43, v75
	v_mov_b32_e32 v44, v75
	v_mov_b32_e32 v45, v75
	v_mov_b32_e32 v46, 0
	v_mov_b32_e32 v47, v75
	v_mov_b32_e32 v48, v75
	v_mov_b32_e32 v49, v75
	v_mov_b32_e32 v50, 0
	v_mov_b32_e32 v51, v75
	v_mov_b32_e32 v52, v75
	v_mov_b32_e32 v53, v75
	v_mov_b32_e32 v54, 0
	v_mov_b32_e32 v55, v75
	v_mov_b32_e32 v56, v75
	v_mov_b32_e32 v57, v75
	v_mov_b32_e32 v58, 0
	v_mov_b32_e32 v59, v75
	v_mov_b32_e32 v60, v75
	v_mov_b32_e32 v61, v75
	v_mov_b32_e32 v62, 0
	v_mov_b32_e32 v63, v75
	v_mov_b32_e32 v64, v75
	v_mov_b32_e32 v65, v75

.LBB0_199:
	s_abs_i32 s1, s15
	s_mul_hi_u32 s2, s1, s14
	s_mul_i32 s8, s2, s10
	s_sub_i32 s1, s1, s8
	s_ashr_i32 s0, s15, 31
	s_add_i32 s8, s2, 1
	s_sub_i32 s9, s1, s10
	s_cmp_ge_u32 s1, s10
	s_cselect_b32 s2, s8, s2
	s_cselect_b32 s1, s9, s1
	s_add_i32 s8, s2, 1
	s_cmp_ge_u32 s1, s10
	s_cselect_b32 s1, s8, s2
	s_xor_b32 s1, s1, s0
	s_sub_i32 s0, s1, s0
	s_mul_i32 s1, s0, s10
	s_sub_i32 s18, s15, s1
	s_cmp_eq_u32 s0, 1
	s_mov_b32 s1, 0x8b7c000
	s_cselect_b32 s1, s1, 0xac7c000
	s_cselect_b32 s2, s81, 0x1a81c000
	s_cmp_eq_u32 s0, 0
	s_cselect_b32 s1, 0x1871c000, s1
	v_readlane_b32 s22, v225, 48
	s_cselect_b32 s2, 0xe21c000, s2
	v_readlane_b32 s23, v225, 49
	s_add_u32 s8, s22, s1
	s_addc_u32 s9, s23, 0
	s_ashr_i32 s1, s0, 31
	s_lshl_b64 s[0:1], s[0:1], 20
	s_add_u32 s19, s12, s0
	s_addc_u32 s20, s13, s1
	s_add_u32 s17, s22, s2
	s_addc_u32 s16, s23, 0
	s_cmpk_gt_i32 s18, 0x3ff
	s_mov_b64 s[0:1], -1
	s_cbranch_scc0 .LBB0_201
	s_lshl_b32 s0, s18, 4
	s_add_i32 s0, s0, 0x7fffc000
	s_and_b32 s0, s0, 0x7fffff80
	s_add_i32 s2, s0, 0x8000
	s_lshl_b32 s0, s15, 7
	v_mov_b32_e32 v10, v196
	s_and_b32 s0, s0, 0x380
	s_lshl_b64 s[22:23], s[2:3], 10
	s_add_u32 s22, s8, s22
	v_lshrrev_b32_e32 v0, 2, v10
	v_and_b32_e32 v0, 12, v0
	s_addc_u32 s23, s9, s23
	s_lshl_b32 s1, s0, 10
	v_lshrrev_b32_e64 v0, v0, s57
	s_add_u32 s24, s19, s1
	v_xor_b32_e32 v0, v0, v10
	v_and_b32_e32 v13, 15, v10
	v_lshrrev_b32_e32 v14, 1, v10
	s_mov_b32 s1, 0x3ffffc0
	v_ashrrev_i32_e32 v2, 2, v10
	v_lshlrev_b32_e32 v0, 4, v0
	v_and_or_b32 v15, v14, s1, v13
	v_and_b32_e32 v13, 12, v10
	v_lshrrev_b32_e32 v12, 4, v10
	v_and_b32_e32 v0, 48, v0
	v_ashrrev_i32_e32 v3, 31, v2
	v_lshl_add_u32 v11, v10, 4, 0
	v_lshrrev_b32_e64 v13, v13, s57
	v_lshl_add_u64 v[4:5], s[22:23], 0, v[0:1]
	v_lshlrev_b64 v[6:7], 10, v[2:3]
	s_mov_b64 s[22:23], 0x10000
	v_xor_b32_e32 v12, v13, v12
	v_readfirstlane_b32 s36, v11
	v_add_u32_e32 v13, 0x1000, v11
	s_addc_u32 s25, s20, 0
	v_lshl_add_u64 v[2:3], v[4:5], 0, v[6:7]
	v_lshl_add_u64 v[8:9], v[6:7], 0, s[22:23]
	v_lshlrev_b32_e32 v12, 4, v12
	s_mov_b32 m0, s36
	v_readfirstlane_b32 s37, v13
	v_add_u32_e32 v14, 0x2000, v11
	v_lshl_add_u64 v[4:5], v[4:5], 0, v[8:9]
	v_lshl_add_u64 v[8:9], s[24:25], 0, v[8:9]
	global_load_lds_dwordx4 v[2:3], off
	s_mov_b32 m0, s37
	v_lshl_add_u64 v[6:7], s[24:25], 0, v[6:7]
	v_and_b32_e32 v32, 48, v12
	v_readfirstlane_b32 s38, v14
	v_add_u32_e32 v12, 0x3000, v11
	global_load_lds_dwordx4 v[4:5], off
	v_lshl_add_u64 v[6:7], v[6:7], 0, v[0:1]
	v_lshl_add_u64 v[8:9], v[8:9], 0, v[0:1]
	s_mov_b32 m0, s38
	v_readfirstlane_b32 s39, v12
	v_add_u32_e32 v0, 0x4000, v11
	global_load_lds_dwordx4 v[6:7], off
	s_mov_b32 m0, s39
	v_readfirstlane_b32 s24, v0
	v_add_u32_e32 v0, 0x5000, v11
	v_lshl_add_u64 v[16:17], v[2:3], 0, 64
	global_load_lds_dwordx4 v[8:9], off
	s_mov_b32 m0, s24
	v_readfirstlane_b32 s25, v0
	v_add_u32_e32 v0, 0x6000, v11
	v_lshl_add_u64 v[18:19], v[4:5], 0, 64
	global_load_lds_dwordx4 v[16:17], off
	s_mov_b32 m0, s25
	v_readfirstlane_b32 s26, v0
	v_add_u32_e32 v0, 0x7000, v11
	v_lshl_add_u64 v[20:21], v[6:7], 0, 64
	global_load_lds_dwordx4 v[18:19], off
	s_mov_b32 m0, s26
	v_readfirstlane_b32 s27, v0
	v_lshl_add_u64 v[16:17], v[8:9], 0, 64
	global_load_lds_dwordx4 v[20:21], off
	s_mov_b32 m0, s27
	v_add_u32_e32 v0, 0x8000, v11
	global_load_lds_dwordx4 v[16:17], off
	v_add_u32_e32 v26, 0x9000, v11
	v_readfirstlane_b32 s23, v0
	v_lshl_add_u64 v[22:23], v[2:3], 0, s[78:79]
	s_waitcnt vmcnt(4) lgkmcnt(0)
	s_barrier
	v_add_u32_e32 v25, 0xa000, v11
	s_mov_b32 m0, s23
	v_readfirstlane_b32 s22, v26
	v_lshl_add_u64 v[20:21], v[4:5], 0, s[78:79]
	v_add_u32_e32 v24, 0xb000, v11
	global_load_lds_dwordx4 v[22:23], off
	s_mov_b32 m0, s22
	v_readfirstlane_b32 s21, v25
	v_lshlrev_b32_e32 v10, 6, v10
	v_lshl_add_u64 v[16:17], v[6:7], 0, s[78:79]
	global_load_lds_dwordx4 v[20:21], off
	s_mov_b32 m0, s21
	v_readfirstlane_b32 s1, v24
	v_and_b32_e32 v10, 0x13c0, v10
	v_lshlrev_b32_e32 v15, 6, v15
	v_lshl_add_u64 v[18:19], v[8:9], 0, s[78:79]
	global_load_lds_dwordx4 v[16:17], off
	s_mov_b32 m0, s1
	v_add3_u32 v0, 0, v10, v32
	global_load_lds_dwordx4 v[18:19], off
	v_add3_u32 v10, 0, v15, v32
	v_lshl_add_u64 v[88:89], v[2:3], 0, s[84:85]
	ds_read_b128 v[16:19], v0 offset:8192
	ds_read_b128 v[20:23], v0 offset:9216
	ds_read_b128 v[24:27], v0 offset:10240
	ds_read_b128 v[28:31], v0 offset:11264
	ds_read_b128 v[32:35], v10
	ds_read_b128 v[36:39], v10 offset:1024
	ds_read_b128 v[40:43], v10 offset:2048
	ds_read_b128 v[44:47], v10 offset:3072
	s_waitcnt vmcnt(4) lgkmcnt(0)
	s_barrier
	s_mov_b32 m0, s36
	v_lshl_add_u64 v[90:91], v[4:5], 0, s[84:85]
	global_load_lds_dwordx4 v[88:89], off
	s_mov_b32 m0, s37
	v_lshl_add_u64 v[86:87], v[6:7], 0, s[84:85]
	global_load_lds_dwordx4 v[90:91], off
	s_mov_b32 m0, s38
	v_lshl_add_u64 v[84:85], v[8:9], 0, s[84:85]
	global_load_lds_dwordx4 v[86:87], off
	s_mov_b32 m0, s39
	s_mov_b64 s[40:41], 0x100
	global_load_lds_dwordx4 v[84:85], off
	s_waitcnt lgkmcnt(0)
	s_setprio 1
	v_mfma_f32_16x16x32_bf16 v[48:51], v[16:19], v[32:35], 0
	v_lshl_add_u64 v[116:117], v[2:3], 0, s[40:41]
	s_mov_b32 m0, s24
	v_lshl_add_u64 v[118:119], v[4:5], 0, s[40:41]
	v_mfma_f32_16x16x32_bf16 v[52:55], v[20:23], v[32:35], 0
	v_lshl_add_u64 v[114:115], v[6:7], 0, s[40:41]
	v_lshl_add_u64 v[112:113], v[8:9], 0, s[40:41]
	s_mov_b64 s[40:41], 0x140
	v_mfma_f32_16x16x32_bf16 v[56:59], v[24:27], v[32:35], 0
	v_lshl_add_u64 v[124:125], v[2:3], 0, s[40:41]
	v_lshl_add_u64 v[126:127], v[4:5], 0, s[40:41]
	v_lshl_add_u64 v[122:123], v[6:7], 0, s[40:41]
	v_mfma_f32_16x16x32_bf16 v[32:35], v[28:31], v[32:35], 0
	v_lshl_add_u64 v[120:121], v[8:9], 0, s[40:41]
	s_mov_b64 s[40:41], 0x180
	v_readlane_b32 s88, v225, 56
	v_mfma_f32_16x16x32_bf16 v[60:63], v[16:19], v[36:39], 0
	v_mfma_f32_16x16x32_bf16 v[64:67], v[20:23], v[36:39], 0
	v_mfma_f32_16x16x32_bf16 v[68:71], v[24:27], v[36:39], 0
	v_mfma_f32_16x16x32_bf16 v[36:39], v[28:31], v[36:39], 0
	v_mfma_f32_16x16x32_bf16 v[72:75], v[16:19], v[40:43], 0
	v_mfma_f32_16x16x32_bf16 v[76:79], v[20:23], v[40:43], 0
	v_mfma_f32_16x16x32_bf16 v[80:83], v[24:27], v[40:43], 0
	v_mfma_f32_16x16x32_bf16 v[40:43], v[28:31], v[40:43], 0
	v_mfma_f32_16x16x32_bf16 v[16:19], v[16:19], v[44:47], 0
	v_mfma_f32_16x16x32_bf16 v[20:23], v[20:23], v[44:47], 0
	v_mfma_f32_16x16x32_bf16 v[24:27], v[24:27], v[44:47], 0
	v_mfma_f32_16x16x32_bf16 v[28:31], v[28:31], v[44:47], 0
	s_setprio 0
	ds_read_b128 v[44:47], v0 offset:24576
	ds_read_b128 v[84:87], v0 offset:25600
	ds_read_b128 v[88:91], v0 offset:26624
	ds_read_b128 v[92:95], v0 offset:27648
	ds_read_b128 v[96:99], v10 offset:16384
	ds_read_b128 v[100:103], v10 offset:17408
	ds_read_b128 v[104:107], v10 offset:18432
	ds_read_b128 v[108:111], v10 offset:19456
	s_waitcnt vmcnt(4) lgkmcnt(0)
	s_barrier
	global_load_lds_dwordx4 v[116:117], off
	s_mov_b32 m0, s25
	s_waitcnt lgkmcnt(0)
	s_setprio 1
	v_mfma_f32_16x16x32_bf16 v[48:51], v[44:47], v[96:99], v[48:51]
	global_load_lds_dwordx4 v[118:119], off
	s_mov_b32 m0, s26
	v_mfma_f32_16x16x32_bf16 v[52:55], v[84:87], v[96:99], v[52:55]
	global_load_lds_dwordx4 v[114:115], off
	s_mov_b32 m0, s27
	v_mfma_f32_16x16x32_bf16 v[56:59], v[88:91], v[96:99], v[56:59]
	global_load_lds_dwordx4 v[112:113], off
	s_mov_b32 m0, s23
	v_mfma_f32_16x16x32_bf16 v[32:35], v[92:95], v[96:99], v[32:35]
	v_lshl_add_u64 v[116:117], v[2:3], 0, s[40:41]
	v_lshl_add_u64 v[118:119], v[4:5], 0, s[40:41]
	v_lshl_add_u64 v[114:115], v[6:7], 0, s[40:41]
	v_mfma_f32_16x16x32_bf16 v[60:63], v[44:47], v[100:103], v[60:63]
	v_lshl_add_u64 v[112:113], v[8:9], 0, s[40:41]
	s_mov_b64 s[40:41], 0x1c0
	v_mfma_f32_16x16x32_bf16 v[64:67], v[84:87], v[100:103], v[64:67]
	v_mfma_f32_16x16x32_bf16 v[68:71], v[88:91], v[100:103], v[68:71]
	v_mfma_f32_16x16x32_bf16 v[36:39], v[92:95], v[100:103], v[36:39]
	v_mfma_f32_16x16x32_bf16 v[72:75], v[44:47], v[104:107], v[72:75]
	v_mfma_f32_16x16x32_bf16 v[76:79], v[84:87], v[104:107], v[76:79]
	v_mfma_f32_16x16x32_bf16 v[80:83], v[88:91], v[104:107], v[80:83]
	v_mfma_f32_16x16x32_bf16 v[40:43], v[92:95], v[104:107], v[40:43]
	v_mfma_f32_16x16x32_bf16 v[16:19], v[44:47], v[108:111], v[16:19]
	v_mfma_f32_16x16x32_bf16 v[20:23], v[84:87], v[108:111], v[20:23]
	v_mfma_f32_16x16x32_bf16 v[24:27], v[88:91], v[108:111], v[24:27]
	v_mfma_f32_16x16x32_bf16 v[28:31], v[92:95], v[108:111], v[28:31]
	s_setprio 0
	ds_read_b128 v[44:47], v0 offset:40960
	ds_read_b128 v[84:87], v0 offset:41984
	ds_read_b128 v[88:91], v0 offset:43008
	ds_read_b128 v[92:95], v0 offset:44032
	ds_read_b128 v[96:99], v10 offset:32768
	ds_read_b128 v[100:103], v10 offset:33792
	ds_read_b128 v[104:107], v10 offset:34816
	ds_read_b128 v[108:111], v10 offset:35840
	s_waitcnt vmcnt(4) lgkmcnt(0)
	s_barrier
	global_load_lds_dwordx4 v[124:125], off
	s_mov_b32 m0, s22
	s_waitcnt lgkmcnt(0)
	s_setprio 1
	v_mfma_f32_16x16x32_bf16 v[48:51], v[44:47], v[96:99], v[48:51]
	global_load_lds_dwordx4 v[126:127], off
	s_mov_b32 m0, s21
	v_mfma_f32_16x16x32_bf16 v[52:55], v[84:87], v[96:99], v[52:55]
	global_load_lds_dwordx4 v[122:123], off
	s_mov_b32 m0, s1
	v_mfma_f32_16x16x32_bf16 v[56:59], v[88:91], v[96:99], v[56:59]
	global_load_lds_dwordx4 v[120:121], off
	s_mov_b32 m0, s36
	v_mfma_f32_16x16x32_bf16 v[32:35], v[92:95], v[96:99], v[32:35]
	v_lshl_add_u64 v[124:125], v[2:3], 0, s[40:41]
	v_lshl_add_u64 v[126:127], v[4:5], 0, s[40:41]
	v_lshl_add_u64 v[122:123], v[6:7], 0, s[40:41]
	v_mfma_f32_16x16x32_bf16 v[60:63], v[44:47], v[100:103], v[60:63]
	v_lshl_add_u64 v[120:121], v[8:9], 0, s[40:41]
	s_mov_b64 s[40:41], 0x200
	v_mfma_f32_16x16x32_bf16 v[64:67], v[84:87], v[100:103], v[64:67]
	v_mfma_f32_16x16x32_bf16 v[68:71], v[88:91], v[100:103], v[68:71]
	v_mfma_f32_16x16x32_bf16 v[36:39], v[92:95], v[100:103], v[36:39]
	v_mfma_f32_16x16x32_bf16 v[72:75], v[44:47], v[104:107], v[72:75]
	v_mfma_f32_16x16x32_bf16 v[76:79], v[84:87], v[104:107], v[76:79]
	v_mfma_f32_16x16x32_bf16 v[80:83], v[88:91], v[104:107], v[80:83]
	v_mfma_f32_16x16x32_bf16 v[40:43], v[92:95], v[104:107], v[40:43]
	v_mfma_f32_16x16x32_bf16 v[16:19], v[44:47], v[108:111], v[16:19]
	v_mfma_f32_16x16x32_bf16 v[20:23], v[84:87], v[108:111], v[20:23]
	v_mfma_f32_16x16x32_bf16 v[24:27], v[88:91], v[108:111], v[24:27]
	v_mfma_f32_16x16x32_bf16 v[28:31], v[92:95], v[108:111], v[28:31]
	s_setprio 0
	ds_read_b128 v[44:47], v0 offset:8192
	ds_read_b128 v[84:87], v0 offset:9216
	ds_read_b128 v[88:91], v0 offset:10240
	ds_read_b128 v[92:95], v0 offset:11264
	ds_read_b128 v[96:99], v10
	ds_read_b128 v[100:103], v10 offset:1024
	ds_read_b128 v[104:107], v10 offset:2048
	ds_read_b128 v[108:111], v10 offset:3072
	s_waitcnt vmcnt(4) lgkmcnt(0)
	s_barrier
	global_load_lds_dwordx4 v[116:117], off
	s_mov_b32 m0, s37
	s_waitcnt lgkmcnt(0)
	s_setprio 1
	v_mfma_f32_16x16x32_bf16 v[48:51], v[44:47], v[96:99], v[48:51]
	global_load_lds_dwordx4 v[118:119], off
	s_mov_b32 m0, s38
	v_mfma_f32_16x16x32_bf16 v[52:55], v[84:87], v[96:99], v[52:55]
	global_load_lds_dwordx4 v[114:115], off
	s_mov_b32 m0, s39
	v_mfma_f32_16x16x32_bf16 v[56:59], v[88:91], v[96:99], v[56:59]
	global_load_lds_dwordx4 v[112:113], off
	s_mov_b32 m0, s24
	v_mfma_f32_16x16x32_bf16 v[32:35], v[92:95], v[96:99], v[32:35]
	v_lshl_add_u64 v[116:117], v[2:3], 0, s[40:41]
	v_lshl_add_u64 v[118:119], v[4:5], 0, s[40:41]
	v_lshl_add_u64 v[114:115], v[6:7], 0, s[40:41]
	v_mfma_f32_16x16x32_bf16 v[60:63], v[44:47], v[100:103], v[60:63]
	v_lshl_add_u64 v[112:113], v[8:9], 0, s[40:41]
	s_mov_b64 s[40:41], 0x240
	v_mfma_f32_16x16x32_bf16 v[64:67], v[84:87], v[100:103], v[64:67]
	v_mfma_f32_16x16x32_bf16 v[68:71], v[88:91], v[100:103], v[68:71]
	v_mfma_f32_16x16x32_bf16 v[36:39], v[92:95], v[100:103], v[36:39]
	v_mfma_f32_16x16x32_bf16 v[72:75], v[44:47], v[104:107], v[72:75]
	v_mfma_f32_16x16x32_bf16 v[76:79], v[84:87], v[104:107], v[76:79]
	v_mfma_f32_16x16x32_bf16 v[80:83], v[88:91], v[104:107], v[80:83]
	v_mfma_f32_16x16x32_bf16 v[40:43], v[92:95], v[104:107], v[40:43]
	v_mfma_f32_16x16x32_bf16 v[16:19], v[44:47], v[108:111], v[16:19]
	v_mfma_f32_16x16x32_bf16 v[20:23], v[84:87], v[108:111], v[20:23]
	v_mfma_f32_16x16x32_bf16 v[24:27], v[88:91], v[108:111], v[24:27]
	v_mfma_f32_16x16x32_bf16 v[28:31], v[92:95], v[108:111], v[28:31]
	s_setprio 0
	ds_read_b128 v[44:47], v0 offset:24576
	ds_read_b128 v[84:87], v0 offset:25600
	ds_read_b128 v[88:91], v0 offset:26624
	ds_read_b128 v[92:95], v0 offset:27648
	ds_read_b128 v[96:99], v10 offset:16384
	ds_read_b128 v[100:103], v10 offset:17408
	ds_read_b128 v[104:107], v10 offset:18432
	ds_read_b128 v[108:111], v10 offset:19456
	s_waitcnt vmcnt(4) lgkmcnt(0)
	s_barrier
	global_load_lds_dwordx4 v[124:125], off
	s_mov_b32 m0, s25
	s_waitcnt lgkmcnt(0)
	s_setprio 1
	v_mfma_f32_16x16x32_bf16 v[48:51], v[44:47], v[96:99], v[48:51]
	global_load_lds_dwordx4 v[126:127], off
	s_mov_b32 m0, s26
	v_mfma_f32_16x16x32_bf16 v[52:55], v[84:87], v[96:99], v[52:55]
	global_load_lds_dwordx4 v[122:123], off
	s_mov_b32 m0, s27
	v_mfma_f32_16x16x32_bf16 v[56:59], v[88:91], v[96:99], v[56:59]
	global_load_lds_dwordx4 v[120:121], off
	s_mov_b32 m0, s23
	v_mfma_f32_16x16x32_bf16 v[32:35], v[92:95], v[96:99], v[32:35]
	v_lshl_add_u64 v[124:125], v[2:3], 0, s[40:41]
	v_lshl_add_u64 v[126:127], v[4:5], 0, s[40:41]
	v_lshl_add_u64 v[122:123], v[6:7], 0, s[40:41]
	v_mfma_f32_16x16x32_bf16 v[60:63], v[44:47], v[100:103], v[60:63]
	v_lshl_add_u64 v[120:121], v[8:9], 0, s[40:41]
	s_mov_b64 s[40:41], 0x280
	v_mfma_f32_16x16x32_bf16 v[64:67], v[84:87], v[100:103], v[64:67]
	v_mfma_f32_16x16x32_bf16 v[68:71], v[88:91], v[100:103], v[68:71]
	v_mfma_f32_16x16x32_bf16 v[36:39], v[92:95], v[100:103], v[36:39]
	v_mfma_f32_16x16x32_bf16 v[72:75], v[44:47], v[104:107], v[72:75]
	v_mfma_f32_16x16x32_bf16 v[76:79], v[84:87], v[104:107], v[76:79]
	v_mfma_f32_16x16x32_bf16 v[80:83], v[88:91], v[104:107], v[80:83]
	v_mfma_f32_16x16x32_bf16 v[40:43], v[92:95], v[104:107], v[40:43]
	v_mfma_f32_16x16x32_bf16 v[16:19], v[44:47], v[108:111], v[16:19]
	v_mfma_f32_16x16x32_bf16 v[20:23], v[84:87], v[108:111], v[20:23]
	v_mfma_f32_16x16x32_bf16 v[24:27], v[88:91], v[108:111], v[24:27]
	v_mfma_f32_16x16x32_bf16 v[28:31], v[92:95], v[108:111], v[28:31]
	s_setprio 0
	ds_read_b128 v[44:47], v0 offset:40960
	ds_read_b128 v[84:87], v0 offset:41984
	ds_read_b128 v[88:91], v0 offset:43008
	ds_read_b128 v[92:95], v0 offset:44032
	ds_read_b128 v[96:99], v10 offset:32768
	ds_read_b128 v[100:103], v10 offset:33792
	ds_read_b128 v[104:107], v10 offset:34816
	ds_read_b128 v[108:111], v10 offset:35840
	s_waitcnt vmcnt(4) lgkmcnt(0)
	s_barrier
	global_load_lds_dwordx4 v[116:117], off
	s_mov_b32 m0, s22
	s_waitcnt lgkmcnt(0)
	s_setprio 1
	v_mfma_f32_16x16x32_bf16 v[48:51], v[44:47], v[96:99], v[48:51]
	global_load_lds_dwordx4 v[118:119], off
	s_mov_b32 m0, s21
	v_mfma_f32_16x16x32_bf16 v[52:55], v[84:87], v[96:99], v[52:55]
	global_load_lds_dwordx4 v[114:115], off
	s_mov_b32 m0, s1
	v_mfma_f32_16x16x32_bf16 v[56:59], v[88:91], v[96:99], v[56:59]
	global_load_lds_dwordx4 v[112:113], off
	s_mov_b32 m0, s36
	v_mfma_f32_16x16x32_bf16 v[32:35], v[92:95], v[96:99], v[32:35]
	v_lshl_add_u64 v[116:117], v[2:3], 0, s[40:41]
	v_lshl_add_u64 v[118:119], v[4:5], 0, s[40:41]
	v_lshl_add_u64 v[114:115], v[6:7], 0, s[40:41]
	v_mfma_f32_16x16x32_bf16 v[60:63], v[44:47], v[100:103], v[60:63]
	v_lshl_add_u64 v[112:113], v[8:9], 0, s[40:41]
	s_mov_b64 s[40:41], 0x2c0
	v_mfma_f32_16x16x32_bf16 v[64:67], v[84:87], v[100:103], v[64:67]
	v_mfma_f32_16x16x32_bf16 v[68:71], v[88:91], v[100:103], v[68:71]
	v_mfma_f32_16x16x32_bf16 v[36:39], v[92:95], v[100:103], v[36:39]
	v_mfma_f32_16x16x32_bf16 v[72:75], v[44:47], v[104:107], v[72:75]
	v_mfma_f32_16x16x32_bf16 v[76:79], v[84:87], v[104:107], v[76:79]
	v_mfma_f32_16x16x32_bf16 v[80:83], v[88:91], v[104:107], v[80:83]
	v_mfma_f32_16x16x32_bf16 v[40:43], v[92:95], v[104:107], v[40:43]
	v_mfma_f32_16x16x32_bf16 v[16:19], v[44:47], v[108:111], v[16:19]
	v_mfma_f32_16x16x32_bf16 v[20:23], v[84:87], v[108:111], v[20:23]
	v_mfma_f32_16x16x32_bf16 v[24:27], v[88:91], v[108:111], v[24:27]
	v_mfma_f32_16x16x32_bf16 v[28:31], v[92:95], v[108:111], v[28:31]
	s_setprio 0
	ds_read_b128 v[44:47], v0 offset:8192
	ds_read_b128 v[84:87], v0 offset:9216
	ds_read_b128 v[88:91], v0 offset:10240
	ds_read_b128 v[92:95], v0 offset:11264
	ds_read_b128 v[96:99], v10
	ds_read_b128 v[100:103], v10 offset:1024
	ds_read_b128 v[104:107], v10 offset:2048
	ds_read_b128 v[108:111], v10 offset:3072
	s_waitcnt vmcnt(4) lgkmcnt(0)
	s_barrier
	global_load_lds_dwordx4 v[124:125], off
	s_mov_b32 m0, s37
	s_waitcnt lgkmcnt(0)
	s_setprio 1
	v_mfma_f32_16x16x32_bf16 v[48:51], v[44:47], v[96:99], v[48:51]
	global_load_lds_dwordx4 v[126:127], off
	s_mov_b32 m0, s38
	v_mfma_f32_16x16x32_bf16 v[52:55], v[84:87], v[96:99], v[52:55]
	global_load_lds_dwordx4 v[122:123], off
	s_mov_b32 m0, s39
	v_mfma_f32_16x16x32_bf16 v[56:59], v[88:91], v[96:99], v[56:59]
	global_load_lds_dwordx4 v[120:121], off
	s_mov_b32 m0, s24
	v_mfma_f32_16x16x32_bf16 v[32:35], v[92:95], v[96:99], v[32:35]
	v_lshl_add_u64 v[124:125], v[2:3], 0, s[40:41]
	v_lshl_add_u64 v[126:127], v[4:5], 0, s[40:41]
	v_lshl_add_u64 v[122:123], v[6:7], 0, s[40:41]
	v_mfma_f32_16x16x32_bf16 v[60:63], v[44:47], v[100:103], v[60:63]
	v_lshl_add_u64 v[120:121], v[8:9], 0, s[40:41]
	s_mov_b64 s[40:41], 0x300
	v_mfma_f32_16x16x32_bf16 v[64:67], v[84:87], v[100:103], v[64:67]
	v_mfma_f32_16x16x32_bf16 v[68:71], v[88:91], v[100:103], v[68:71]
	v_mfma_f32_16x16x32_bf16 v[36:39], v[92:95], v[100:103], v[36:39]
	v_mfma_f32_16x16x32_bf16 v[72:75], v[44:47], v[104:107], v[72:75]
	v_mfma_f32_16x16x32_bf16 v[76:79], v[84:87], v[104:107], v[76:79]
	v_mfma_f32_16x16x32_bf16 v[80:83], v[88:91], v[104:107], v[80:83]
	v_mfma_f32_16x16x32_bf16 v[40:43], v[92:95], v[104:107], v[40:43]
	v_mfma_f32_16x16x32_bf16 v[16:19], v[44:47], v[108:111], v[16:19]
	v_mfma_f32_16x16x32_bf16 v[20:23], v[84:87], v[108:111], v[20:23]
	v_mfma_f32_16x16x32_bf16 v[24:27], v[88:91], v[108:111], v[24:27]
	v_mfma_f32_16x16x32_bf16 v[28:31], v[92:95], v[108:111], v[28:31]
	s_setprio 0
	ds_read_b128 v[44:47], v0 offset:24576
	ds_read_b128 v[84:87], v0 offset:25600
	ds_read_b128 v[88:91], v0 offset:26624
	ds_read_b128 v[92:95], v0 offset:27648
	ds_read_b128 v[96:99], v10 offset:16384
	ds_read_b128 v[100:103], v10 offset:17408
	ds_read_b128 v[104:107], v10 offset:18432
	ds_read_b128 v[108:111], v10 offset:19456
	s_waitcnt vmcnt(4) lgkmcnt(0)
	s_barrier
	global_load_lds_dwordx4 v[116:117], off
	s_mov_b32 m0, s25
	s_waitcnt lgkmcnt(0)
	s_setprio 1
	v_mfma_f32_16x16x32_bf16 v[48:51], v[44:47], v[96:99], v[48:51]
	global_load_lds_dwordx4 v[118:119], off
	s_mov_b32 m0, s26
	v_mfma_f32_16x16x32_bf16 v[52:55], v[84:87], v[96:99], v[52:55]
	global_load_lds_dwordx4 v[114:115], off
	s_mov_b32 m0, s27
	v_mfma_f32_16x16x32_bf16 v[56:59], v[88:91], v[96:99], v[56:59]
	global_load_lds_dwordx4 v[112:113], off
	s_mov_b32 m0, s23
	v_mfma_f32_16x16x32_bf16 v[32:35], v[92:95], v[96:99], v[32:35]
	v_lshl_add_u64 v[116:117], v[2:3], 0, s[40:41]
	v_lshl_add_u64 v[118:119], v[4:5], 0, s[40:41]
	v_lshl_add_u64 v[114:115], v[6:7], 0, s[40:41]
	v_mfma_f32_16x16x32_bf16 v[60:63], v[44:47], v[100:103], v[60:63]
	v_lshl_add_u64 v[112:113], v[8:9], 0, s[40:41]
	s_mov_b64 s[40:41], 0x340
	v_mfma_f32_16x16x32_bf16 v[64:67], v[84:87], v[100:103], v[64:67]
	v_mfma_f32_16x16x32_bf16 v[68:71], v[88:91], v[100:103], v[68:71]
	v_mfma_f32_16x16x32_bf16 v[36:39], v[92:95], v[100:103], v[36:39]
	v_mfma_f32_16x16x32_bf16 v[72:75], v[44:47], v[104:107], v[72:75]
	v_mfma_f32_16x16x32_bf16 v[76:79], v[84:87], v[104:107], v[76:79]
	v_mfma_f32_16x16x32_bf16 v[80:83], v[88:91], v[104:107], v[80:83]
	v_mfma_f32_16x16x32_bf16 v[40:43], v[92:95], v[104:107], v[40:43]
	v_mfma_f32_16x16x32_bf16 v[16:19], v[44:47], v[108:111], v[16:19]
	v_mfma_f32_16x16x32_bf16 v[20:23], v[84:87], v[108:111], v[20:23]
	v_mfma_f32_16x16x32_bf16 v[24:27], v[88:91], v[108:111], v[24:27]
	v_mfma_f32_16x16x32_bf16 v[28:31], v[92:95], v[108:111], v[28:31]
	s_setprio 0
	ds_read_b128 v[44:47], v0 offset:40960
	ds_read_b128 v[84:87], v0 offset:41984
	ds_read_b128 v[88:91], v0 offset:43008
	ds_read_b128 v[92:95], v0 offset:44032
	ds_read_b128 v[96:99], v10 offset:32768
	ds_read_b128 v[100:103], v10 offset:33792
	ds_read_b128 v[104:107], v10 offset:34816
	ds_read_b128 v[108:111], v10 offset:35840
	s_waitcnt vmcnt(4) lgkmcnt(0)
	s_barrier
	global_load_lds_dwordx4 v[124:125], off
	s_mov_b32 m0, s22
	s_waitcnt lgkmcnt(0)
	s_setprio 1
	v_mfma_f32_16x16x32_bf16 v[48:51], v[44:47], v[96:99], v[48:51]
	global_load_lds_dwordx4 v[126:127], off
	s_mov_b32 m0, s21
	v_mfma_f32_16x16x32_bf16 v[52:55], v[84:87], v[96:99], v[52:55]
	global_load_lds_dwordx4 v[122:123], off
	s_mov_b32 m0, s1
	v_mfma_f32_16x16x32_bf16 v[56:59], v[88:91], v[96:99], v[56:59]
	global_load_lds_dwordx4 v[120:121], off
	s_mov_b32 m0, s36
	v_mfma_f32_16x16x32_bf16 v[32:35], v[92:95], v[96:99], v[32:35]
	v_lshl_add_u64 v[124:125], v[2:3], 0, s[40:41]
	v_lshl_add_u64 v[126:127], v[4:5], 0, s[40:41]
	v_lshl_add_u64 v[122:123], v[6:7], 0, s[40:41]
	v_mfma_f32_16x16x32_bf16 v[60:63], v[44:47], v[100:103], v[60:63]
	v_lshl_add_u64 v[120:121], v[8:9], 0, s[40:41]
	v_mfma_f32_16x16x32_bf16 v[64:67], v[84:87], v[100:103], v[64:67]
	v_mfma_f32_16x16x32_bf16 v[68:71], v[88:91], v[100:103], v[68:71]
	v_mfma_f32_16x16x32_bf16 v[36:39], v[92:95], v[100:103], v[36:39]
	v_mfma_f32_16x16x32_bf16 v[72:75], v[44:47], v[104:107], v[72:75]
	v_mfma_f32_16x16x32_bf16 v[76:79], v[84:87], v[104:107], v[76:79]
	v_mfma_f32_16x16x32_bf16 v[80:83], v[88:91], v[104:107], v[80:83]
	v_mfma_f32_16x16x32_bf16 v[40:43], v[92:95], v[104:107], v[40:43]
	v_mfma_f32_16x16x32_bf16 v[16:19], v[44:47], v[108:111], v[16:19]
	v_mfma_f32_16x16x32_bf16 v[20:23], v[84:87], v[108:111], v[20:23]
	v_mfma_f32_16x16x32_bf16 v[24:27], v[88:91], v[108:111], v[24:27]
	v_mfma_f32_16x16x32_bf16 v[28:31], v[92:95], v[108:111], v[28:31]
	s_setprio 0
	ds_read_b128 v[44:47], v0 offset:8192
	ds_read_b128 v[84:87], v0 offset:9216
	ds_read_b128 v[88:91], v0 offset:10240
	ds_read_b128 v[92:95], v0 offset:11264
	ds_read_b128 v[96:99], v10
	ds_read_b128 v[100:103], v10 offset:1024
	ds_read_b128 v[104:107], v10 offset:2048
	ds_read_b128 v[108:111], v10 offset:3072
	s_waitcnt vmcnt(4) lgkmcnt(0)
	s_barrier
	global_load_lds_dwordx4 v[116:117], off
	s_mov_b32 m0, s37
	s_waitcnt lgkmcnt(0)
	s_setprio 1
	v_mfma_f32_16x16x32_bf16 v[48:51], v[44:47], v[96:99], v[48:51]
	global_load_lds_dwordx4 v[118:119], off
	s_mov_b32 m0, s38
	v_mfma_f32_16x16x32_bf16 v[52:55], v[84:87], v[96:99], v[52:55]
	global_load_lds_dwordx4 v[114:115], off
	s_mov_b32 m0, s39
	v_mfma_f32_16x16x32_bf16 v[56:59], v[88:91], v[96:99], v[56:59]
	global_load_lds_dwordx4 v[112:113], off
	s_mov_b32 m0, s24
	v_mfma_f32_16x16x32_bf16 v[32:35], v[92:95], v[96:99], v[32:35]
	s_mov_b64 s[36:37], 0x380
	v_lshl_add_u64 v[116:117], v[2:3], 0, s[36:37]
	v_lshl_add_u64 v[118:119], v[4:5], 0, s[36:37]
	v_mfma_f32_16x16x32_bf16 v[60:63], v[44:47], v[100:103], v[60:63]
	v_lshl_add_u64 v[114:115], v[6:7], 0, s[36:37]
	v_lshl_add_u64 v[112:113], v[8:9], 0, s[36:37]
	v_mfma_f32_16x16x32_bf16 v[64:67], v[84:87], v[100:103], v[64:67]
	v_mfma_f32_16x16x32_bf16 v[68:71], v[88:91], v[100:103], v[68:71]
	v_mfma_f32_16x16x32_bf16 v[36:39], v[92:95], v[100:103], v[36:39]
	v_mfma_f32_16x16x32_bf16 v[72:75], v[44:47], v[104:107], v[72:75]
	v_mfma_f32_16x16x32_bf16 v[76:79], v[84:87], v[104:107], v[76:79]
	v_mfma_f32_16x16x32_bf16 v[80:83], v[88:91], v[104:107], v[80:83]
	v_mfma_f32_16x16x32_bf16 v[40:43], v[92:95], v[104:107], v[40:43]
	v_mfma_f32_16x16x32_bf16 v[16:19], v[44:47], v[108:111], v[16:19]
	v_mfma_f32_16x16x32_bf16 v[20:23], v[84:87], v[108:111], v[20:23]
	v_mfma_f32_16x16x32_bf16 v[24:27], v[88:91], v[108:111], v[24:27]
	v_mfma_f32_16x16x32_bf16 v[28:31], v[92:95], v[108:111], v[28:31]
	s_setprio 0
	ds_read_b128 v[44:47], v0 offset:24576
	ds_read_b128 v[84:87], v0 offset:25600
	ds_read_b128 v[88:91], v0 offset:26624
	ds_read_b128 v[92:95], v0 offset:27648
	ds_read_b128 v[96:99], v10 offset:16384
	ds_read_b128 v[100:103], v10 offset:17408
	ds_read_b128 v[104:107], v10 offset:18432
	ds_read_b128 v[108:111], v10 offset:19456
	s_waitcnt vmcnt(4) lgkmcnt(0)
	s_barrier
	global_load_lds_dwordx4 v[124:125], off
	s_mov_b32 m0, s25
	s_waitcnt lgkmcnt(0)
	s_setprio 1
	v_mfma_f32_16x16x32_bf16 v[48:51], v[44:47], v[96:99], v[48:51]
	global_load_lds_dwordx4 v[126:127], off
	s_mov_b32 m0, s26
	v_mfma_f32_16x16x32_bf16 v[52:55], v[84:87], v[96:99], v[52:55]
	global_load_lds_dwordx4 v[122:123], off
	s_mov_b32 m0, s27
	v_mfma_f32_16x16x32_bf16 v[56:59], v[88:91], v[96:99], v[56:59]
	global_load_lds_dwordx4 v[120:121], off
	s_mov_b32 m0, s23
	v_mfma_f32_16x16x32_bf16 v[32:35], v[92:95], v[96:99], v[32:35]
	s_mov_b64 s[26:27], 0x3c0
	s_mov_b64 s[24:25], 0x3000
	v_mfma_f32_16x16x32_bf16 v[60:63], v[44:47], v[100:103], v[60:63]
	v_mfma_f32_16x16x32_bf16 v[64:67], v[84:87], v[100:103], v[64:67]
	v_mfma_f32_16x16x32_bf16 v[68:71], v[88:91], v[100:103], v[68:71]
	v_mfma_f32_16x16x32_bf16 v[36:39], v[92:95], v[100:103], v[36:39]
	v_mfma_f32_16x16x32_bf16 v[72:75], v[44:47], v[104:107], v[72:75]
	v_mfma_f32_16x16x32_bf16 v[76:79], v[84:87], v[104:107], v[76:79]
	v_mfma_f32_16x16x32_bf16 v[80:83], v[88:91], v[104:107], v[80:83]
	v_mfma_f32_16x16x32_bf16 v[40:43], v[92:95], v[104:107], v[40:43]
	v_mfma_f32_16x16x32_bf16 v[16:19], v[44:47], v[108:111], v[16:19]
	v_mfma_f32_16x16x32_bf16 v[20:23], v[84:87], v[108:111], v[20:23]
	v_mfma_f32_16x16x32_bf16 v[24:27], v[88:91], v[108:111], v[24:27]
	v_mfma_f32_16x16x32_bf16 v[28:31], v[92:95], v[108:111], v[28:31]
	s_setprio 0
	ds_read_b128 v[44:47], v0 offset:40960
	ds_read_b128 v[84:87], v0 offset:41984
	ds_read_b128 v[88:91], v0 offset:43008
	ds_read_b128 v[92:95], v0 offset:44032
	ds_read_b128 v[96:99], v10 offset:32768
	ds_read_b128 v[100:103], v10 offset:33792
	ds_read_b128 v[104:107], v10 offset:34816
	ds_read_b128 v[108:111], v10 offset:35840
	s_waitcnt vmcnt(4) lgkmcnt(0)
	s_barrier
	global_load_lds_dwordx4 v[116:117], off
	s_mov_b32 m0, s22
	s_waitcnt lgkmcnt(0)
	s_setprio 1
	v_mfma_f32_16x16x32_bf16 v[48:51], v[44:47], v[96:99], v[48:51]
	global_load_lds_dwordx4 v[118:119], off
	s_mov_b32 m0, s21
	v_mfma_f32_16x16x32_bf16 v[52:55], v[84:87], v[96:99], v[52:55]
	global_load_lds_dwordx4 v[114:115], off
	s_mov_b32 m0, s1
	v_readfirstlane_b32 s1, v11
	global_load_lds_dwordx4 v[112:113], off
	v_mfma_f32_16x16x32_bf16 v[56:59], v[88:91], v[96:99], v[56:59]
	s_mov_b32 m0, s1
	v_readfirstlane_b32 s1, v13
	s_lshl_b64 s[22:23], s[2:3], 11
	v_mfma_f32_16x16x32_bf16 v[32:35], v[92:95], v[96:99], v[32:35]
	v_mfma_f32_16x16x32_bf16 v[60:63], v[44:47], v[100:103], v[60:63]
	v_mfma_f32_16x16x32_bf16 v[64:67], v[84:87], v[100:103], v[64:67]
	v_mfma_f32_16x16x32_bf16 v[68:71], v[88:91], v[100:103], v[68:71]
	v_mfma_f32_16x16x32_bf16 v[36:39], v[92:95], v[100:103], v[36:39]
	v_mfma_f32_16x16x32_bf16 v[72:75], v[44:47], v[104:107], v[72:75]
	v_mfma_f32_16x16x32_bf16 v[76:79], v[84:87], v[104:107], v[76:79]
	v_mfma_f32_16x16x32_bf16 v[80:83], v[88:91], v[104:107], v[80:83]
	v_mfma_f32_16x16x32_bf16 v[40:43], v[92:95], v[104:107], v[40:43]
	v_lshl_add_u64 v[104:105], v[8:9], 0, s[26:27]
	v_lshl_add_u64 v[106:107], v[6:7], 0, s[26:27]
	v_mfma_f32_16x16x32_bf16 v[16:19], v[44:47], v[108:111], v[16:19]
	v_mfma_f32_16x16x32_bf16 v[20:23], v[84:87], v[108:111], v[20:23]
	v_mfma_f32_16x16x32_bf16 v[24:27], v[88:91], v[108:111], v[24:27]
	v_mfma_f32_16x16x32_bf16 v[28:31], v[92:95], v[108:111], v[28:31]
	v_lshl_add_u64 v[108:109], v[2:3], 0, s[26:27]
	v_lshl_add_u64 v[110:111], v[4:5], 0, s[26:27]
	s_setprio 0
	ds_read_b128 v[2:5], v0 offset:8192
	ds_read_b128 v[6:9], v0 offset:9216
	ds_read_b128 v[44:47], v0 offset:10240
	ds_read_b128 v[84:87], v0 offset:11264
	ds_read_b128 v[88:91], v10
	ds_read_b128 v[92:95], v10 offset:1024
	ds_read_b128 v[96:99], v10 offset:2048
	ds_read_b128 v[100:103], v10 offset:3072
	s_waitcnt vmcnt(4) lgkmcnt(0)
	s_barrier
	global_load_lds_dwordx4 v[108:109], off
	s_mov_b32 m0, s1
	v_readfirstlane_b32 s1, v14
	global_load_lds_dwordx4 v[110:111], off
	s_mov_b32 m0, s1
	v_readfirstlane_b32 s1, v12
	global_load_lds_dwordx4 v[106:107], off
	s_mov_b32 m0, s1
	s_waitcnt lgkmcnt(0)
	s_setprio 1
	v_mfma_f32_16x16x32_bf16 v[48:51], v[2:5], v[88:91], v[48:51]
	global_load_lds_dwordx4 v[104:105], off
	s_add_u32 s1, s17, s22
	v_mfma_f32_16x16x32_bf16 v[52:55], v[6:9], v[88:91], v[52:55]
	s_addc_u32 s2, s16, s23
	s_lshl_b32 s0, s0, 1
	s_add_u32 s0, s1, s0
	v_mfma_f32_16x16x32_bf16 v[56:59], v[44:47], v[88:91], v[56:59]
	s_addc_u32 s1, s2, 0
	s_mov_b32 s2, 0xfffffc0
	v_mfma_f32_16x16x32_bf16 v[32:35], v[84:87], v[88:91], v[32:35]
	v_mfma_f32_16x16x32_bf16 v[60:63], v[2:5], v[92:95], v[60:63]
	v_mfma_f32_16x16x32_bf16 v[64:67], v[6:9], v[92:95], v[64:67]
	v_mfma_f32_16x16x32_bf16 v[68:71], v[44:47], v[92:95], v[68:71]
	v_mfma_f32_16x16x32_bf16 v[36:39], v[84:87], v[92:95], v[36:39]
	v_mfma_f32_16x16x32_bf16 v[72:75], v[2:5], v[96:99], v[72:75]
	v_mfma_f32_16x16x32_bf16 v[76:79], v[6:9], v[96:99], v[76:79]
	v_mfma_f32_16x16x32_bf16 v[80:83], v[44:47], v[96:99], v[80:83]
	v_mfma_f32_16x16x32_bf16 v[40:43], v[84:87], v[96:99], v[40:43]
	v_mfma_f32_16x16x32_bf16 v[2:5], v[2:5], v[100:103], v[16:19]
	v_mfma_f32_16x16x32_bf16 v[6:9], v[6:9], v[100:103], v[20:23]
	v_mfma_f32_16x16x32_bf16 v[16:19], v[44:47], v[100:103], v[24:27]
	v_mfma_f32_16x16x32_bf16 v[20:23], v[84:87], v[100:103], v[28:31]
	s_setprio 0
	ds_read_b128 v[12:15], v0 offset:24576
	s_nop 0
	ds_read_b128 v[24:27], v0 offset:25600
	ds_read_b128 v[28:31], v0 offset:26624
	ds_read_b128 v[44:47], v0 offset:27648
	ds_read_b128 v[84:87], v10 offset:16384
	ds_read_b128 v[88:91], v10 offset:17408
	ds_read_b128 v[92:95], v10 offset:18432
	ds_read_b128 v[96:99], v10 offset:19456
	s_waitcnt vmcnt(4) lgkmcnt(0)
	s_barrier
	s_waitcnt lgkmcnt(0)
	s_setprio 1
	v_mfma_f32_16x16x32_bf16 v[48:51], v[12:15], v[84:87], v[48:51]
	v_mfma_f32_16x16x32_bf16 v[52:55], v[24:27], v[84:87], v[52:55]
	v_mfma_f32_16x16x32_bf16 v[56:59], v[28:31], v[84:87], v[56:59]
	v_mfma_f32_16x16x32_bf16 v[32:35], v[44:47], v[84:87], v[32:35]
	v_mfma_f32_16x16x32_bf16 v[60:63], v[12:15], v[88:91], v[60:63]
	v_mfma_f32_16x16x32_bf16 v[64:67], v[24:27], v[88:91], v[64:67]
	v_mfma_f32_16x16x32_bf16 v[68:71], v[28:31], v[88:91], v[68:71]
	v_mfma_f32_16x16x32_bf16 v[36:39], v[44:47], v[88:91], v[36:39]
	v_mfma_f32_16x16x32_bf16 v[72:75], v[12:15], v[92:95], v[72:75]
	v_mfma_f32_16x16x32_bf16 v[76:79], v[24:27], v[92:95], v[76:79]
	v_mfma_f32_16x16x32_bf16 v[80:83], v[28:31], v[92:95], v[80:83]
	v_mfma_f32_16x16x32_bf16 v[40:43], v[44:47], v[92:95], v[40:43]
	v_mfma_f32_16x16x32_bf16 v[2:5], v[12:15], v[96:99], v[2:5]
	v_mfma_f32_16x16x32_bf16 v[6:9], v[24:27], v[96:99], v[6:9]
	v_mfma_f32_16x16x32_bf16 v[12:15], v[28:31], v[96:99], v[16:19]
	v_mfma_f32_16x16x32_bf16 v[16:19], v[44:47], v[96:99], v[20:23]
	s_nop 2
	s_setprio 0
	ds_read_b128 v[20:23], v0 offset:40960
	ds_read_b128 v[24:27], v0 offset:41984
	ds_read_b128 v[28:31], v0 offset:43008
	ds_read_b128 v[44:47], v0 offset:44032
	ds_read_b128 v[84:87], v10 offset:32768
	ds_read_b128 v[88:91], v10 offset:33792
	ds_read_b128 v[92:95], v10 offset:34816
	ds_read_b128 v[96:99], v10 offset:35840
	s_waitcnt vmcnt(0) lgkmcnt(0)
	s_barrier
	s_waitcnt lgkmcnt(0)
	s_setprio 1
	v_mfma_f32_16x16x32_bf16 v[48:51], v[20:23], v[84:87], v[48:51]
	v_mfma_f32_16x16x32_bf16 v[52:55], v[24:27], v[84:87], v[52:55]
	v_mfma_f32_16x16x32_bf16 v[56:59], v[28:31], v[84:87], v[56:59]
	v_mfma_f32_16x16x32_bf16 v[32:35], v[44:47], v[84:87], v[32:35]
	v_mfma_f32_16x16x32_bf16 v[60:63], v[20:23], v[88:91], v[60:63]
	v_mfma_f32_16x16x32_bf16 v[64:67], v[24:27], v[88:91], v[64:67]
	v_mfma_f32_16x16x32_bf16 v[68:71], v[28:31], v[88:91], v[68:71]
	v_mfma_f32_16x16x32_bf16 v[36:39], v[44:47], v[88:91], v[36:39]
	v_mfma_f32_16x16x32_bf16 v[72:75], v[20:23], v[92:95], v[72:75]
	v_mfma_f32_16x16x32_bf16 v[76:79], v[24:27], v[92:95], v[76:79]
	v_mfma_f32_16x16x32_bf16 v[80:83], v[28:31], v[92:95], v[80:83]
	v_mfma_f32_16x16x32_bf16 v[40:43], v[44:47], v[92:95], v[40:43]
	v_mfma_f32_16x16x32_bf16 v[2:5], v[20:23], v[96:99], v[2:5]
	v_mfma_f32_16x16x32_bf16 v[6:9], v[24:27], v[96:99], v[6:9]
	v_mfma_f32_16x16x32_bf16 v[12:15], v[28:31], v[96:99], v[12:15]
	v_mfma_f32_16x16x32_bf16 v[16:19], v[44:47], v[96:99], v[16:19]
	s_setprio 0
	ds_read_b128 v[20:23], v0 offset:8192
	ds_read_b128 v[24:27], v0 offset:9216
	ds_read_b128 v[28:31], v0 offset:10240
	ds_read_b128 v[44:47], v0 offset:11264
	ds_read_b128 v[84:87], v10
	ds_read_b128 v[88:91], v10 offset:1024
	ds_read_b128 v[92:95], v10 offset:2048
	ds_read_b128 v[96:99], v10 offset:3072
	s_waitcnt vmcnt(0) lgkmcnt(0)
	s_barrier
	s_setprio 1
	v_mfma_f32_16x16x32_bf16 v[48:51], v[20:23], v[84:87], v[48:51]
	v_mfma_f32_16x16x32_bf16 v[52:55], v[24:27], v[84:87], v[52:55]
	v_mfma_f32_16x16x32_bf16 v[60:63], v[20:23], v[88:91], v[60:63]
	v_mfma_f32_16x16x32_bf16 v[72:75], v[20:23], v[92:95], v[72:75]
	v_mfma_f32_16x16x32_bf16 v[2:5], v[20:23], v[96:99], v[2:5]
	v_mov_b32_e32 v22, v196
	s_setprio 0
	s_nop 3
	v_cvt_pk_bf16_f32 v20, v52, v53
	s_setprio 1
	v_mfma_f32_16x16x32_bf16 v[56:59], v[28:31], v[84:87], v[56:59]
	v_and_b32_e32 v23, 15, v22
	v_and_b32_e32 v0, 64, v22
	v_lshl_add_u32 v0, v0, 1, 0
	v_mfma_f32_16x16x32_bf16 v[32:35], v[44:47], v[84:87], v[32:35]
	v_cvt_pk_bf16_f32 v21, v54, v55
	v_cvt_pk_bf16_f32 v2, v2, v3
	v_cvt_pk_bf16_f32 v3, v4, v5
	v_mfma_f32_16x16x32_bf16 v[10:13], v[28:31], v[96:99], v[12:15]
	v_mfma_f32_16x16x32_bf16 v[14:17], v[44:47], v[96:99], v[16:19]
	s_nop 2
	v_lshrrev_b32_e32 v18, 1, v22
	v_mfma_f32_16x16x32_bf16 v[64:67], v[24:27], v[88:91], v[64:67]
	v_and_or_b32 v19, v18, s2, v23
	v_and_b32_e32 v18, 24, v18
	v_mul_lo_u32 v19, v19, s30
	v_mfma_f32_16x16x32_bf16 v[68:71], v[28:31], v[88:91], v[68:71]
	v_add3_u32 v0, v0, v18, v19
	v_cvt_pk_bf16_f32 v18, v48, v49
	v_cvt_pk_bf16_f32 v19, v50, v51
	v_mfma_f32_16x16x32_bf16 v[36:39], v[44:47], v[88:91], v[36:39]
	ds_write2_b64 v0, v[18:19], v[20:21] offset1:4
	v_cvt_pk_bf16_f32 v18, v56, v57
	v_cvt_pk_bf16_f32 v19, v58, v59
	v_mfma_f32_16x16x32_bf16 v[6:9], v[24:27], v[96:99], v[6:9]
	v_cvt_pk_bf16_f32 v20, v32, v33
	v_cvt_pk_bf16_f32 v21, v34, v35
	ds_write2_b64 v0, v[18:19], v[20:21] offset0:8 offset1:12
	v_mfma_f32_16x16x32_bf16 v[76:79], v[24:27], v[92:95], v[76:79]
	v_cvt_pk_bf16_f32 v18, v60, v61
	v_cvt_pk_bf16_f32 v19, v62, v63
	v_cvt_pk_bf16_f32 v20, v64, v65
	v_cvt_pk_bf16_f32 v21, v66, v67
	v_add_u32_e32 v24, 0x1000, v0
	ds_write2_b64 v24, v[18:19], v[20:21] offset0:32 offset1:36
	v_cvt_pk_bf16_f32 v18, v68, v69
	v_cvt_pk_bf16_f32 v19, v70, v71
	v_cvt_pk_bf16_f32 v20, v36, v37
	v_cvt_pk_bf16_f32 v21, v38, v39
	v_mfma_f32_16x16x32_bf16 v[80:83], v[28:31], v[92:95], v[80:83]
	ds_write2_b64 v24, v[18:19], v[20:21] offset0:40 offset1:44
	v_add_u32_e32 v24, 0x2000, v0
	v_cvt_pk_bf16_f32 v4, v6, v7
	v_mfma_f32_16x16x32_bf16 v[40:43], v[44:47], v[92:95], v[40:43]
	v_cvt_pk_bf16_f32 v5, v8, v9
	v_add_u32_e32 v0, 0x3000, v0
	ds_write2_b64 v0, v[2:3], v[4:5] offset0:96 offset1:100
	v_cvt_pk_bf16_f32 v2, v10, v11
	v_cvt_pk_bf16_f32 v3, v12, v13
	v_cvt_pk_bf16_f32 v4, v14, v15
	v_cvt_pk_bf16_f32 v5, v16, v17
	ds_write2_b64 v0, v[2:3], v[4:5] offset0:104 offset1:108
	v_lshlrev_b32_e32 v0, 4, v23
	v_ashrrev_i32_e32 v2, 4, v22
	v_cvt_pk_bf16_f32 v18, v72, v73
	v_cvt_pk_bf16_f32 v19, v74, v75
	v_cvt_pk_bf16_f32 v20, v76, v77
	v_cvt_pk_bf16_f32 v21, v78, v79
	v_lshl_add_u64 v[6:7], s[0:1], 0, v[0:1]
	v_add_u32_e32 v0, 0, v0
	v_ashrrev_i32_e32 v3, 31, v2
	ds_write2_b64 v24, v[18:19], v[20:21] offset0:64 offset1:68
	v_cvt_pk_bf16_f32 v18, v80, v81
	v_cvt_pk_bf16_f32 v19, v82, v83
	v_cvt_pk_bf16_f32 v20, v40, v41
	v_cvt_pk_bf16_f32 v21, v42, v43
	v_mad_u64_u32 v[4:5], s[0:1], v2, s30, v[0:1]
	v_lshlrev_b64 v[2:3], 11, v[2:3]
	ds_write2_b64 v24, v[18:19], v[20:21] offset0:72 offset1:76
	s_setprio 0
	s_waitcnt lgkmcnt(0)
	s_barrier
	v_lshl_add_u64 v[8:9], v[6:7], 0, v[2:3]
	ds_read_b128 v[2:5], v4
	s_waitcnt lgkmcnt(0)
	global_store_dwordx4 v[8:9], v[2:5], off
	s_nop 1
	v_add_u32_e32 v2, 0x100, v22
	v_ashrrev_i32_e32 v2, 4, v2
	v_ashrrev_i32_e32 v3, 31, v2
	v_mad_u64_u32 v[4:5], s[0:1], v2, s30, v[0:1]
	v_lshlrev_b64 v[2:3], 11, v[2:3]
	v_lshl_add_u64 v[8:9], v[6:7], 0, v[2:3]
	ds_read_b128 v[2:5], v4
	s_waitcnt lgkmcnt(0)
	global_store_dwordx4 v[8:9], v[2:5], off
	s_nop 1
	v_add_u32_e32 v2, 0x200, v22
	v_ashrrev_i32_e32 v2, 4, v2
	v_ashrrev_i32_e32 v3, 31, v2
	v_mad_u64_u32 v[4:5], s[0:1], v2, s30, v[0:1]
	v_lshlrev_b64 v[2:3], 11, v[2:3]
	v_lshl_add_u64 v[8:9], v[6:7], 0, v[2:3]
	ds_read_b128 v[2:5], v4
	s_waitcnt lgkmcnt(0)
	global_store_dwordx4 v[8:9], v[2:5], off
	s_nop 1
	v_add_u32_e32 v2, 0x300, v22
	v_ashrrev_i32_e32 v2, 4, v2
	v_ashrrev_i32_e32 v3, 31, v2
	v_mad_u64_u32 v[4:5], s[0:1], v2, s30, v[0:1]
	v_lshlrev_b64 v[2:3], 11, v[2:3]
	v_lshl_add_u64 v[8:9], v[6:7], 0, v[2:3]
	ds_read_b128 v[2:5], v4
	s_waitcnt lgkmcnt(0)
	global_store_dwordx4 v[8:9], v[2:5], off
	s_nop 1
	v_add_u32_e32 v2, 0x400, v22
	v_ashrrev_i32_e32 v2, 4, v2
	v_ashrrev_i32_e32 v3, 31, v2
	v_mad_u64_u32 v[4:5], s[0:1], v2, s30, v[0:1]
	v_lshlrev_b64 v[2:3], 11, v[2:3]
	v_lshl_add_u64 v[8:9], v[6:7], 0, v[2:3]
	ds_read_b128 v[2:5], v4
	s_waitcnt lgkmcnt(0)
	global_store_dwordx4 v[8:9], v[2:5], off
	s_nop 1
	v_add_u32_e32 v2, 0x500, v22
	v_ashrrev_i32_e32 v2, 4, v2
	v_ashrrev_i32_e32 v3, 31, v2
	v_mad_u64_u32 v[4:5], s[0:1], v2, s30, v[0:1]
	v_lshlrev_b64 v[2:3], 11, v[2:3]
	v_lshl_add_u64 v[8:9], v[6:7], 0, v[2:3]
	ds_read_b128 v[2:5], v4
	s_waitcnt lgkmcnt(0)
	global_store_dwordx4 v[8:9], v[2:5], off
	s_nop 1
	v_add_u32_e32 v2, 0x600, v22
	v_ashrrev_i32_e32 v2, 4, v2
	v_ashrrev_i32_e32 v3, 31, v2
	v_mad_u64_u32 v[4:5], s[0:1], v2, s30, v[0:1]
	v_lshlrev_b64 v[2:3], 11, v[2:3]
	v_lshl_add_u64 v[8:9], v[6:7], 0, v[2:3]
	ds_read_b128 v[2:5], v4
	s_waitcnt lgkmcnt(0)
	global_store_dwordx4 v[8:9], v[2:5], off
	s_nop 1
	v_add_u32_e32 v2, 0x700, v22
	v_ashrrev_i32_e32 v2, 4, v2
	v_ashrrev_i32_e32 v3, 31, v2
	v_mad_u64_u32 v[4:5], s[0:1], v2, s30, v[0:1]
	v_lshlrev_b64 v[2:3], 11, v[2:3]
	v_lshl_add_u64 v[6:7], v[6:7], 0, v[2:3]
	ds_read_b128 v[2:5], v4
	s_mov_b64 s[0:1], 0
	s_waitcnt lgkmcnt(0)
	global_store_dwordx4 v[6:7], v[2:5], off
	s_barrier
.LBB0_201:
	s_andn2_b64 vcc, exec, s[0:1]
	s_cbranch_vccnz .LBB0_198
	s_lshr_b32 s1, s18, 3
	s_and_b32 s0, s15, 7
	s_and_b32 s1, s1, 0xfffff8
	v_mov_b32_e32 v14, v196
	s_or_b32 s0, s1, s0
	s_lshl_b32 s0, s0, 8
	v_lshrrev_b32_e32 v0, 2, v14
	s_lshl_b32 s1, s18, 4
	v_and_b32_e32 v0, 12, v0
	s_and_b32 s2, s1, 0x380
	s_ashr_i32 s1, s0, 31
	v_lshrrev_b32_e64 v0, v0, s57
	s_lshl_b64 s[22:23], s[0:1], 10
	v_xor_b32_e32 v0, v0, v14
	s_add_u32 s22, s8, s22
	v_ashrrev_i32_e32 v2, 2, v14
	v_lshlrev_b32_e32 v0, 4, v0
	s_addc_u32 s23, s9, s23
	s_lshl_b32 s8, s2, 10
	v_and_b32_e32 v0, 48, v0
	v_ashrrev_i32_e32 v3, 31, v2
	v_lshl_add_u32 v19, v14, 4, 0
	s_add_u32 s8, s19, s8
	v_lshl_add_u64 v[6:7], s[22:23], 0, v[0:1]
	v_lshlrev_b64 v[8:9], 10, v[2:3]
	s_mov_b64 s[18:19], 0x10000
	v_readfirstlane_b32 s25, v19
	v_add_u32_e32 v21, 0x1000, v19
	v_lshl_add_u64 v[10:11], v[8:9], 0, s[18:19]
	v_lshl_add_u64 v[2:3], v[6:7], 0, v[8:9]
	s_mov_b32 m0, s25
	v_readfirstlane_b32 s24, v21
	v_add_u32_e32 v20, 0x2000, v19
	v_lshl_add_u64 v[4:5], v[6:7], 0, v[10:11]
	global_load_lds_dwordx4 v[2:3], off
	s_mov_b32 m0, s24
	v_readfirstlane_b32 s23, v20
	v_add_u32_e32 v18, 0x3000, v19
	s_addc_u32 s9, s20, 0
	v_lshrrev_b32_e32 v15, 4, v14
	v_lshl_add_u64 v[6:7], v[2:3], 0, s[76:77]
	s_mov_b64 s[18:19], 0x30000
	v_lshlrev_b32_e32 v24, 6, v14
	v_and_b32_e32 v14, 12, v14
	global_load_lds_dwordx4 v[4:5], off
	s_mov_b32 m0, s23
	v_readfirstlane_b32 s22, v18
	v_add_u32_e32 v28, 0x4000, v19
	v_lshl_add_u64 v[12:13], v[2:3], 0, s[18:19]
	v_lshrrev_b32_e64 v14, v14, s57
	global_load_lds_dwordx4 v[6:7], off
	s_mov_b32 m0, s22
	v_lshl_add_u64 v[6:7], s[8:9], 0, v[8:9]
	v_readfirstlane_b32 s40, v28
	v_add_u32_e32 v29, 0x5000, v19
	v_lshl_add_u64 v[10:11], s[8:9], 0, v[10:11]
	v_xor_b32_e32 v14, v14, v15
	global_load_lds_dwordx4 v[12:13], off
	v_lshl_add_u64 v[8:9], v[6:7], 0, v[0:1]
	s_mov_b32 m0, s40
	v_readfirstlane_b32 s41, v29
	v_add_u32_e32 v27, 0x6000, v19
	v_lshlrev_b32_e32 v25, 4, v14
	v_lshl_add_u64 v[6:7], v[10:11], 0, v[0:1]
	global_load_lds_dwordx4 v[8:9], off
	s_mov_b32 m0, s41
	v_readfirstlane_b32 s39, v27
	v_add_u32_e32 v26, 0x7000, v19
	v_lshl_add_u64 v[14:15], v[2:3], 0, 64
	v_and_b32_e32 v0, 48, v25
	global_load_lds_dwordx4 v[6:7], off
	s_mov_b32 m0, s39
	v_readfirstlane_b32 s38, v26
	v_add_u32_e32 v25, 0x8000, v19
	v_lshl_add_u64 v[16:17], v[4:5], 0, 64
	global_load_lds_dwordx4 v[14:15], off
	s_mov_b32 m0, s38
	v_readfirstlane_b32 s37, v25
	v_lshl_add_u64 v[22:23], v[2:3], 0, s[96:97]
	global_load_lds_dwordx4 v[16:17], off
	s_mov_b32 m0, s37
	s_mov_b64 s[18:19], 0x30040
	global_load_lds_dwordx4 v[22:23], off
	v_add_u32_e32 v22, 0x9000, v19
	v_add_u32_e32 v23, 0xa000, v19
	v_readfirstlane_b32 s26, v22
	v_and_b32_e32 v36, 0x13c0, v24
	v_lshl_add_u64 v[12:13], v[2:3], 0, s[18:19]
	s_mov_b32 m0, s26
	v_and_b32_e32 v46, 0xffffe3c0, v24
	v_readfirstlane_b32 s27, v23
	v_add_u32_e32 v24, 0xb000, v19
	v_lshl_add_u64 v[10:11], v[8:9], 0, 64
	global_load_lds_dwordx4 v[12:13], off
	s_mov_b32 m0, s27
	v_readfirstlane_b32 s36, v24
	v_lshl_add_u64 v[12:13], v[6:7], 0, 64
	global_load_lds_dwordx4 v[10:11], off
	s_mov_b32 m0, s36
	s_mov_b64 s[8:9], 0x30080
	global_load_lds_dwordx4 v[12:13], off
	v_add_u32_e32 v12, 0xc000, v19
	v_lshl_add_u64 v[16:17], v[2:3], 0, s[8:9]
	v_readfirstlane_b32 s8, v12
	v_lshl_add_u64 v[14:15], v[2:3], 0, s[78:79]
	s_waitcnt vmcnt(6) lgkmcnt(0)
	s_barrier
	s_mov_b32 m0, s8
	v_add_u32_e32 v13, 0xd000, v19
	global_load_lds_dwordx4 v[14:15], off
	v_readfirstlane_b32 s9, v13
	v_add_u32_e32 v14, 0xe000, v19
	v_lshl_add_u64 v[32:33], v[4:5], 0, s[78:79]
	s_mov_b32 m0, s9
	v_readfirstlane_b32 s19, v14
	v_add_u32_e32 v15, 0xf000, v19
	v_lshl_add_u64 v[34:35], v[2:3], 0, s[90:91]
	global_load_lds_dwordx4 v[32:33], off
	s_mov_b32 m0, s19
	v_readfirstlane_b32 s18, v15
	global_load_lds_dwordx4 v[34:35], off
	s_mov_b64 s[20:21], 0x200c0
	s_mov_b32 m0, s18
	v_lshl_add_u64 v[166:167], v[2:3], 0, s[20:21]
	global_load_lds_dwordx4 v[16:17], off
	s_mov_b64 s[20:21], 0x300c0
	v_add_u32_e32 v16, 0x10000, v19
	v_lshl_add_u64 v[168:169], v[2:3], 0, s[20:21]
	v_readfirstlane_b32 s20, v16
	v_add_u32_e32 v17, 0x11000, v19
	v_lshl_add_u64 v[10:11], v[8:9], 0, s[78:79]
	s_mov_b32 m0, s20
	v_readfirstlane_b32 s21, v17
	v_lshl_add_u64 v[30:31], v[6:7], 0, s[78:79]
	global_load_lds_dwordx4 v[10:11], off
	s_mov_b32 m0, s21
	v_add3_u32 v10, 0, v36, v0
	global_load_lds_dwordx4 v[30:31], off
	v_add3_u32 v0, 0, v46, v0
	v_lshl_add_u64 v[162:163], v[2:3], 0, s[84:85]
	ds_read_b128 v[30:33], v10 offset:16384
	ds_read_b128 v[34:37], v10 offset:17408
	ds_read_b128 v[38:41], v10 offset:18432
	ds_read_b128 v[42:45], v10 offset:19456
	ds_read_b128 v[46:49], v0
	ds_read_b128 v[50:53], v0 offset:1024
	ds_read_b128 v[54:57], v0 offset:2048
	ds_read_b128 v[58:61], v0 offset:3072
	ds_read_b128 v[110:113], v0 offset:4096
	ds_read_b128 v[114:117], v0 offset:5120
	ds_read_b128 v[118:121], v0 offset:6144
	ds_read_b128 v[122:125], v0 offset:7168
	s_waitcnt vmcnt(6) lgkmcnt(0)
	s_barrier
	s_mov_b32 m0, s25
	v_lshl_add_u64 v[164:165], v[4:5], 0, s[84:85]
	global_load_lds_dwordx4 v[162:163], off
	s_mov_b32 m0, s24
	v_lshl_add_u64 v[170:171], v[8:9], 0, s[84:85]
	global_load_lds_dwordx4 v[164:165], off
	s_mov_b32 m0, s23
	v_lshl_add_u64 v[172:173], v[6:7], 0, s[84:85]
	global_load_lds_dwordx4 v[166:167], off
	s_mov_b32 m0, s22
	s_waitcnt lgkmcnt(0)
	v_mfma_f32_16x16x32_bf16 v[62:65], v[30:33], v[46:49], 0
	global_load_lds_dwordx4 v[168:169], off
	s_mov_b32 m0, s40
	v_mfma_f32_16x16x32_bf16 v[66:69], v[34:37], v[46:49], 0
	global_load_lds_dwordx4 v[170:171], off
	s_mov_b32 m0, s41
	v_mfma_f32_16x16x32_bf16 v[70:73], v[38:41], v[46:49], 0
	global_load_lds_dwordx4 v[172:173], off
	s_mov_b32 s44, s59
	v_mfma_f32_16x16x32_bf16 v[46:49], v[42:45], v[46:49], 0
	s_mov_b64 s[58:59], 0x100
	v_lshl_add_u64 v[190:191], v[2:3], 0, s[58:59]
	s_mov_b32 m0, s39
	v_mfma_f32_16x16x32_bf16 v[74:77], v[30:33], v[50:53], 0
	v_lshl_add_u64 v[192:193], v[4:5], 0, s[58:59]
	s_mov_b64 s[42:43], 0x20100
	v_lshl_add_u64 v[194:195], v[2:3], 0, s[42:43]
	v_mfma_f32_16x16x32_bf16 v[78:81], v[34:37], v[50:53], 0
	s_mov_b64 s[42:43], 0x30100
	v_lshl_add_u64 v[214:215], v[2:3], 0, s[42:43]
	v_lshl_add_u64 v[216:217], v[8:9], 0, s[58:59]
	v_mfma_f32_16x16x32_bf16 v[82:85], v[38:41], v[50:53], 0
	v_lshl_add_u64 v[218:219], v[6:7], 0, s[58:59]
	v_add_u32_e32 v11, 0xc000, v10
	s_mov_b64 s[58:59], 0x140
	v_mfma_f32_16x16x32_bf16 v[50:53], v[42:45], v[50:53], 0
	s_mov_b64 s[42:43], 0x20140
	s_lshl_b64 s[0:1], s[0:1], 11
	s_add_u32 s0, s17, s0
	v_mfma_f32_16x16x32_bf16 v[86:89], v[30:33], v[54:57], 0
	s_addc_u32 s1, s16, s1
	s_lshl_b32 s2, s2, 1
	s_add_u32 s0, s0, s2
	v_mfma_f32_16x16x32_bf16 v[90:93], v[34:37], v[54:57], 0
	s_addc_u32 s1, s1, 0
	s_movk_i32 s57, 0x1320
	s_mov_b32 s56, 0x800000
	v_mfma_f32_16x16x32_bf16 v[94:97], v[38:41], v[54:57], 0
	v_readlane_b32 s88, v225, 56
	v_mfma_f32_16x16x32_bf16 v[54:57], v[42:45], v[54:57], 0
	v_mfma_f32_16x16x32_bf16 v[98:101], v[30:33], v[58:61], 0
	v_mfma_f32_16x16x32_bf16 v[102:105], v[34:37], v[58:61], 0
	v_mfma_f32_16x16x32_bf16 v[106:109], v[38:41], v[58:61], 0
	v_mfma_f32_16x16x32_bf16 v[58:61], v[42:45], v[58:61], 0
	v_mfma_f32_16x16x32_bf16 v[126:129], v[30:33], v[110:113], 0
	v_mfma_f32_16x16x32_bf16 v[130:133], v[34:37], v[110:113], 0
	v_mfma_f32_16x16x32_bf16 v[134:137], v[38:41], v[110:113], 0
	v_mfma_f32_16x16x32_bf16 v[110:113], v[42:45], v[110:113], 0
	v_mfma_f32_16x16x32_bf16 v[138:141], v[30:33], v[114:117], 0
	v_mfma_f32_16x16x32_bf16 v[142:145], v[34:37], v[114:117], 0
	v_mfma_f32_16x16x32_bf16 v[146:149], v[38:41], v[114:117], 0
	v_mfma_f32_16x16x32_bf16 v[114:117], v[42:45], v[114:117], 0
	v_mfma_f32_16x16x32_bf16 v[150:153], v[30:33], v[118:121], 0
	v_mfma_f32_16x16x32_bf16 v[154:157], v[34:37], v[118:121], 0
	v_mfma_f32_16x16x32_bf16 v[158:161], v[38:41], v[118:121], 0
	v_mfma_f32_16x16x32_bf16 v[118:121], v[42:45], v[118:121], 0
	v_mfma_f32_16x16x32_bf16 v[30:33], v[30:33], v[122:125], 0
	v_mfma_f32_16x16x32_bf16 v[34:37], v[34:37], v[122:125], 0
	v_mfma_f32_16x16x32_bf16 v[38:41], v[38:41], v[122:125], 0
	v_mfma_f32_16x16x32_bf16 v[42:45], v[42:45], v[122:125], 0
	ds_read_b128 v[122:125], v10 offset:40960
	ds_read_b128 v[162:165], v10 offset:41984
	ds_read_b128 v[166:169], v10 offset:43008
	ds_read_b128 v[170:173], v10 offset:44032
	ds_read_b128 v[174:177], v0 offset:24576
	ds_read_b128 v[178:181], v0 offset:25600
	ds_read_b128 v[182:185], v0 offset:26624
	ds_read_b128 v[186:189], v0 offset:27648
	s_waitcnt lgkmcnt(0)
	v_mfma_f32_16x16x32_bf16 v[62:65], v[122:125], v[174:177], v[62:65]
	v_mfma_f32_16x16x32_bf16 v[66:69], v[162:165], v[174:177], v[66:69]
	v_mfma_f32_16x16x32_bf16 v[70:73], v[166:169], v[174:177], v[70:73]
	v_mfma_f32_16x16x32_bf16 v[46:49], v[170:173], v[174:177], v[46:49]
	v_mfma_f32_16x16x32_bf16 v[74:77], v[122:125], v[178:181], v[74:77]
	v_mfma_f32_16x16x32_bf16 v[78:81], v[162:165], v[178:181], v[78:81]
	v_mfma_f32_16x16x32_bf16 v[82:85], v[166:169], v[178:181], v[82:85]
	v_mfma_f32_16x16x32_bf16 v[50:53], v[170:173], v[178:181], v[50:53]
	v_mfma_f32_16x16x32_bf16 v[86:89], v[122:125], v[182:185], v[86:89]
	v_mfma_f32_16x16x32_bf16 v[90:93], v[162:165], v[182:185], v[90:93]
	v_mfma_f32_16x16x32_bf16 v[94:97], v[166:169], v[182:185], v[94:97]
	v_mfma_f32_16x16x32_bf16 v[54:57], v[170:173], v[182:185], v[54:57]
	v_mfma_f32_16x16x32_bf16 v[98:101], v[122:125], v[186:189], v[98:101]
	v_mfma_f32_16x16x32_bf16 v[102:105], v[162:165], v[186:189], v[102:105]
	v_mfma_f32_16x16x32_bf16 v[106:109], v[166:169], v[186:189], v[106:109]
	v_mfma_f32_16x16x32_bf16 v[58:61], v[170:173], v[186:189], v[58:61]
	ds_read_b128 v[174:177], v0 offset:28672
	ds_read_b128 v[178:181], v0 offset:29696
	ds_read_b128 v[182:185], v0 offset:30720
	ds_read_b128 v[186:189], v0 offset:31744
	s_waitcnt vmcnt(6) lgkmcnt(0)
	s_barrier
	global_load_lds_dwordx4 v[190:191], off
	s_mov_b32 m0, s38
	s_waitcnt lgkmcnt(0)
	v_mfma_f32_16x16x32_bf16 v[126:129], v[122:125], v[174:177], v[126:129]
	global_load_lds_dwordx4 v[192:193], off
	s_mov_b32 m0, s37
	v_mfma_f32_16x16x32_bf16 v[130:133], v[162:165], v[174:177], v[130:133]
	global_load_lds_dwordx4 v[194:195], off
	s_mov_b32 m0, s26
	v_mfma_f32_16x16x32_bf16 v[134:137], v[166:169], v[174:177], v[134:137]
	global_load_lds_dwordx4 v[214:215], off
	s_mov_b32 m0, s27
	v_mfma_f32_16x16x32_bf16 v[110:113], v[170:173], v[174:177], v[110:113]
	global_load_lds_dwordx4 v[216:217], off
	s_mov_b32 m0, s36
	v_mfma_f32_16x16x32_bf16 v[138:141], v[122:125], v[178:181], v[138:141]
	global_load_lds_dwordx4 v[218:219], off
	v_lshl_add_u64 v[190:191], v[2:3], 0, s[58:59]
	v_mfma_f32_16x16x32_bf16 v[142:145], v[162:165], v[178:181], v[142:145]
	s_mov_b32 m0, s8
	v_lshl_add_u64 v[192:193], v[4:5], 0, s[58:59]
	v_lshl_add_u64 v[194:195], v[2:3], 0, s[42:43]
	v_mfma_f32_16x16x32_bf16 v[146:149], v[166:169], v[178:181], v[146:149]
	s_mov_b64 s[42:43], 0x30140
	v_lshl_add_u64 v[214:215], v[2:3], 0, s[42:43]
	v_lshl_add_u64 v[216:217], v[8:9], 0, s[58:59]
	v_mfma_f32_16x16x32_bf16 v[114:117], v[170:173], v[178:181], v[114:117]
	v_lshl_add_u64 v[218:219], v[6:7], 0, s[58:59]
	s_mov_b64 s[58:59], 0x180
	s_mov_b64 s[42:43], 0x20180
	v_mfma_f32_16x16x32_bf16 v[150:153], v[122:125], v[182:185], v[150:153]
	v_mfma_f32_16x16x32_bf16 v[154:157], v[162:165], v[182:185], v[154:157]
	v_mfma_f32_16x16x32_bf16 v[158:161], v[166:169], v[182:185], v[158:161]
	v_mfma_f32_16x16x32_bf16 v[118:121], v[170:173], v[182:185], v[118:121]
	v_mfma_f32_16x16x32_bf16 v[30:33], v[122:125], v[186:189], v[30:33]
	v_mfma_f32_16x16x32_bf16 v[34:37], v[162:165], v[186:189], v[34:37]
	v_mfma_f32_16x16x32_bf16 v[38:41], v[166:169], v[186:189], v[38:41]
	v_mfma_f32_16x16x32_bf16 v[42:45], v[170:173], v[186:189], v[42:45]
	ds_read_b128 v[122:125], v11 offset:16384
	ds_read_b128 v[162:165], v11 offset:17408
	ds_read_b128 v[166:169], v11 offset:18432
	ds_read_b128 v[170:173], v11 offset:19456
	ds_read_b128 v[174:177], v0 offset:49152
	ds_read_b128 v[178:181], v0 offset:50176
	ds_read_b128 v[182:185], v0 offset:51200
	ds_read_b128 v[186:189], v0 offset:52224
	s_waitcnt lgkmcnt(0)
	v_mfma_f32_16x16x32_bf16 v[62:65], v[122:125], v[174:177], v[62:65]
	v_mfma_f32_16x16x32_bf16 v[66:69], v[162:165], v[174:177], v[66:69]
	v_mfma_f32_16x16x32_bf16 v[70:73], v[166:169], v[174:177], v[70:73]
	v_mfma_f32_16x16x32_bf16 v[46:49], v[170:173], v[174:177], v[46:49]
	v_mfma_f32_16x16x32_bf16 v[74:77], v[122:125], v[178:181], v[74:77]
	v_mfma_f32_16x16x32_bf16 v[78:81], v[162:165], v[178:181], v[78:81]
	v_mfma_f32_16x16x32_bf16 v[82:85], v[166:169], v[178:181], v[82:85]
	v_mfma_f32_16x16x32_bf16 v[50:53], v[170:173], v[178:181], v[50:53]
	v_mfma_f32_16x16x32_bf16 v[86:89], v[122:125], v[182:185], v[86:89]
	v_mfma_f32_16x16x32_bf16 v[90:93], v[162:165], v[182:185], v[90:93]
	v_mfma_f32_16x16x32_bf16 v[94:97], v[166:169], v[182:185], v[94:97]
	v_mfma_f32_16x16x32_bf16 v[54:57], v[170:173], v[182:185], v[54:57]
	v_mfma_f32_16x16x32_bf16 v[98:101], v[122:125], v[186:189], v[98:101]
	v_mfma_f32_16x16x32_bf16 v[102:105], v[162:165], v[186:189], v[102:105]
	v_mfma_f32_16x16x32_bf16 v[106:109], v[166:169], v[186:189], v[106:109]
	v_mfma_f32_16x16x32_bf16 v[58:61], v[170:173], v[186:189], v[58:61]
	ds_read_b128 v[174:177], v0 offset:53248
	ds_read_b128 v[178:181], v0 offset:54272
	ds_read_b128 v[182:185], v0 offset:55296
	ds_read_b128 v[186:189], v0 offset:56320
	s_waitcnt vmcnt(6) lgkmcnt(0)
	s_barrier
	global_load_lds_dwordx4 v[190:191], off
	s_mov_b32 m0, s9
	s_waitcnt lgkmcnt(0)
	v_mfma_f32_16x16x32_bf16 v[126:129], v[122:125], v[174:177], v[126:129]
	global_load_lds_dwordx4 v[192:193], off
	s_mov_b32 m0, s19
	v_mfma_f32_16x16x32_bf16 v[130:133], v[162:165], v[174:177], v[130:133]
	global_load_lds_dwordx4 v[194:195], off
	s_mov_b32 m0, s18
	v_mfma_f32_16x16x32_bf16 v[134:137], v[166:169], v[174:177], v[134:137]
	global_load_lds_dwordx4 v[214:215], off
	s_mov_b32 m0, s20
	v_mfma_f32_16x16x32_bf16 v[110:113], v[170:173], v[174:177], v[110:113]
	global_load_lds_dwordx4 v[216:217], off
	s_mov_b32 m0, s21
	v_mfma_f32_16x16x32_bf16 v[138:141], v[122:125], v[178:181], v[138:141]
	global_load_lds_dwordx4 v[218:219], off
	v_lshl_add_u64 v[190:191], v[2:3], 0, s[58:59]
	v_mfma_f32_16x16x32_bf16 v[142:145], v[162:165], v[178:181], v[142:145]
	s_mov_b32 m0, s25
	v_lshl_add_u64 v[192:193], v[4:5], 0, s[58:59]
	v_lshl_add_u64 v[194:195], v[2:3], 0, s[42:43]
	v_mfma_f32_16x16x32_bf16 v[146:149], v[166:169], v[178:181], v[146:149]
	s_mov_b64 s[42:43], 0x30180
	v_lshl_add_u64 v[214:215], v[2:3], 0, s[42:43]
	v_lshl_add_u64 v[216:217], v[8:9], 0, s[58:59]
	v_mfma_f32_16x16x32_bf16 v[114:117], v[170:173], v[178:181], v[114:117]
	v_lshl_add_u64 v[218:219], v[6:7], 0, s[58:59]
	s_mov_b64 s[42:43], 0x1c0
	s_mov_b64 s[58:59], 0x340
	v_mfma_f32_16x16x32_bf16 v[150:153], v[122:125], v[182:185], v[150:153]
	v_mfma_f32_16x16x32_bf16 v[154:157], v[162:165], v[182:185], v[154:157]
	v_mfma_f32_16x16x32_bf16 v[158:161], v[166:169], v[182:185], v[158:161]
	v_mfma_f32_16x16x32_bf16 v[118:121], v[170:173], v[182:185], v[118:121]
	v_mfma_f32_16x16x32_bf16 v[30:33], v[122:125], v[186:189], v[30:33]
	v_mfma_f32_16x16x32_bf16 v[34:37], v[162:165], v[186:189], v[34:37]
	v_mfma_f32_16x16x32_bf16 v[38:41], v[166:169], v[186:189], v[38:41]
	v_mfma_f32_16x16x32_bf16 v[42:45], v[170:173], v[186:189], v[42:45]
	ds_read_b128 v[122:125], v10 offset:16384
	ds_read_b128 v[162:165], v10 offset:17408
	ds_read_b128 v[166:169], v10 offset:18432
	ds_read_b128 v[170:173], v10 offset:19456
	ds_read_b128 v[174:177], v0
	ds_read_b128 v[178:181], v0 offset:1024
	ds_read_b128 v[182:185], v0 offset:2048
	ds_read_b128 v[186:189], v0 offset:3072
	s_waitcnt lgkmcnt(0)
	v_mfma_f32_16x16x32_bf16 v[62:65], v[122:125], v[174:177], v[62:65]
	v_mfma_f32_16x16x32_bf16 v[66:69], v[162:165], v[174:177], v[66:69]
	v_mfma_f32_16x16x32_bf16 v[70:73], v[166:169], v[174:177], v[70:73]
	v_mfma_f32_16x16x32_bf16 v[46:49], v[170:173], v[174:177], v[46:49]
	v_mfma_f32_16x16x32_bf16 v[74:77], v[122:125], v[178:181], v[74:77]
	v_mfma_f32_16x16x32_bf16 v[78:81], v[162:165], v[178:181], v[78:81]
	v_mfma_f32_16x16x32_bf16 v[82:85], v[166:169], v[178:181], v[82:85]
	v_mfma_f32_16x16x32_bf16 v[50:53], v[170:173], v[178:181], v[50:53]
	v_mfma_f32_16x16x32_bf16 v[86:89], v[122:125], v[182:185], v[86:89]
	v_mfma_f32_16x16x32_bf16 v[90:93], v[162:165], v[182:185], v[90:93]
	v_mfma_f32_16x16x32_bf16 v[94:97], v[166:169], v[182:185], v[94:97]
	v_mfma_f32_16x16x32_bf16 v[54:57], v[170:173], v[182:185], v[54:57]
	v_mfma_f32_16x16x32_bf16 v[98:101], v[122:125], v[186:189], v[98:101]
	v_mfma_f32_16x16x32_bf16 v[102:105], v[162:165], v[186:189], v[102:105]
	v_mfma_f32_16x16x32_bf16 v[106:109], v[166:169], v[186:189], v[106:109]
	v_mfma_f32_16x16x32_bf16 v[58:61], v[170:173], v[186:189], v[58:61]
	ds_read_b128 v[174:177], v0 offset:4096
	ds_read_b128 v[178:181], v0 offset:5120
	ds_read_b128 v[182:185], v0 offset:6144
	ds_read_b128 v[186:189], v0 offset:7168
	s_waitcnt vmcnt(6) lgkmcnt(0)
	s_barrier
	global_load_lds_dwordx4 v[190:191], off
	s_mov_b32 m0, s24
	s_waitcnt lgkmcnt(0)
	v_mfma_f32_16x16x32_bf16 v[126:129], v[122:125], v[174:177], v[126:129]
	global_load_lds_dwordx4 v[192:193], off
	s_mov_b32 m0, s23
	v_mfma_f32_16x16x32_bf16 v[130:133], v[162:165], v[174:177], v[130:133]
	global_load_lds_dwordx4 v[194:195], off
	s_mov_b32 m0, s22
	v_mfma_f32_16x16x32_bf16 v[134:137], v[166:169], v[174:177], v[134:137]
	global_load_lds_dwordx4 v[214:215], off
	s_mov_b32 m0, s40
	v_mfma_f32_16x16x32_bf16 v[110:113], v[170:173], v[174:177], v[110:113]
	global_load_lds_dwordx4 v[216:217], off
	s_mov_b32 m0, s41
	v_mfma_f32_16x16x32_bf16 v[138:141], v[122:125], v[178:181], v[138:141]
	global_load_lds_dwordx4 v[218:219], off
	v_lshl_add_u64 v[190:191], v[2:3], 0, s[42:43]
	v_mfma_f32_16x16x32_bf16 v[142:145], v[162:165], v[178:181], v[142:145]
	s_mov_b32 m0, s39
	v_lshl_add_u64 v[192:193], v[4:5], 0, s[42:43]
	s_mov_b64 s[24:25], 0x201c0
	v_mfma_f32_16x16x32_bf16 v[146:149], v[166:169], v[178:181], v[146:149]
	v_lshl_add_u64 v[194:195], v[2:3], 0, s[24:25]
	s_mov_b64 s[22:23], 0x301c0
	v_lshl_add_u64 v[214:215], v[2:3], 0, s[22:23]
	v_mfma_f32_16x16x32_bf16 v[114:117], v[170:173], v[178:181], v[114:117]
	v_lshl_add_u64 v[216:217], v[8:9], 0, s[42:43]
	v_lshl_add_u64 v[218:219], v[6:7], 0, s[42:43]
	s_mov_b64 s[24:25], 0x200
	v_mfma_f32_16x16x32_bf16 v[150:153], v[122:125], v[182:185], v[150:153]
	s_mov_b64 s[22:23], 0x20200
	s_mov_b64 s[40:41], 0x20300
	v_readfirstlane_b32 s39, v15
	v_mfma_f32_16x16x32_bf16 v[154:157], v[162:165], v[182:185], v[154:157]
	s_mov_b64 s[42:43], 0x300
	v_mfma_f32_16x16x32_bf16 v[158:161], v[166:169], v[182:185], v[158:161]
	v_mfma_f32_16x16x32_bf16 v[118:121], v[170:173], v[182:185], v[118:121]
	v_mfma_f32_16x16x32_bf16 v[30:33], v[122:125], v[186:189], v[30:33]
	v_mfma_f32_16x16x32_bf16 v[34:37], v[162:165], v[186:189], v[34:37]
	v_mfma_f32_16x16x32_bf16 v[38:41], v[166:169], v[186:189], v[38:41]
	v_mfma_f32_16x16x32_bf16 v[42:45], v[170:173], v[186:189], v[42:45]
	ds_read_b128 v[122:125], v10 offset:40960
	ds_read_b128 v[162:165], v10 offset:41984
	ds_read_b128 v[166:169], v10 offset:43008
	ds_read_b128 v[170:173], v10 offset:44032
	ds_read_b128 v[174:177], v0 offset:24576
	ds_read_b128 v[178:181], v0 offset:25600
	ds_read_b128 v[182:185], v0 offset:26624
	ds_read_b128 v[186:189], v0 offset:27648
	s_waitcnt lgkmcnt(0)
	v_mfma_f32_16x16x32_bf16 v[62:65], v[122:125], v[174:177], v[62:65]
	v_mfma_f32_16x16x32_bf16 v[66:69], v[162:165], v[174:177], v[66:69]
	v_mfma_f32_16x16x32_bf16 v[70:73], v[166:169], v[174:177], v[70:73]
	v_mfma_f32_16x16x32_bf16 v[46:49], v[170:173], v[174:177], v[46:49]
	v_mfma_f32_16x16x32_bf16 v[74:77], v[122:125], v[178:181], v[74:77]
	v_mfma_f32_16x16x32_bf16 v[78:81], v[162:165], v[178:181], v[78:81]
	v_mfma_f32_16x16x32_bf16 v[82:85], v[166:169], v[178:181], v[82:85]
	v_mfma_f32_16x16x32_bf16 v[50:53], v[170:173], v[178:181], v[50:53]
	v_mfma_f32_16x16x32_bf16 v[86:89], v[122:125], v[182:185], v[86:89]
	v_mfma_f32_16x16x32_bf16 v[90:93], v[162:165], v[182:185], v[90:93]
	v_mfma_f32_16x16x32_bf16 v[94:97], v[166:169], v[182:185], v[94:97]
	v_mfma_f32_16x16x32_bf16 v[54:57], v[170:173], v[182:185], v[54:57]
	v_mfma_f32_16x16x32_bf16 v[98:101], v[122:125], v[186:189], v[98:101]
	v_mfma_f32_16x16x32_bf16 v[102:105], v[162:165], v[186:189], v[102:105]
	v_mfma_f32_16x16x32_bf16 v[106:109], v[166:169], v[186:189], v[106:109]
	v_mfma_f32_16x16x32_bf16 v[58:61], v[170:173], v[186:189], v[58:61]
	ds_read_b128 v[174:177], v0 offset:28672
	ds_read_b128 v[178:181], v0 offset:29696
	ds_read_b128 v[182:185], v0 offset:30720
	ds_read_b128 v[186:189], v0 offset:31744
	s_waitcnt vmcnt(6) lgkmcnt(0)
	s_barrier
	global_load_lds_dwordx4 v[190:191], off
	s_mov_b32 m0, s38
	s_waitcnt lgkmcnt(0)
	v_mfma_f32_16x16x32_bf16 v[126:129], v[122:125], v[174:177], v[126:129]
	global_load_lds_dwordx4 v[192:193], off
	s_mov_b32 m0, s37
	v_mfma_f32_16x16x32_bf16 v[130:133], v[162:165], v[174:177], v[130:133]
	global_load_lds_dwordx4 v[194:195], off
	s_mov_b32 m0, s26
	v_mfma_f32_16x16x32_bf16 v[134:137], v[166:169], v[174:177], v[134:137]
	global_load_lds_dwordx4 v[214:215], off
	s_mov_b32 m0, s27
	v_mfma_f32_16x16x32_bf16 v[110:113], v[170:173], v[174:177], v[110:113]
	global_load_lds_dwordx4 v[216:217], off
	s_mov_b32 m0, s36
	v_mfma_f32_16x16x32_bf16 v[138:141], v[122:125], v[178:181], v[138:141]
	global_load_lds_dwordx4 v[218:219], off
	v_lshl_add_u64 v[190:191], v[2:3], 0, s[24:25]
	v_mfma_f32_16x16x32_bf16 v[142:145], v[162:165], v[178:181], v[142:145]
	s_mov_b32 m0, s8
	v_lshl_add_u64 v[192:193], v[4:5], 0, s[24:25]
	v_lshl_add_u64 v[194:195], v[2:3], 0, s[22:23]
	v_mfma_f32_16x16x32_bf16 v[146:149], v[166:169], v[178:181], v[146:149]
	s_mov_b64 s[22:23], 0x30200
	v_lshl_add_u64 v[214:215], v[2:3], 0, s[22:23]
	v_lshl_add_u64 v[216:217], v[8:9], 0, s[24:25]
	v_mfma_f32_16x16x32_bf16 v[114:117], v[170:173], v[178:181], v[114:117]
	v_lshl_add_u64 v[218:219], v[6:7], 0, s[24:25]
	s_mov_b64 s[22:23], 0x240
	v_readfirstlane_b32 s24, v25
	v_mfma_f32_16x16x32_bf16 v[150:153], v[122:125], v[182:185], v[150:153]
	s_mov_b64 s[26:27], 0x202c0
	v_readfirstlane_b32 s25, v22
	s_mov_b64 s[36:37], 0x2c0
	v_mfma_f32_16x16x32_bf16 v[154:157], v[162:165], v[182:185], v[154:157]
	v_readfirstlane_b32 s38, v14
	v_mfma_f32_16x16x32_bf16 v[158:161], v[166:169], v[182:185], v[158:161]
	v_mfma_f32_16x16x32_bf16 v[118:121], v[170:173], v[182:185], v[118:121]
	v_mfma_f32_16x16x32_bf16 v[30:33], v[122:125], v[186:189], v[30:33]
	v_mfma_f32_16x16x32_bf16 v[34:37], v[162:165], v[186:189], v[34:37]
	v_mfma_f32_16x16x32_bf16 v[38:41], v[166:169], v[186:189], v[38:41]
	v_mfma_f32_16x16x32_bf16 v[42:45], v[170:173], v[186:189], v[42:45]
	ds_read_b128 v[122:125], v11 offset:16384
	ds_read_b128 v[162:165], v11 offset:17408
	ds_read_b128 v[166:169], v11 offset:18432
	ds_read_b128 v[170:173], v11 offset:19456
	ds_read_b128 v[174:177], v0 offset:49152
	ds_read_b128 v[178:181], v0 offset:50176
	ds_read_b128 v[182:185], v0 offset:51200
	ds_read_b128 v[186:189], v0 offset:52224
	s_waitcnt lgkmcnt(0)
	v_mfma_f32_16x16x32_bf16 v[62:65], v[122:125], v[174:177], v[62:65]
	v_mfma_f32_16x16x32_bf16 v[66:69], v[162:165], v[174:177], v[66:69]
	v_mfma_f32_16x16x32_bf16 v[70:73], v[166:169], v[174:177], v[70:73]
	v_mfma_f32_16x16x32_bf16 v[46:49], v[170:173], v[174:177], v[46:49]
	v_mfma_f32_16x16x32_bf16 v[74:77], v[122:125], v[178:181], v[74:77]
	v_mfma_f32_16x16x32_bf16 v[78:81], v[162:165], v[178:181], v[78:81]
	v_mfma_f32_16x16x32_bf16 v[82:85], v[166:169], v[178:181], v[82:85]
	v_mfma_f32_16x16x32_bf16 v[50:53], v[170:173], v[178:181], v[50:53]
	v_mfma_f32_16x16x32_bf16 v[86:89], v[122:125], v[182:185], v[86:89]
	v_mfma_f32_16x16x32_bf16 v[90:93], v[162:165], v[182:185], v[90:93]
	v_mfma_f32_16x16x32_bf16 v[94:97], v[166:169], v[182:185], v[94:97]
	v_mfma_f32_16x16x32_bf16 v[54:57], v[170:173], v[182:185], v[54:57]
	v_mfma_f32_16x16x32_bf16 v[98:101], v[122:125], v[186:189], v[98:101]
	v_mfma_f32_16x16x32_bf16 v[102:105], v[162:165], v[186:189], v[102:105]
	v_mfma_f32_16x16x32_bf16 v[106:109], v[166:169], v[186:189], v[106:109]
	v_mfma_f32_16x16x32_bf16 v[58:61], v[170:173], v[186:189], v[58:61]
	ds_read_b128 v[174:177], v0 offset:53248
	ds_read_b128 v[178:181], v0 offset:54272
	ds_read_b128 v[182:185], v0 offset:55296
	ds_read_b128 v[186:189], v0 offset:56320
	s_waitcnt vmcnt(6) lgkmcnt(0)
	s_barrier
	global_load_lds_dwordx4 v[190:191], off
	s_mov_b32 m0, s9
	s_waitcnt lgkmcnt(0)
	v_mfma_f32_16x16x32_bf16 v[126:129], v[122:125], v[174:177], v[126:129]
	global_load_lds_dwordx4 v[192:193], off
	s_mov_b32 m0, s19
	v_mfma_f32_16x16x32_bf16 v[130:133], v[162:165], v[174:177], v[130:133]
	global_load_lds_dwordx4 v[194:195], off
	s_mov_b32 m0, s18
	v_mfma_f32_16x16x32_bf16 v[134:137], v[166:169], v[174:177], v[134:137]
	global_load_lds_dwordx4 v[214:215], off
	s_mov_b32 m0, s20
	v_mfma_f32_16x16x32_bf16 v[110:113], v[170:173], v[174:177], v[110:113]
	global_load_lds_dwordx4 v[216:217], off
	s_mov_b32 m0, s21
	v_mfma_f32_16x16x32_bf16 v[138:141], v[122:125], v[178:181], v[138:141]
	global_load_lds_dwordx4 v[218:219], off
	s_mov_b64 s[8:9], 0x20240
	v_mfma_f32_16x16x32_bf16 v[142:145], v[162:165], v[178:181], v[142:145]
	v_lshl_add_u64 v[194:195], v[2:3], 0, s[8:9]
	s_mov_b64 s[8:9], 0x30240
	v_lshl_add_u64 v[214:215], v[2:3], 0, s[8:9]
	v_mfma_f32_16x16x32_bf16 v[146:149], v[166:169], v[178:181], v[146:149]
	v_readfirstlane_b32 s8, v19
	v_lshl_add_u64 v[190:191], v[2:3], 0, s[22:23]
	s_mov_b32 m0, s8
	v_mfma_f32_16x16x32_bf16 v[114:117], v[170:173], v[178:181], v[114:117]
	v_readfirstlane_b32 s9, v21
	v_lshl_add_u64 v[192:193], v[4:5], 0, s[22:23]
	v_readfirstlane_b32 s18, v20
	v_mfma_f32_16x16x32_bf16 v[150:153], v[122:125], v[182:185], v[150:153]
	s_mov_b64 s[20:21], 0x20280
	v_readfirstlane_b32 s19, v18
	v_lshl_add_u64 v[216:217], v[8:9], 0, s[22:23]
	v_mfma_f32_16x16x32_bf16 v[154:157], v[162:165], v[182:185], v[154:157]
	v_lshl_add_u64 v[218:219], v[6:7], 0, s[22:23]
	s_mov_b64 s[22:23], 0x280
	v_mfma_f32_16x16x32_bf16 v[158:161], v[166:169], v[182:185], v[158:161]
	v_mfma_f32_16x16x32_bf16 v[118:121], v[170:173], v[182:185], v[118:121]
	v_mfma_f32_16x16x32_bf16 v[30:33], v[122:125], v[186:189], v[30:33]
	v_mfma_f32_16x16x32_bf16 v[34:37], v[162:165], v[186:189], v[34:37]
	v_mfma_f32_16x16x32_bf16 v[38:41], v[166:169], v[186:189], v[38:41]
	v_mfma_f32_16x16x32_bf16 v[42:45], v[170:173], v[186:189], v[42:45]
	ds_read_b128 v[122:125], v10 offset:16384
	ds_read_b128 v[162:165], v10 offset:17408
	ds_read_b128 v[166:169], v10 offset:18432
	ds_read_b128 v[170:173], v10 offset:19456
	ds_read_b128 v[174:177], v0
	ds_read_b128 v[178:181], v0 offset:1024
	ds_read_b128 v[182:185], v0 offset:2048
	ds_read_b128 v[186:189], v0 offset:3072
	s_waitcnt lgkmcnt(0)
	v_mfma_f32_16x16x32_bf16 v[62:65], v[122:125], v[174:177], v[62:65]
	v_mfma_f32_16x16x32_bf16 v[66:69], v[162:165], v[174:177], v[66:69]
	v_mfma_f32_16x16x32_bf16 v[70:73], v[166:169], v[174:177], v[70:73]
	v_mfma_f32_16x16x32_bf16 v[46:49], v[170:173], v[174:177], v[46:49]
	v_mfma_f32_16x16x32_bf16 v[74:77], v[122:125], v[178:181], v[74:77]
	v_mfma_f32_16x16x32_bf16 v[78:81], v[162:165], v[178:181], v[78:81]
	v_mfma_f32_16x16x32_bf16 v[82:85], v[166:169], v[178:181], v[82:85]
	v_mfma_f32_16x16x32_bf16 v[50:53], v[170:173], v[178:181], v[50:53]
	v_mfma_f32_16x16x32_bf16 v[86:89], v[122:125], v[182:185], v[86:89]
	v_mfma_f32_16x16x32_bf16 v[90:93], v[162:165], v[182:185], v[90:93]
	v_mfma_f32_16x16x32_bf16 v[94:97], v[166:169], v[182:185], v[94:97]
	v_mfma_f32_16x16x32_bf16 v[54:57], v[170:173], v[182:185], v[54:57]
	v_mfma_f32_16x16x32_bf16 v[98:101], v[122:125], v[186:189], v[98:101]
	v_mfma_f32_16x16x32_bf16 v[102:105], v[162:165], v[186:189], v[102:105]
	v_mfma_f32_16x16x32_bf16 v[106:109], v[166:169], v[186:189], v[106:109]
	v_mfma_f32_16x16x32_bf16 v[58:61], v[170:173], v[186:189], v[58:61]
	ds_read_b128 v[174:177], v0 offset:4096
	ds_read_b128 v[178:181], v0 offset:5120
	ds_read_b128 v[182:185], v0 offset:6144
	ds_read_b128 v[186:189], v0 offset:7168
	s_waitcnt vmcnt(6) lgkmcnt(0)
	s_barrier
	global_load_lds_dwordx4 v[190:191], off
	s_mov_b32 m0, s9
	v_lshl_add_u64 v[190:191], v[2:3], 0, s[20:21]
	global_load_lds_dwordx4 v[192:193], off
	s_mov_b32 m0, s18
	s_mov_b64 s[20:21], 0x30280
	global_load_lds_dwordx4 v[194:195], off
	s_mov_b32 m0, s19
	v_lshl_add_u64 v[192:193], v[2:3], 0, s[20:21]
	v_readfirstlane_b32 s21, v28
	global_load_lds_dwordx4 v[214:215], off
	s_mov_b32 m0, s21
	v_readfirstlane_b32 s20, v29
	global_load_lds_dwordx4 v[216:217], off
	s_mov_b32 m0, s20
	s_waitcnt lgkmcnt(0)
	v_mfma_f32_16x16x32_bf16 v[126:129], v[122:125], v[174:177], v[126:129]
	global_load_lds_dwordx4 v[218:219], off
	v_lshl_add_u64 v[194:195], v[8:9], 0, s[22:23]
	v_mfma_f32_16x16x32_bf16 v[130:133], v[162:165], v[174:177], v[130:133]
	v_lshl_add_u64 v[214:215], v[6:7], 0, s[22:23]
	v_mfma_f32_16x16x32_bf16 v[134:137], v[166:169], v[174:177], v[134:137]
	v_mfma_f32_16x16x32_bf16 v[110:113], v[170:173], v[174:177], v[110:113]
	v_mfma_f32_16x16x32_bf16 v[138:141], v[122:125], v[178:181], v[138:141]
	v_mfma_f32_16x16x32_bf16 v[142:145], v[162:165], v[178:181], v[142:145]
	v_mfma_f32_16x16x32_bf16 v[146:149], v[166:169], v[178:181], v[146:149]
	v_mfma_f32_16x16x32_bf16 v[114:117], v[170:173], v[178:181], v[114:117]
	v_mfma_f32_16x16x32_bf16 v[150:153], v[122:125], v[182:185], v[150:153]
	v_mfma_f32_16x16x32_bf16 v[154:157], v[162:165], v[182:185], v[154:157]
	v_mfma_f32_16x16x32_bf16 v[158:161], v[166:169], v[182:185], v[158:161]
	v_mfma_f32_16x16x32_bf16 v[118:121], v[170:173], v[182:185], v[118:121]
	v_mfma_f32_16x16x32_bf16 v[30:33], v[122:125], v[186:189], v[30:33]
	v_mfma_f32_16x16x32_bf16 v[34:37], v[162:165], v[186:189], v[34:37]
	v_mfma_f32_16x16x32_bf16 v[38:41], v[166:169], v[186:189], v[38:41]
	v_mfma_f32_16x16x32_bf16 v[42:45], v[170:173], v[186:189], v[42:45]
	ds_read_b128 v[18:21], v10 offset:40960
	ds_read_b128 v[122:125], v10 offset:41984
	ds_read_b128 v[162:165], v10 offset:43008
	ds_read_b128 v[166:169], v10 offset:44032
	ds_read_b128 v[170:173], v0 offset:24576
	ds_read_b128 v[174:177], v0 offset:25600
	ds_read_b128 v[178:181], v0 offset:26624
	ds_read_b128 v[182:185], v0 offset:27648
	v_lshl_add_u64 v[186:187], v[2:3], 0, s[22:23]
	v_lshl_add_u64 v[188:189], v[4:5], 0, s[22:23]
	v_readfirstlane_b32 s22, v27
	s_waitcnt lgkmcnt(0)
	v_mfma_f32_16x16x32_bf16 v[62:65], v[18:21], v[170:173], v[62:65]
	s_mov_b32 m0, s22
	v_readfirstlane_b32 s23, v26
	v_mfma_f32_16x16x32_bf16 v[66:69], v[122:125], v[170:173], v[66:69]
	v_mfma_f32_16x16x32_bf16 v[70:73], v[162:165], v[170:173], v[70:73]
	v_mfma_f32_16x16x32_bf16 v[46:49], v[166:169], v[170:173], v[46:49]
	v_mfma_f32_16x16x32_bf16 v[74:77], v[18:21], v[174:177], v[74:77]
	v_mfma_f32_16x16x32_bf16 v[78:81], v[122:125], v[174:177], v[78:81]
	v_mfma_f32_16x16x32_bf16 v[82:85], v[162:165], v[174:177], v[82:85]
	v_mfma_f32_16x16x32_bf16 v[50:53], v[166:169], v[174:177], v[50:53]
	v_mfma_f32_16x16x32_bf16 v[86:89], v[18:21], v[178:181], v[86:89]
	v_mfma_f32_16x16x32_bf16 v[90:93], v[122:125], v[178:181], v[90:93]
	v_mfma_f32_16x16x32_bf16 v[94:97], v[162:165], v[178:181], v[94:97]
	v_mfma_f32_16x16x32_bf16 v[54:57], v[166:169], v[178:181], v[54:57]
	v_mfma_f32_16x16x32_bf16 v[98:101], v[18:21], v[182:185], v[98:101]
	v_mfma_f32_16x16x32_bf16 v[102:105], v[122:125], v[182:185], v[102:105]
	v_mfma_f32_16x16x32_bf16 v[106:109], v[162:165], v[182:185], v[106:109]
	v_mfma_f32_16x16x32_bf16 v[58:61], v[166:169], v[182:185], v[58:61]
	ds_read_b128 v[170:173], v0 offset:28672
	ds_read_b128 v[174:177], v0 offset:29696
	ds_read_b128 v[178:181], v0 offset:30720
	ds_read_b128 v[182:185], v0 offset:31744
	s_waitcnt vmcnt(6) lgkmcnt(0)
	s_barrier
	global_load_lds_dwordx4 v[186:187], off
	s_mov_b32 m0, s23
	v_lshl_add_u64 v[186:187], v[2:3], 0, s[26:27]
	global_load_lds_dwordx4 v[188:189], off
	s_mov_b32 m0, s24
	s_mov_b64 s[26:27], 0x302c0
	global_load_lds_dwordx4 v[190:191], off
	s_mov_b32 m0, s25
	v_lshl_add_u64 v[188:189], v[2:3], 0, s[26:27]
	v_readfirstlane_b32 s26, v23
	global_load_lds_dwordx4 v[192:193], off
	s_mov_b32 m0, s26
	v_readfirstlane_b32 s27, v24
	global_load_lds_dwordx4 v[194:195], off
	s_mov_b32 m0, s27
	s_waitcnt lgkmcnt(0)
	v_mfma_f32_16x16x32_bf16 v[126:129], v[18:21], v[170:173], v[126:129]
	global_load_lds_dwordx4 v[214:215], off
	v_lshl_add_u64 v[190:191], v[8:9], 0, s[36:37]
	v_mfma_f32_16x16x32_bf16 v[130:133], v[122:125], v[170:173], v[130:133]
	v_lshl_add_u64 v[192:193], v[6:7], 0, s[36:37]
	v_mfma_f32_16x16x32_bf16 v[134:137], v[162:165], v[170:173], v[134:137]
	v_mfma_f32_16x16x32_bf16 v[110:113], v[166:169], v[170:173], v[110:113]
	v_mfma_f32_16x16x32_bf16 v[138:141], v[18:21], v[174:177], v[138:141]
	v_mfma_f32_16x16x32_bf16 v[142:145], v[122:125], v[174:177], v[142:145]
	v_mfma_f32_16x16x32_bf16 v[146:149], v[162:165], v[174:177], v[146:149]
	v_mfma_f32_16x16x32_bf16 v[114:117], v[166:169], v[174:177], v[114:117]
	v_mfma_f32_16x16x32_bf16 v[150:153], v[18:21], v[178:181], v[150:153]
	v_mfma_f32_16x16x32_bf16 v[154:157], v[122:125], v[178:181], v[154:157]
	v_mfma_f32_16x16x32_bf16 v[158:161], v[162:165], v[178:181], v[158:161]
	v_mfma_f32_16x16x32_bf16 v[118:121], v[166:169], v[178:181], v[118:121]
	v_mfma_f32_16x16x32_bf16 v[18:21], v[18:21], v[182:185], v[30:33]
	v_mfma_f32_16x16x32_bf16 v[28:31], v[122:125], v[182:185], v[34:37]
	v_mfma_f32_16x16x32_bf16 v[32:35], v[162:165], v[182:185], v[38:41]
	v_mfma_f32_16x16x32_bf16 v[36:39], v[166:169], v[182:185], v[42:45]
	ds_read_b128 v[22:25], v11 offset:16384
	s_nop 1
	ds_read_b128 v[40:43], v11 offset:17408
	ds_read_b128 v[122:125], v11 offset:18432
	ds_read_b128 v[162:165], v11 offset:19456
	ds_read_b128 v[166:169], v0 offset:49152
	ds_read_b128 v[170:173], v0 offset:50176
	ds_read_b128 v[174:177], v0 offset:51200
	ds_read_b128 v[178:181], v0 offset:52224
	v_lshl_add_u64 v[182:183], v[2:3], 0, s[36:37]
	v_lshl_add_u64 v[184:185], v[4:5], 0, s[36:37]
	v_readfirstlane_b32 s36, v12
	s_waitcnt lgkmcnt(0)
	v_mfma_f32_16x16x32_bf16 v[62:65], v[22:25], v[166:169], v[62:65]
	s_mov_b32 m0, s36
	v_readfirstlane_b32 s37, v13
	v_mfma_f32_16x16x32_bf16 v[66:69], v[40:43], v[166:169], v[66:69]
	v_mfma_f32_16x16x32_bf16 v[70:73], v[122:125], v[166:169], v[70:73]
	v_mfma_f32_16x16x32_bf16 v[44:47], v[162:165], v[166:169], v[46:49]
	v_mfma_f32_16x16x32_bf16 v[74:77], v[22:25], v[170:173], v[74:77]
	v_mfma_f32_16x16x32_bf16 v[78:81], v[40:43], v[170:173], v[78:81]
	v_mfma_f32_16x16x32_bf16 v[82:85], v[122:125], v[170:173], v[82:85]
	v_mfma_f32_16x16x32_bf16 v[48:51], v[162:165], v[170:173], v[50:53]
	v_mfma_f32_16x16x32_bf16 v[86:89], v[22:25], v[174:177], v[86:89]
	v_mfma_f32_16x16x32_bf16 v[90:93], v[40:43], v[174:177], v[90:93]
	v_mfma_f32_16x16x32_bf16 v[94:97], v[122:125], v[174:177], v[94:97]
	v_mfma_f32_16x16x32_bf16 v[52:55], v[162:165], v[174:177], v[54:57]
	v_mfma_f32_16x16x32_bf16 v[98:101], v[22:25], v[178:181], v[98:101]
	v_mfma_f32_16x16x32_bf16 v[102:105], v[40:43], v[178:181], v[102:105]
	v_mfma_f32_16x16x32_bf16 v[106:109], v[122:125], v[178:181], v[106:109]
	v_mfma_f32_16x16x32_bf16 v[56:59], v[162:165], v[178:181], v[58:61]
	ds_read_b128 v[166:169], v0 offset:53248
	ds_read_b128 v[170:173], v0 offset:54272
	ds_read_b128 v[174:177], v0 offset:55296
	ds_read_b128 v[178:181], v0 offset:56320
	s_waitcnt vmcnt(6) lgkmcnt(0)
	s_barrier
	global_load_lds_dwordx4 v[182:183], off
	s_mov_b32 m0, s37
	v_lshl_add_u64 v[182:183], v[2:3], 0, s[40:41]
	global_load_lds_dwordx4 v[184:185], off
	s_mov_b32 m0, s38
	s_mov_b64 s[40:41], 0x30300
	global_load_lds_dwordx4 v[186:187], off
	s_mov_b32 m0, s39
	v_lshl_add_u64 v[184:185], v[2:3], 0, s[40:41]
	v_readfirstlane_b32 s40, v16
	global_load_lds_dwordx4 v[188:189], off
	s_mov_b32 m0, s40
	v_readfirstlane_b32 s41, v17
	global_load_lds_dwordx4 v[190:191], off
	s_mov_b32 m0, s41
	s_waitcnt lgkmcnt(0)
	v_mfma_f32_16x16x32_bf16 v[126:129], v[22:25], v[166:169], v[126:129]
	global_load_lds_dwordx4 v[192:193], off
	s_mov_b32 m0, s8
	v_mfma_f32_16x16x32_bf16 v[130:133], v[40:43], v[166:169], v[130:133]
	v_lshl_add_u64 v[186:187], v[8:9], 0, s[42:43]
	v_lshl_add_u64 v[188:189], v[6:7], 0, s[42:43]
	v_mfma_f32_16x16x32_bf16 v[134:137], v[122:125], v[166:169], v[134:137]
	v_mfma_f32_16x16x32_bf16 v[110:113], v[162:165], v[166:169], v[110:113]
	v_mfma_f32_16x16x32_bf16 v[138:141], v[22:25], v[170:173], v[138:141]
	v_mfma_f32_16x16x32_bf16 v[142:145], v[40:43], v[170:173], v[142:145]
	v_mfma_f32_16x16x32_bf16 v[146:149], v[122:125], v[170:173], v[146:149]
	v_mfma_f32_16x16x32_bf16 v[114:117], v[162:165], v[170:173], v[114:117]
	v_mfma_f32_16x16x32_bf16 v[150:153], v[22:25], v[174:177], v[150:153]
	v_mfma_f32_16x16x32_bf16 v[154:157], v[40:43], v[174:177], v[154:157]
	v_mfma_f32_16x16x32_bf16 v[158:161], v[122:125], v[174:177], v[158:161]
	v_mfma_f32_16x16x32_bf16 v[118:121], v[162:165], v[174:177], v[118:121]
	v_mfma_f32_16x16x32_bf16 v[18:21], v[22:25], v[178:181], v[18:21]
	v_mfma_f32_16x16x32_bf16 v[22:25], v[40:43], v[178:181], v[28:31]
	v_mfma_f32_16x16x32_bf16 v[26:29], v[122:125], v[178:181], v[32:35]
	v_mfma_f32_16x16x32_bf16 v[30:33], v[162:165], v[178:181], v[36:39]
	ds_read_b128 v[12:15], v10 offset:16384
	s_nop 1
	ds_read_b128 v[34:37], v10 offset:17408
	ds_read_b128 v[38:41], v10 offset:18432
	ds_read_b128 v[122:125], v10 offset:19456
	ds_read_b128 v[162:165], v0
	ds_read_b128 v[166:169], v0 offset:1024
	ds_read_b128 v[170:173], v0 offset:2048
	ds_read_b128 v[174:177], v0 offset:3072
	v_lshl_add_u64 v[178:179], v[2:3], 0, s[42:43]
	v_lshl_add_u64 v[180:181], v[4:5], 0, s[42:43]
	s_waitcnt lgkmcnt(0)
	v_mfma_f32_16x16x32_bf16 v[60:63], v[12:15], v[162:165], v[62:65]
	s_mov_b64 s[42:43], 0x20340
	v_mfma_f32_16x16x32_bf16 v[64:67], v[34:37], v[162:165], v[66:69]
	v_mfma_f32_16x16x32_bf16 v[68:71], v[38:41], v[162:165], v[70:73]
	v_mfma_f32_16x16x32_bf16 v[42:45], v[122:125], v[162:165], v[44:47]
	v_mfma_f32_16x16x32_bf16 v[72:75], v[12:15], v[166:169], v[74:77]
	v_mfma_f32_16x16x32_bf16 v[76:79], v[34:37], v[166:169], v[78:81]
	v_mfma_f32_16x16x32_bf16 v[80:83], v[38:41], v[166:169], v[82:85]
	v_mfma_f32_16x16x32_bf16 v[46:49], v[122:125], v[166:169], v[48:51]
	v_mfma_f32_16x16x32_bf16 v[84:87], v[12:15], v[170:173], v[86:89]
	v_mfma_f32_16x16x32_bf16 v[88:91], v[34:37], v[170:173], v[90:93]
	v_mfma_f32_16x16x32_bf16 v[92:95], v[38:41], v[170:173], v[94:97]
	v_mfma_f32_16x16x32_bf16 v[50:53], v[122:125], v[170:173], v[52:55]
	v_mfma_f32_16x16x32_bf16 v[96:99], v[12:15], v[174:177], v[98:101]
	v_mfma_f32_16x16x32_bf16 v[100:103], v[34:37], v[174:177], v[102:105]
	v_mfma_f32_16x16x32_bf16 v[104:107], v[38:41], v[174:177], v[106:109]
	v_mfma_f32_16x16x32_bf16 v[54:57], v[122:125], v[174:177], v[56:59]
	ds_read_b128 v[162:165], v0 offset:4096
	ds_read_b128 v[166:169], v0 offset:5120
	ds_read_b128 v[170:173], v0 offset:6144
	ds_read_b128 v[174:177], v0 offset:7168
	s_waitcnt vmcnt(6) lgkmcnt(0)
	s_barrier
	global_load_lds_dwordx4 v[178:179], off
	s_mov_b32 m0, s9
	s_waitcnt lgkmcnt(0)
	v_mfma_f32_16x16x32_bf16 v[126:129], v[12:15], v[162:165], v[126:129]
	global_load_lds_dwordx4 v[180:181], off
	s_mov_b32 m0, s18
	v_mfma_f32_16x16x32_bf16 v[130:133], v[34:37], v[162:165], v[130:133]
	global_load_lds_dwordx4 v[182:183], off
	s_mov_b32 m0, s19
	v_mfma_f32_16x16x32_bf16 v[134:137], v[38:41], v[162:165], v[134:137]
	global_load_lds_dwordx4 v[184:185], off
	s_mov_b32 m0, s21
	v_mfma_f32_16x16x32_bf16 v[108:111], v[122:125], v[162:165], v[110:113]
	global_load_lds_dwordx4 v[186:187], off
	s_mov_b32 m0, s20
	v_mfma_f32_16x16x32_bf16 v[138:141], v[12:15], v[166:169], v[138:141]
	global_load_lds_dwordx4 v[188:189], off
	v_lshl_add_u64 v[178:179], v[2:3], 0, s[58:59]
	v_mfma_f32_16x16x32_bf16 v[142:145], v[34:37], v[166:169], v[142:145]
	s_mov_b32 m0, s22
	v_lshl_add_u64 v[180:181], v[4:5], 0, s[58:59]
	v_lshl_add_u64 v[182:183], v[2:3], 0, s[42:43]
	v_mfma_f32_16x16x32_bf16 v[146:149], v[38:41], v[166:169], v[146:149]
	s_mov_b64 s[42:43], 0x30340
	v_lshl_add_u64 v[184:185], v[2:3], 0, s[42:43]
	v_lshl_add_u64 v[186:187], v[8:9], 0, s[58:59]
	v_mfma_f32_16x16x32_bf16 v[112:115], v[122:125], v[166:169], v[114:117]
	v_lshl_add_u64 v[188:189], v[6:7], 0, s[58:59]
	s_mov_b64 s[58:59], 0x380
	v_mfma_f32_16x16x32_bf16 v[150:153], v[12:15], v[170:173], v[150:153]
	v_mfma_f32_16x16x32_bf16 v[154:157], v[34:37], v[170:173], v[154:157]
	v_mfma_f32_16x16x32_bf16 v[158:161], v[38:41], v[170:173], v[158:161]
	v_mfma_f32_16x16x32_bf16 v[116:119], v[122:125], v[170:173], v[118:121]
	v_mfma_f32_16x16x32_bf16 v[12:15], v[12:15], v[174:177], v[18:21]
	v_mfma_f32_16x16x32_bf16 v[16:19], v[34:37], v[174:177], v[22:25]
	v_mfma_f32_16x16x32_bf16 v[20:23], v[38:41], v[174:177], v[26:29]
	v_mfma_f32_16x16x32_bf16 v[24:27], v[122:125], v[174:177], v[30:33]
	s_nop 2
	ds_read_b128 v[28:31], v10 offset:40960
	ds_read_b128 v[32:35], v10 offset:41984
	ds_read_b128 v[36:39], v10 offset:43008
	ds_read_b128 v[120:123], v10 offset:44032
	ds_read_b128 v[162:165], v0 offset:24576
	ds_read_b128 v[166:169], v0 offset:25600
	ds_read_b128 v[170:173], v0 offset:26624
	ds_read_b128 v[174:177], v0 offset:27648
	s_waitcnt lgkmcnt(0)
	v_mfma_f32_16x16x32_bf16 v[58:61], v[28:31], v[162:165], v[60:63]
	v_mfma_f32_16x16x32_bf16 v[62:65], v[32:35], v[162:165], v[64:67]
	v_mfma_f32_16x16x32_bf16 v[66:69], v[36:39], v[162:165], v[68:71]
	v_mfma_f32_16x16x32_bf16 v[40:43], v[120:123], v[162:165], v[42:45]
	v_mfma_f32_16x16x32_bf16 v[70:73], v[28:31], v[166:169], v[72:75]
	v_mfma_f32_16x16x32_bf16 v[74:77], v[32:35], v[166:169], v[76:79]
	v_mfma_f32_16x16x32_bf16 v[78:81], v[36:39], v[166:169], v[80:83]
	v_mfma_f32_16x16x32_bf16 v[44:47], v[120:123], v[166:169], v[46:49]
	v_mfma_f32_16x16x32_bf16 v[82:85], v[28:31], v[170:173], v[84:87]
	v_mfma_f32_16x16x32_bf16 v[86:89], v[32:35], v[170:173], v[88:91]
	v_mfma_f32_16x16x32_bf16 v[90:93], v[36:39], v[170:173], v[92:95]
	v_mfma_f32_16x16x32_bf16 v[48:51], v[120:123], v[170:173], v[50:53]
	v_mfma_f32_16x16x32_bf16 v[94:97], v[28:31], v[174:177], v[96:99]
	v_mfma_f32_16x16x32_bf16 v[98:101], v[32:35], v[174:177], v[100:103]
	v_mfma_f32_16x16x32_bf16 v[102:105], v[36:39], v[174:177], v[104:107]
	v_mfma_f32_16x16x32_bf16 v[52:55], v[120:123], v[174:177], v[54:57]
	ds_read_b128 v[162:165], v0 offset:28672
	ds_read_b128 v[166:169], v0 offset:29696
	ds_read_b128 v[170:173], v0 offset:30720
	ds_read_b128 v[174:177], v0 offset:31744
	s_waitcnt vmcnt(6) lgkmcnt(0)
	s_barrier
	global_load_lds_dwordx4 v[178:179], off
	s_mov_b32 m0, s23
	s_waitcnt lgkmcnt(0)
	v_mfma_f32_16x16x32_bf16 v[124:127], v[28:31], v[162:165], v[126:129]
	global_load_lds_dwordx4 v[180:181], off
	s_mov_b32 m0, s24
	v_mfma_f32_16x16x32_bf16 v[128:131], v[32:35], v[162:165], v[130:133]
	global_load_lds_dwordx4 v[182:183], off
	s_mov_b32 m0, s25
	v_mfma_f32_16x16x32_bf16 v[132:135], v[36:39], v[162:165], v[134:137]
	global_load_lds_dwordx4 v[184:185], off
	s_mov_b32 m0, s26
	v_mfma_f32_16x16x32_bf16 v[106:109], v[120:123], v[162:165], v[108:111]
	global_load_lds_dwordx4 v[186:187], off
	s_mov_b32 m0, s27
	v_mfma_f32_16x16x32_bf16 v[136:139], v[28:31], v[166:169], v[138:141]
	global_load_lds_dwordx4 v[188:189], off
	s_mov_b32 m0, s36
	v_mfma_f32_16x16x32_bf16 v[140:143], v[32:35], v[166:169], v[142:145]
	v_lshl_add_u64 v[178:179], v[4:5], 0, s[58:59]
	s_mov_b64 s[22:23], 0x20380
	v_lshl_add_u64 v[180:181], v[2:3], 0, s[22:23]
	v_mfma_f32_16x16x32_bf16 v[144:147], v[36:39], v[166:169], v[146:149]
	s_mov_b64 s[22:23], 0x30380
	v_lshl_add_u64 v[182:183], v[2:3], 0, s[22:23]
	v_lshl_add_u64 v[184:185], v[8:9], 0, s[58:59]
	v_mfma_f32_16x16x32_bf16 v[110:113], v[120:123], v[166:169], v[112:115]
	v_lshl_add_u64 v[186:187], v[6:7], 0, s[58:59]
	s_mov_b64 s[22:23], 0x203c0
	s_mov_b64 s[26:27], 0x3c0
	v_mfma_f32_16x16x32_bf16 v[148:151], v[28:31], v[170:173], v[150:153]
	s_mov_b64 s[24:25], 0x3000
	v_mfma_f32_16x16x32_bf16 v[152:155], v[32:35], v[170:173], v[154:157]
	v_mfma_f32_16x16x32_bf16 v[156:159], v[36:39], v[170:173], v[158:161]
	v_mfma_f32_16x16x32_bf16 v[114:117], v[120:123], v[170:173], v[116:119]
	v_mfma_f32_16x16x32_bf16 v[12:15], v[28:31], v[174:177], v[12:15]
	v_mfma_f32_16x16x32_bf16 v[16:19], v[32:35], v[174:177], v[16:19]
	v_mfma_f32_16x16x32_bf16 v[20:23], v[36:39], v[174:177], v[20:23]
	v_mfma_f32_16x16x32_bf16 v[24:27], v[120:123], v[174:177], v[24:27]
	ds_read_b128 v[28:31], v11 offset:16384
	ds_read_b128 v[32:35], v11 offset:17408
	ds_read_b128 v[36:39], v11 offset:18432
	ds_read_b128 v[118:121], v11 offset:19456
	ds_read_b128 v[160:163], v0 offset:49152
	ds_read_b128 v[164:167], v0 offset:50176
	ds_read_b128 v[168:171], v0 offset:51200
	ds_read_b128 v[172:175], v0 offset:52224
	v_lshl_add_u64 v[176:177], v[2:3], 0, s[58:59]
	s_mov_b32 s59, s44
	s_waitcnt lgkmcnt(0)
	v_mfma_f32_16x16x32_bf16 v[56:59], v[28:31], v[160:163], v[58:61]
	v_mfma_f32_16x16x32_bf16 v[60:63], v[32:35], v[160:163], v[62:65]
	v_mfma_f32_16x16x32_bf16 v[64:67], v[36:39], v[160:163], v[66:69]
	v_mfma_f32_16x16x32_bf16 v[40:43], v[118:121], v[160:163], v[40:43]
	v_mfma_f32_16x16x32_bf16 v[68:71], v[28:31], v[164:167], v[70:73]
	v_mfma_f32_16x16x32_bf16 v[72:75], v[32:35], v[164:167], v[74:77]
	v_mfma_f32_16x16x32_bf16 v[76:79], v[36:39], v[164:167], v[78:81]
	v_mfma_f32_16x16x32_bf16 v[44:47], v[118:121], v[164:167], v[44:47]
	v_mfma_f32_16x16x32_bf16 v[80:83], v[28:31], v[168:171], v[82:85]
	v_mfma_f32_16x16x32_bf16 v[84:87], v[32:35], v[168:171], v[86:89]
	v_mfma_f32_16x16x32_bf16 v[88:91], v[36:39], v[168:171], v[90:93]
	v_mfma_f32_16x16x32_bf16 v[48:51], v[118:121], v[168:171], v[48:51]
	v_mfma_f32_16x16x32_bf16 v[92:95], v[28:31], v[172:175], v[94:97]
	v_mfma_f32_16x16x32_bf16 v[96:99], v[32:35], v[172:175], v[98:101]
	v_mfma_f32_16x16x32_bf16 v[100:103], v[36:39], v[172:175], v[102:105]
	v_mfma_f32_16x16x32_bf16 v[52:55], v[118:121], v[172:175], v[52:55]
	ds_read_b128 v[160:163], v0 offset:53248
	ds_read_b128 v[164:167], v0 offset:54272
	ds_read_b128 v[168:171], v0 offset:55296
	ds_read_b128 v[172:175], v0 offset:56320
	s_waitcnt vmcnt(6) lgkmcnt(0)
	s_barrier
	global_load_lds_dwordx4 v[176:177], off
	s_mov_b32 m0, s37
	s_waitcnt lgkmcnt(0)
	v_mfma_f32_16x16x32_bf16 v[122:125], v[28:31], v[160:163], v[124:127]
	global_load_lds_dwordx4 v[178:179], off
	s_mov_b32 m0, s38
	v_mfma_f32_16x16x32_bf16 v[126:129], v[32:35], v[160:163], v[128:131]
	global_load_lds_dwordx4 v[180:181], off
	s_mov_b32 m0, s39
	v_mfma_f32_16x16x32_bf16 v[130:133], v[36:39], v[160:163], v[132:135]
	global_load_lds_dwordx4 v[182:183], off
	s_mov_b32 m0, s40
	v_mfma_f32_16x16x32_bf16 v[104:107], v[118:121], v[160:163], v[106:109]
	global_load_lds_dwordx4 v[184:185], off
	s_mov_b32 m0, s41
	v_mfma_f32_16x16x32_bf16 v[134:137], v[28:31], v[164:167], v[136:139]
	global_load_lds_dwordx4 v[186:187], off
	v_lshl_add_u64 v[176:177], v[6:7], 0, s[26:27]
	v_mfma_f32_16x16x32_bf16 v[138:141], v[32:35], v[164:167], v[140:143]
	s_mov_b32 m0, s8
	v_mfma_f32_16x16x32_bf16 v[142:145], v[36:39], v[164:167], v[144:147]
	v_mfma_f32_16x16x32_bf16 v[108:111], v[118:121], v[164:167], v[110:113]
	v_lshl_add_u64 v[166:167], v[2:3], 0, s[26:27]
	v_mfma_f32_16x16x32_bf16 v[146:149], v[28:31], v[168:171], v[148:151]
	v_mfma_f32_16x16x32_bf16 v[150:153], v[32:35], v[168:171], v[152:155]
	v_mfma_f32_16x16x32_bf16 v[154:157], v[36:39], v[168:171], v[156:159]
	v_mfma_f32_16x16x32_bf16 v[112:115], v[118:121], v[168:171], v[114:117]
	v_lshl_add_u64 v[170:171], v[2:3], 0, s[22:23]
	s_mov_b64 s[22:23], 0x303c0
	v_lshl_add_u64 v[168:169], v[4:5], 0, s[26:27]
	v_mfma_f32_16x16x32_bf16 v[12:15], v[28:31], v[172:175], v[12:15]
	v_mfma_f32_16x16x32_bf16 v[16:19], v[32:35], v[172:175], v[16:19]
	v_mfma_f32_16x16x32_bf16 v[20:23], v[36:39], v[172:175], v[20:23]
	v_mfma_f32_16x16x32_bf16 v[24:27], v[118:121], v[172:175], v[24:27]
	v_lshl_add_u64 v[172:173], v[2:3], 0, s[22:23]
	v_lshl_add_u64 v[174:175], v[8:9], 0, s[26:27]
	ds_read_b128 v[2:5], v10 offset:16384
	ds_read_b128 v[6:9], v10 offset:17408
	ds_read_b128 v[28:31], v10 offset:18432
	ds_read_b128 v[32:35], v10 offset:19456
	ds_read_b128 v[36:39], v0
	ds_read_b128 v[116:119], v0 offset:1024
	ds_read_b128 v[158:161], v0 offset:2048
	ds_read_b128 v[162:165], v0 offset:3072
	s_waitcnt lgkmcnt(0)
	v_mfma_f32_16x16x32_bf16 v[56:59], v[2:5], v[36:39], v[56:59]
	v_mfma_f32_16x16x32_bf16 v[60:63], v[6:9], v[36:39], v[60:63]
	v_mfma_f32_16x16x32_bf16 v[64:67], v[28:31], v[36:39], v[64:67]
	v_mfma_f32_16x16x32_bf16 v[36:39], v[32:35], v[36:39], v[40:43]
	v_mfma_f32_16x16x32_bf16 v[40:43], v[2:5], v[116:119], v[68:71]
	v_mfma_f32_16x16x32_bf16 v[68:71], v[6:9], v[116:119], v[72:75]
	v_mfma_f32_16x16x32_bf16 v[72:75], v[28:31], v[116:119], v[76:79]
	v_mfma_f32_16x16x32_bf16 v[44:47], v[32:35], v[116:119], v[44:47]
	v_mfma_f32_16x16x32_bf16 v[76:79], v[2:5], v[158:161], v[80:83]
	v_mfma_f32_16x16x32_bf16 v[80:83], v[6:9], v[158:161], v[84:87]
	v_mfma_f32_16x16x32_bf16 v[84:87], v[28:31], v[158:161], v[88:91]
	v_mfma_f32_16x16x32_bf16 v[48:51], v[32:35], v[158:161], v[48:51]
	v_mfma_f32_16x16x32_bf16 v[88:91], v[2:5], v[162:165], v[92:95]
	v_mfma_f32_16x16x32_bf16 v[92:95], v[6:9], v[162:165], v[96:99]
	v_mfma_f32_16x16x32_bf16 v[96:99], v[28:31], v[162:165], v[100:103]
	v_mfma_f32_16x16x32_bf16 v[52:55], v[32:35], v[162:165], v[52:55]
	s_nop 1
	ds_read_b128 v[100:103], v0 offset:4096
	ds_read_b128 v[116:119], v0 offset:5120
	ds_read_b128 v[158:161], v0 offset:6144
	ds_read_b128 v[162:165], v0 offset:7168
	s_waitcnt vmcnt(6) lgkmcnt(0)
	s_barrier
	global_load_lds_dwordx4 v[166:167], off
	s_mov_b32 m0, s9
	s_waitcnt lgkmcnt(0)
	v_mfma_f32_16x16x32_bf16 v[120:123], v[2:5], v[100:103], v[122:125]
	global_load_lds_dwordx4 v[168:169], off
	s_mov_b32 m0, s18
	v_mfma_f32_16x16x32_bf16 v[124:127], v[6:9], v[100:103], v[126:129]
	global_load_lds_dwordx4 v[170:171], off
	s_mov_b32 m0, s19
	v_mfma_f32_16x16x32_bf16 v[128:131], v[28:31], v[100:103], v[130:133]
	global_load_lds_dwordx4 v[172:173], off
	s_mov_b32 m0, s21
	v_mfma_f32_16x16x32_bf16 v[100:103], v[32:35], v[100:103], v[104:107]
	global_load_lds_dwordx4 v[174:175], off
	s_mov_b32 m0, s20
	v_mfma_f32_16x16x32_bf16 v[104:107], v[2:5], v[116:119], v[134:137]
	global_load_lds_dwordx4 v[176:177], off
	v_mfma_f32_16x16x32_bf16 v[132:135], v[6:9], v[116:119], v[138:141]
	v_mfma_f32_16x16x32_bf16 v[136:139], v[28:31], v[116:119], v[142:145]
	v_mfma_f32_16x16x32_bf16 v[108:111], v[32:35], v[116:119], v[108:111]
	v_mfma_f32_16x16x32_bf16 v[116:119], v[2:5], v[158:161], v[146:149]
	v_mfma_f32_16x16x32_bf16 v[140:143], v[6:9], v[158:161], v[150:153]
	v_mfma_f32_16x16x32_bf16 v[144:147], v[28:31], v[158:161], v[154:157]
	v_mfma_f32_16x16x32_bf16 v[112:115], v[32:35], v[158:161], v[112:115]
	v_mfma_f32_16x16x32_bf16 v[2:5], v[2:5], v[162:165], v[12:15]
	v_mfma_f32_16x16x32_bf16 v[6:9], v[6:9], v[162:165], v[16:19]
	v_mfma_f32_16x16x32_bf16 v[12:15], v[28:31], v[162:165], v[20:23]
	v_mfma_f32_16x16x32_bf16 v[16:19], v[32:35], v[162:165], v[24:27]
	s_nop 1
	ds_read_b128 v[20:23], v10 offset:40960
	ds_read_b128 v[24:27], v10 offset:41984
	ds_read_b128 v[28:31], v10 offset:43008
	ds_read_b128 v[32:35], v10 offset:44032
	ds_read_b128 v[148:151], v0 offset:24576
	ds_read_b128 v[152:155], v0 offset:25600
	ds_read_b128 v[156:159], v0 offset:26624
	ds_read_b128 v[160:163], v0 offset:27648
	s_waitcnt lgkmcnt(0)
	v_mfma_f32_16x16x32_bf16 v[56:59], v[20:23], v[148:151], v[56:59]
	v_mfma_f32_16x16x32_bf16 v[60:63], v[24:27], v[148:151], v[60:63]
	v_mfma_f32_16x16x32_bf16 v[64:67], v[28:31], v[148:151], v[64:67]
	v_mfma_f32_16x16x32_bf16 v[36:39], v[32:35], v[148:151], v[36:39]
	v_mfma_f32_16x16x32_bf16 v[40:43], v[20:23], v[152:155], v[40:43]
	v_mfma_f32_16x16x32_bf16 v[68:71], v[24:27], v[152:155], v[68:71]
	v_mfma_f32_16x16x32_bf16 v[72:75], v[28:31], v[152:155], v[72:75]
	v_mfma_f32_16x16x32_bf16 v[44:47], v[32:35], v[152:155], v[44:47]
	v_mfma_f32_16x16x32_bf16 v[76:79], v[20:23], v[156:159], v[76:79]
	v_mfma_f32_16x16x32_bf16 v[80:83], v[24:27], v[156:159], v[80:83]
	v_mfma_f32_16x16x32_bf16 v[84:87], v[28:31], v[156:159], v[84:87]
	v_mfma_f32_16x16x32_bf16 v[48:51], v[32:35], v[156:159], v[48:51]
	v_mfma_f32_16x16x32_bf16 v[88:91], v[20:23], v[160:163], v[88:91]
	v_mfma_f32_16x16x32_bf16 v[92:95], v[24:27], v[160:163], v[92:95]
	v_mfma_f32_16x16x32_bf16 v[96:99], v[28:31], v[160:163], v[96:99]
	v_mfma_f32_16x16x32_bf16 v[52:55], v[32:35], v[160:163], v[52:55]
	ds_read_b128 v[148:151], v0 offset:28672
	ds_read_b128 v[152:155], v0 offset:29696
	ds_read_b128 v[156:159], v0 offset:30720
	ds_read_b128 v[160:163], v0 offset:31744
	s_waitcnt vmcnt(6) lgkmcnt(0)
	s_barrier
	s_waitcnt lgkmcnt(0)
	v_mfma_f32_16x16x32_bf16 v[120:123], v[20:23], v[148:151], v[120:123]
	v_mfma_f32_16x16x32_bf16 v[124:127], v[24:27], v[148:151], v[124:127]
	v_mfma_f32_16x16x32_bf16 v[128:131], v[28:31], v[148:151], v[128:131]
	v_mfma_f32_16x16x32_bf16 v[100:103], v[32:35], v[148:151], v[100:103]
	v_mfma_f32_16x16x32_bf16 v[104:107], v[20:23], v[152:155], v[104:107]
	v_mfma_f32_16x16x32_bf16 v[132:135], v[24:27], v[152:155], v[132:135]
	v_mfma_f32_16x16x32_bf16 v[136:139], v[28:31], v[152:155], v[136:139]
	v_mfma_f32_16x16x32_bf16 v[108:111], v[32:35], v[152:155], v[108:111]
	v_mfma_f32_16x16x32_bf16 v[116:119], v[20:23], v[156:159], v[116:119]
	v_mfma_f32_16x16x32_bf16 v[140:143], v[24:27], v[156:159], v[140:143]
	v_mfma_f32_16x16x32_bf16 v[144:147], v[28:31], v[156:159], v[144:147]
	v_mfma_f32_16x16x32_bf16 v[112:115], v[32:35], v[156:159], v[112:115]
	v_mfma_f32_16x16x32_bf16 v[2:5], v[20:23], v[160:163], v[2:5]
	v_mfma_f32_16x16x32_bf16 v[6:9], v[24:27], v[160:163], v[6:9]
	v_mfma_f32_16x16x32_bf16 v[12:15], v[28:31], v[160:163], v[12:15]
	v_mfma_f32_16x16x32_bf16 v[16:19], v[32:35], v[160:163], v[16:19]
	ds_read_b128 v[20:23], v11 offset:16384
	ds_read_b128 v[24:27], v11 offset:17408
	ds_read_b128 v[28:31], v11 offset:18432
	ds_read_b128 v[32:35], v11 offset:19456
	ds_read_b128 v[148:151], v0 offset:49152
	ds_read_b128 v[152:155], v0 offset:50176
	ds_read_b128 v[156:159], v0 offset:51200
	ds_read_b128 v[160:163], v0 offset:52224
	s_waitcnt lgkmcnt(0)
	v_mfma_f32_16x16x32_bf16 v[56:59], v[20:23], v[148:151], v[56:59]
	v_mfma_f32_16x16x32_bf16 v[60:63], v[24:27], v[148:151], v[60:63]
	v_mfma_f32_16x16x32_bf16 v[64:67], v[28:31], v[148:151], v[64:67]
	v_mfma_f32_16x16x32_bf16 v[36:39], v[32:35], v[148:151], v[36:39]
	v_mfma_f32_16x16x32_bf16 v[40:43], v[20:23], v[152:155], v[40:43]
	v_mfma_f32_16x16x32_bf16 v[68:71], v[24:27], v[152:155], v[68:71]
	v_mfma_f32_16x16x32_bf16 v[72:75], v[28:31], v[152:155], v[72:75]
	v_mfma_f32_16x16x32_bf16 v[44:47], v[32:35], v[152:155], v[44:47]
	v_mfma_f32_16x16x32_bf16 v[76:79], v[20:23], v[156:159], v[76:79]
	v_mfma_f32_16x16x32_bf16 v[80:83], v[24:27], v[156:159], v[80:83]
	v_mfma_f32_16x16x32_bf16 v[84:87], v[28:31], v[156:159], v[84:87]
	v_mfma_f32_16x16x32_bf16 v[48:51], v[32:35], v[156:159], v[48:51]
	v_mfma_f32_16x16x32_bf16 v[88:91], v[20:23], v[160:163], v[88:91]
	v_mfma_f32_16x16x32_bf16 v[92:95], v[24:27], v[160:163], v[92:95]
	v_mfma_f32_16x16x32_bf16 v[96:99], v[28:31], v[160:163], v[96:99]
	v_mfma_f32_16x16x32_bf16 v[52:55], v[32:35], v[160:163], v[52:55]
	ds_read_b128 v[148:151], v0 offset:53248
	ds_read_b128 v[152:155], v0 offset:54272
	ds_read_b128 v[156:159], v0 offset:55296
	ds_read_b128 v[160:163], v0 offset:56320
	s_waitcnt vmcnt(0) lgkmcnt(0)
	s_barrier
	s_waitcnt lgkmcnt(0)
	v_mfma_f32_16x16x32_bf16 v[120:123], v[20:23], v[148:151], v[120:123]
	v_mfma_f32_16x16x32_bf16 v[124:127], v[24:27], v[148:151], v[124:127]
	v_mfma_f32_16x16x32_bf16 v[128:131], v[28:31], v[148:151], v[128:131]
	v_mfma_f32_16x16x32_bf16 v[100:103], v[32:35], v[148:151], v[100:103]
	v_mfma_f32_16x16x32_bf16 v[104:107], v[20:23], v[152:155], v[104:107]
	v_mfma_f32_16x16x32_bf16 v[132:135], v[24:27], v[152:155], v[132:135]
	v_mfma_f32_16x16x32_bf16 v[136:139], v[28:31], v[152:155], v[136:139]
	v_mfma_f32_16x16x32_bf16 v[108:111], v[32:35], v[152:155], v[108:111]
	v_mfma_f32_16x16x32_bf16 v[116:119], v[20:23], v[156:159], v[116:119]
	v_mfma_f32_16x16x32_bf16 v[140:143], v[24:27], v[156:159], v[140:143]
	v_mfma_f32_16x16x32_bf16 v[144:147], v[28:31], v[156:159], v[144:147]
	v_mfma_f32_16x16x32_bf16 v[112:115], v[32:35], v[156:159], v[112:115]
	v_mfma_f32_16x16x32_bf16 v[2:5], v[20:23], v[160:163], v[2:5]
	v_mfma_f32_16x16x32_bf16 v[6:9], v[24:27], v[160:163], v[6:9]
	v_mfma_f32_16x16x32_bf16 v[12:15], v[28:31], v[160:163], v[12:15]
	v_mfma_f32_16x16x32_bf16 v[16:19], v[32:35], v[160:163], v[16:19]
	ds_read_b128 v[20:23], v10 offset:16384
	ds_read_b128 v[24:27], v10 offset:17408
	ds_read_b128 v[28:31], v10 offset:18432
	ds_read_b128 v[32:35], v10 offset:19456
	ds_read_b128 v[148:151], v0
	ds_read_b128 v[152:155], v0 offset:1024
	ds_read_b128 v[156:159], v0 offset:2048
	ds_read_b128 v[160:163], v0 offset:3072
	s_waitcnt lgkmcnt(0)
	v_mfma_f32_16x16x32_bf16 v[56:59], v[20:23], v[148:151], v[56:59]
	v_mfma_f32_16x16x32_bf16 v[60:63], v[24:27], v[148:151], v[60:63]
	v_mfma_f32_16x16x32_bf16 v[64:67], v[28:31], v[148:151], v[64:67]
	v_mfma_f32_16x16x32_bf16 v[36:39], v[32:35], v[148:151], v[36:39]
	v_mfma_f32_16x16x32_bf16 v[40:43], v[20:23], v[152:155], v[40:43]
	v_mfma_f32_16x16x32_bf16 v[68:71], v[24:27], v[152:155], v[68:71]
	v_mfma_f32_16x16x32_bf16 v[72:75], v[28:31], v[152:155], v[72:75]
	v_mfma_f32_16x16x32_bf16 v[44:47], v[32:35], v[152:155], v[44:47]
	v_mfma_f32_16x16x32_bf16 v[76:79], v[20:23], v[156:159], v[76:79]
	v_mfma_f32_16x16x32_bf16 v[80:83], v[24:27], v[156:159], v[80:83]
	v_mfma_f32_16x16x32_bf16 v[84:87], v[28:31], v[156:159], v[84:87]
	v_mfma_f32_16x16x32_bf16 v[48:51], v[32:35], v[156:159], v[48:51]
	v_mfma_f32_16x16x32_bf16 v[88:91], v[20:23], v[160:163], v[88:91]
	v_mfma_f32_16x16x32_bf16 v[92:95], v[24:27], v[160:163], v[92:95]
	v_mfma_f32_16x16x32_bf16 v[96:99], v[28:31], v[160:163], v[96:99]
	v_mfma_f32_16x16x32_bf16 v[52:55], v[32:35], v[160:163], v[52:55]
	ds_read_b128 v[148:151], v0 offset:4096
	ds_read_b128 v[152:155], v0 offset:5120
	ds_read_b128 v[156:159], v0 offset:6144
	ds_read_b128 v[160:163], v0 offset:7168
	s_waitcnt vmcnt(0) lgkmcnt(0)
	s_barrier
	v_mfma_f32_16x16x32_bf16 v[120:123], v[20:23], v[148:151], v[120:123]
	v_mfma_f32_16x16x32_bf16 v[104:107], v[20:23], v[152:155], v[104:107]
	v_mfma_f32_16x16x32_bf16 v[116:119], v[20:23], v[156:159], v[116:119]
	v_mfma_f32_16x16x32_bf16 v[20:23], v[20:23], v[160:163], v[2:5]
	s_nop 2
	v_mov_b32_e32 v4, v196
	v_mfma_f32_16x16x32_bf16 v[124:127], v[24:27], v[148:151], v[124:127]
	v_and_b32_e32 v0, 64, v4
	v_lshrrev_b32_e32 v3, 1, v4
	v_lshlrev_b32_e32 v0, 1, v0
	v_and_b32_e32 v3, 24, v3
	v_and_b32_e32 v2, 0xfffff8f, v4
	v_add3_u32 v0, 0, v0, v3
	v_mfma_f32_16x16x32_bf16 v[132:135], v[24:27], v[152:155], v[132:135]
	v_mad_u64_u32 v[2:3], s[8:9], v2, s30, v[0:1]
	v_add_u32_e32 v3, 0x1000, v2
	v_mfma_f32_16x16x32_bf16 v[140:143], v[24:27], v[156:159], v[140:143]
	v_add_u32_e32 v5, 0x6000, v2
	v_mfma_f32_16x16x32_bf16 v[6:9], v[24:27], v[160:163], v[6:9]
	v_cvt_pk_bf16_f32 v24, v60, v61
	v_cvt_pk_bf16_f32 v25, v62, v63
	v_mfma_f32_16x16x32_bf16 v[10:13], v[28:31], v[160:163], v[12:15]
	v_mfma_f32_16x16x32_bf16 v[14:17], v[32:35], v[160:163], v[16:19]
	s_nop 3
	v_cvt_pk_bf16_f32 v6, v6, v7
	v_cvt_pk_bf16_f32 v7, v8, v9
	v_cvt_pk_bf16_f32 v18, v56, v57
	v_cvt_pk_bf16_f32 v19, v58, v59
	ds_write2_b64 v2, v[18:19], v[24:25] offset1:4
	v_cvt_pk_bf16_f32 v18, v64, v65
	v_cvt_pk_bf16_f32 v19, v66, v67
	v_cvt_pk_bf16_f32 v24, v36, v37
	v_cvt_pk_bf16_f32 v25, v38, v39
	ds_write2_b64 v2, v[18:19], v[24:25] offset0:8 offset1:12
	v_cvt_pk_bf16_f32 v18, v40, v41
	v_cvt_pk_bf16_f32 v19, v42, v43
	v_cvt_pk_bf16_f32 v24, v68, v69
	v_cvt_pk_bf16_f32 v25, v70, v71
	ds_write2_b64 v3, v[18:19], v[24:25] offset0:32 offset1:36
	v_cvt_pk_bf16_f32 v18, v72, v73
	v_cvt_pk_bf16_f32 v19, v74, v75
	v_cvt_pk_bf16_f32 v24, v44, v45
	v_cvt_pk_bf16_f32 v25, v46, v47
	ds_write2_b64 v3, v[18:19], v[24:25] offset0:40 offset1:44
	v_cvt_pk_bf16_f32 v18, v76, v77
	v_cvt_pk_bf16_f32 v19, v78, v79
	v_cvt_pk_bf16_f32 v24, v80, v81
	v_cvt_pk_bf16_f32 v25, v82, v83
	v_add_u32_e32 v3, 0x2000, v2
	v_mfma_f32_16x16x32_bf16 v[128:131], v[28:31], v[148:151], v[128:131]
	ds_write2_b64 v3, v[18:19], v[24:25] offset0:64 offset1:68
	v_cvt_pk_bf16_f32 v18, v84, v85
	v_cvt_pk_bf16_f32 v19, v86, v87
	v_mfma_f32_16x16x32_bf16 v[100:103], v[32:35], v[148:151], v[100:103]
	v_cvt_pk_bf16_f32 v24, v48, v49
	v_cvt_pk_bf16_f32 v25, v50, v51
	ds_write2_b64 v3, v[18:19], v[24:25] offset0:72 offset1:76
	v_cvt_pk_bf16_f32 v18, v88, v89
	v_cvt_pk_bf16_f32 v19, v90, v91
	v_cvt_pk_bf16_f32 v24, v92, v93
	v_cvt_pk_bf16_f32 v25, v94, v95
	v_add_u32_e32 v3, 0x3000, v2
	v_mfma_f32_16x16x32_bf16 v[136:139], v[28:31], v[152:155], v[136:139]
	ds_write2_b64 v3, v[18:19], v[24:25] offset0:96 offset1:100
	v_cvt_pk_bf16_f32 v18, v96, v97
	v_cvt_pk_bf16_f32 v19, v98, v99
	v_mfma_f32_16x16x32_bf16 v[108:111], v[32:35], v[152:155], v[108:111]
	v_cvt_pk_bf16_f32 v24, v52, v53
	v_cvt_pk_bf16_f32 v25, v54, v55
	ds_write2_b64 v3, v[18:19], v[24:25] offset0:104 offset1:108
	v_cvt_pk_bf16_f32 v18, v120, v121
	v_cvt_pk_bf16_f32 v19, v122, v123
	v_cvt_pk_bf16_f32 v24, v124, v125
	v_cvt_pk_bf16_f32 v25, v126, v127
	v_add_u32_e32 v3, 0x4000, v2
	v_mfma_f32_16x16x32_bf16 v[144:147], v[28:31], v[156:159], v[144:147]
	ds_write2_b64 v3, v[18:19], v[24:25] offset0:128 offset1:132
	v_cvt_pk_bf16_f32 v18, v128, v129
	v_cvt_pk_bf16_f32 v19, v130, v131
	v_mfma_f32_16x16x32_bf16 v[112:115], v[32:35], v[156:159], v[112:115]
	v_cvt_pk_bf16_f32 v24, v100, v101
	v_cvt_pk_bf16_f32 v25, v102, v103
	ds_write2_b64 v3, v[18:19], v[24:25] offset0:136 offset1:140
	v_cvt_pk_bf16_f32 v18, v104, v105
	v_cvt_pk_bf16_f32 v19, v106, v107
	v_cvt_pk_bf16_f32 v24, v132, v133
	v_cvt_pk_bf16_f32 v25, v134, v135
	v_add_u32_e32 v3, 0x5000, v2
	ds_write2_b64 v3, v[18:19], v[24:25] offset0:160 offset1:164
	v_cvt_pk_bf16_f32 v18, v136, v137
	v_cvt_pk_bf16_f32 v19, v138, v139
	v_cvt_pk_bf16_f32 v24, v108, v109
	v_cvt_pk_bf16_f32 v25, v110, v111
	ds_write2_b64 v3, v[18:19], v[24:25] offset0:168 offset1:172
	v_cvt_pk_bf16_f32 v18, v116, v117
	v_cvt_pk_bf16_f32 v19, v118, v119
	v_cvt_pk_bf16_f32 v24, v140, v141
	v_cvt_pk_bf16_f32 v25, v142, v143
	ds_write2_b64 v5, v[18:19], v[24:25] offset0:192 offset1:196
	v_cvt_pk_bf16_f32 v2, v144, v145
	v_cvt_pk_bf16_f32 v3, v146, v147
	v_cvt_pk_bf16_f32 v18, v112, v113
	v_cvt_pk_bf16_f32 v19, v114, v115
	ds_write2_b64 v5, v[2:3], v[18:19] offset0:200 offset1:204
	v_or_b32_e32 v2, 0x70, v4
	v_mad_u64_u32 v[2:3], s[8:9], v2, s30, v[0:1]
	v_cvt_pk_bf16_f32 v18, v20, v21
	v_cvt_pk_bf16_f32 v19, v22, v23
	ds_write2_b64 v2, v[18:19], v[6:7] offset1:4
	v_cvt_pk_bf16_f32 v6, v10, v11
	v_cvt_pk_bf16_f32 v7, v12, v13
	v_cvt_pk_bf16_f32 v8, v14, v15
	v_cvt_pk_bf16_f32 v9, v16, v17
	v_lshlrev_b32_e32 v0, 4, v4
	ds_write2_b64 v2, v[6:7], v[8:9] offset0:8 offset1:12
	v_and_b32_e32 v0, 0xf0, v0
	v_ashrrev_i32_e32 v6, 4, v4
	v_lshl_add_u64 v[2:3], s[0:1], 0, v[0:1]
	v_add_u32_e32 v0, 0, v0
	v_ashrrev_i32_e32 v7, 31, v6
	v_mad_u64_u32 v[8:9], s[0:1], v6, s30, v[0:1]
	v_lshlrev_b64 v[6:7], 11, v[6:7]
	s_waitcnt lgkmcnt(0)
	s_barrier
	v_lshl_add_u64 v[10:11], v[2:3], 0, v[6:7]
	ds_read_b128 v[6:9], v8
	v_add_u32_e32 v5, 0x100, v4
	s_waitcnt lgkmcnt(0)
	global_store_dwordx4 v[10:11], v[6:9], off
	s_nop 1
	v_ashrrev_i32_e32 v6, 4, v5
	v_ashrrev_i32_e32 v7, 31, v6
	v_mad_u64_u32 v[8:9], s[0:1], v6, s30, v[0:1]
	v_lshlrev_b64 v[6:7], 11, v[6:7]
	v_lshl_add_u64 v[10:11], v[2:3], 0, v[6:7]
	ds_read_b128 v[6:9], v8
	v_add_u32_e32 v5, 0x200, v4
	s_waitcnt lgkmcnt(0)
	global_store_dwordx4 v[10:11], v[6:9], off
	s_nop 1
	v_ashrrev_i32_e32 v6, 4, v5
	v_ashrrev_i32_e32 v7, 31, v6
	v_mad_u64_u32 v[8:9], s[0:1], v6, s30, v[0:1]
	v_lshlrev_b64 v[6:7], 11, v[6:7]
	v_lshl_add_u64 v[10:11], v[2:3], 0, v[6:7]
	ds_read_b128 v[6:9], v8
	v_add_u32_e32 v5, 0x300, v4
	s_waitcnt lgkmcnt(0)
	global_store_dwordx4 v[10:11], v[6:9], off
	s_nop 1
	v_ashrrev_i32_e32 v6, 4, v5
	v_ashrrev_i32_e32 v7, 31, v6
	v_mad_u64_u32 v[8:9], s[0:1], v6, s30, v[0:1]
	v_lshlrev_b64 v[6:7], 11, v[6:7]
	v_lshl_add_u64 v[10:11], v[2:3], 0, v[6:7]
	ds_read_b128 v[6:9], v8
	v_add_u32_e32 v5, 0x400, v4
	s_waitcnt lgkmcnt(0)
	global_store_dwordx4 v[10:11], v[6:9], off
	s_nop 1
	v_ashrrev_i32_e32 v6, 4, v5
	v_ashrrev_i32_e32 v7, 31, v6
	v_mad_u64_u32 v[8:9], s[0:1], v6, s30, v[0:1]
	v_lshlrev_b64 v[6:7], 11, v[6:7]
	v_lshl_add_u64 v[10:11], v[2:3], 0, v[6:7]
	ds_read_b128 v[6:9], v8
	v_add_u32_e32 v5, 0x500, v4
	s_waitcnt lgkmcnt(0)
	global_store_dwordx4 v[10:11], v[6:9], off
	s_nop 1
	v_ashrrev_i32_e32 v6, 4, v5
	v_ashrrev_i32_e32 v7, 31, v6
	v_mad_u64_u32 v[8:9], s[0:1], v6, s30, v[0:1]
	v_lshlrev_b64 v[6:7], 11, v[6:7]
	v_lshl_add_u64 v[10:11], v[2:3], 0, v[6:7]
	ds_read_b128 v[6:9], v8
	v_add_u32_e32 v5, 0x600, v4
	s_waitcnt lgkmcnt(0)
	global_store_dwordx4 v[10:11], v[6:9], off
	s_nop 1
	v_ashrrev_i32_e32 v6, 4, v5
	v_ashrrev_i32_e32 v7, 31, v6
	v_mad_u64_u32 v[8:9], s[0:1], v6, s30, v[0:1]
	v_lshlrev_b64 v[6:7], 11, v[6:7]
	v_lshl_add_u64 v[10:11], v[2:3], 0, v[6:7]
	ds_read_b128 v[6:9], v8
	v_add_u32_e32 v5, 0x700, v4
	s_waitcnt lgkmcnt(0)
	global_store_dwordx4 v[10:11], v[6:9], off
	s_nop 1
	v_ashrrev_i32_e32 v6, 4, v5
	v_ashrrev_i32_e32 v7, 31, v6
	v_mad_u64_u32 v[8:9], s[0:1], v6, s30, v[0:1]
	v_lshlrev_b64 v[6:7], 11, v[6:7]
	v_lshl_add_u64 v[10:11], v[2:3], 0, v[6:7]
	ds_read_b128 v[6:9], v8
	v_add_u32_e32 v5, 0x800, v4
	s_waitcnt lgkmcnt(0)
	global_store_dwordx4 v[10:11], v[6:9], off
	s_nop 1
	v_ashrrev_i32_e32 v6, 4, v5
	v_ashrrev_i32_e32 v7, 31, v6
	v_mad_u64_u32 v[8:9], s[0:1], v6, s30, v[0:1]
	v_lshlrev_b64 v[6:7], 11, v[6:7]
	v_lshl_add_u64 v[10:11], v[2:3], 0, v[6:7]
	ds_read_b128 v[6:9], v8
	v_add_u32_e32 v5, 0x900, v4
	s_waitcnt lgkmcnt(0)
	global_store_dwordx4 v[10:11], v[6:9], off
	s_nop 1
	v_ashrrev_i32_e32 v6, 4, v5
	v_ashrrev_i32_e32 v7, 31, v6
	v_mad_u64_u32 v[8:9], s[0:1], v6, s30, v[0:1]
	v_lshlrev_b64 v[6:7], 11, v[6:7]
	v_lshl_add_u64 v[10:11], v[2:3], 0, v[6:7]
	ds_read_b128 v[6:9], v8
	v_add_u32_e32 v5, 0xa00, v4
	s_waitcnt lgkmcnt(0)
	global_store_dwordx4 v[10:11], v[6:9], off
	s_nop 1
	v_ashrrev_i32_e32 v6, 4, v5
	v_ashrrev_i32_e32 v7, 31, v6
	v_mad_u64_u32 v[8:9], s[0:1], v6, s30, v[0:1]
	v_lshlrev_b64 v[6:7], 11, v[6:7]
	v_lshl_add_u64 v[10:11], v[2:3], 0, v[6:7]
	ds_read_b128 v[6:9], v8
	v_add_u32_e32 v5, 0xb00, v4
	s_waitcnt lgkmcnt(0)
	global_store_dwordx4 v[10:11], v[6:9], off
	s_nop 1
	v_ashrrev_i32_e32 v6, 4, v5
	v_ashrrev_i32_e32 v7, 31, v6
	v_mad_u64_u32 v[8:9], s[0:1], v6, s30, v[0:1]
	v_lshlrev_b64 v[6:7], 11, v[6:7]
	v_lshl_add_u64 v[10:11], v[2:3], 0, v[6:7]
	ds_read_b128 v[6:9], v8
	v_add_u32_e32 v5, 0xc00, v4
	s_waitcnt lgkmcnt(0)
	global_store_dwordx4 v[10:11], v[6:9], off
	s_nop 1
	v_ashrrev_i32_e32 v6, 4, v5
	v_ashrrev_i32_e32 v7, 31, v6
	v_mad_u64_u32 v[8:9], s[0:1], v6, s30, v[0:1]
	v_lshlrev_b64 v[6:7], 11, v[6:7]
	v_lshl_add_u64 v[10:11], v[2:3], 0, v[6:7]
	ds_read_b128 v[6:9], v8
	v_add_u32_e32 v5, 0xd00, v4
	s_waitcnt lgkmcnt(0)
	global_store_dwordx4 v[10:11], v[6:9], off
	s_nop 1
	v_ashrrev_i32_e32 v6, 4, v5
	v_ashrrev_i32_e32 v7, 31, v6
	v_mad_u64_u32 v[8:9], s[0:1], v6, s30, v[0:1]
	v_lshlrev_b64 v[6:7], 11, v[6:7]
	v_lshl_add_u64 v[10:11], v[2:3], 0, v[6:7]
	ds_read_b128 v[6:9], v8
	v_add_u32_e32 v5, 0xe00, v4
	v_add_u32_e32 v4, 0xf00, v4
	v_ashrrev_i32_e32 v4, 4, v4
	s_waitcnt lgkmcnt(0)
	global_store_dwordx4 v[10:11], v[6:9], off
	s_nop 1
	v_ashrrev_i32_e32 v6, 4, v5
	v_ashrrev_i32_e32 v7, 31, v6
	v_mad_u64_u32 v[8:9], s[0:1], v6, s30, v[0:1]
	v_lshlrev_b64 v[6:7], 11, v[6:7]
	v_lshl_add_u64 v[10:11], v[2:3], 0, v[6:7]
	ds_read_b128 v[6:9], v8
	v_ashrrev_i32_e32 v5, 31, v4
	s_waitcnt lgkmcnt(0)
	global_store_dwordx4 v[10:11], v[6:9], off
	s_nop 1
	v_mad_u64_u32 v[6:7], s[0:1], v4, s30, v[0:1]
	v_lshlrev_b64 v[4:5], 11, v[4:5]
	v_lshl_add_u64 v[8:9], v[2:3], 0, v[4:5]
	ds_read_b128 v[2:5], v6
	s_waitcnt lgkmcnt(0)
	global_store_dwordx4 v[8:9], v[2:5], off
	s_barrier
	s_branch .LBB0_198

.LBB0_209:
	s_cmp_ge_i32 s20, s14
	s_mov_b64 s[0:1], -1
	s_cbranch_scc0 .LBB0_211
	s_sub_i32 s0, s20, s14
	s_lshl_b32 s0, s0, 5
	v_mov_b32_e32 v10, v196
	s_and_b32 s2, s0, 0x7fffff80
	s_and_b32 s5, s20, 3
	v_lshrrev_b32_e32 v0, 2, v10
	s_lshl_b64 s[0:1], s[2:3], 10
	v_and_b32_e32 v0, 12, v0
	s_add_u32 s2, s15, s0
	v_lshrrev_b32_e64 v0, v0, s57
	s_addc_u32 s7, s21, s1
	s_lshl_b32 s4, s5, 8
	v_xor_b32_e32 v0, v0, v10
	s_add_u32 s6, s2, s4
	v_ashrrev_i32_e32 v2, 2, v10
	v_lshlrev_b32_e32 v0, 4, v0
	s_addc_u32 s7, s7, 0
	v_and_b32_e32 v0, 48, v0
	v_ashrrev_i32_e32 v3, 31, v2
	v_lshl_add_u64 v[4:5], s[6:7], 0, v[0:1]
	v_lshlrev_b64 v[6:7], 10, v[2:3]
	v_lshl_add_u64 v[70:71], v[4:5], 0, v[6:7]
	v_add_u32_e32 v6, 64, v2
	s_lshl_b32 s2, s5, 15
	v_readlane_b32 s8, v224, 11
	v_ashrrev_i32_e32 v7, 31, v6
	s_add_u32 s8, s8, s2
	v_readlane_b32 s2, v224, 12
	v_lshlrev_b64 v[8:9], 10, v[6:7]
	s_addc_u32 s9, s2, 0
	v_lshl_add_u64 v[72:73], v[4:5], 0, v[8:9]
	v_and_b32_e32 v8, 15, v10
	v_lshlrev_b64 v[4:5], 8, v[6:7]
	v_lshl_add_u32 v12, v10, 4, 0
	v_lshrrev_b32_e32 v6, 1, v10
	s_mov_b32 s2, 0x3ffffc0
	v_lshlrev_b64 v[2:3], 8, v[2:3]
	v_and_or_b32 v13, v6, s2, v8
	v_readfirstlane_b32 s2, v12
	v_add_u32_e32 v8, 0x1000, v12
	v_lshl_add_u64 v[2:3], s[8:9], 0, v[2:3]
	v_and_b32_e32 v6, 12, v10
	s_mov_b32 m0, s2
	v_readfirstlane_b32 s6, v8
	v_lshl_add_u64 v[74:75], v[2:3], 0, v[0:1]
	v_add_u32_e32 v2, 0x2000, v12
	v_lshrrev_b32_e32 v11, 4, v10
	v_lshl_add_u64 v[4:5], s[8:9], 0, v[4:5]
	v_lshrrev_b32_e64 v6, v6, s57
	global_load_lds_dwordx4 v[70:71], off
	s_mov_b32 m0, s6
	v_readfirstlane_b32 s7, v2
	v_add_u32_e32 v2, 0x3000, v12
	v_xor_b32_e32 v6, v6, v11
	global_load_lds_dwordx4 v[72:73], off
	v_lshl_add_u64 v[76:77], v[4:5], 0, v[0:1]
	s_mov_b32 m0, s7
	v_readfirstlane_b32 s8, v2
	v_add_u32_e32 v4, 0x4000, v12
	v_lshlrev_b32_e32 v11, 4, v6
	v_lshlrev_b32_e32 v6, 6, v10
	global_load_lds_dwordx4 v[74:75], off
	s_mov_b32 m0, s8
	v_readfirstlane_b32 s9, v4
	v_and_b32_e32 v10, 0x13c0, v6
	v_lshl_add_u64 v[6:7], v[70:71], 0, 64
	global_load_lds_dwordx4 v[76:77], off
	s_mov_b32 m0, s9
	v_add_u32_e32 v4, 0x5000, v12
	global_load_lds_dwordx4 v[6:7], off
	v_readfirstlane_b32 s9, v4
	v_add_u32_e32 v6, 0x6000, v12
	v_lshl_add_u64 v[8:9], v[72:73], 0, 64
	s_mov_b32 m0, s9
	v_readfirstlane_b32 s9, v6
	v_lshl_add_u64 v[2:3], v[74:75], 0, 64
	global_load_lds_dwordx4 v[8:9], off
	s_mov_b32 m0, s9
	v_and_b32_e32 v0, 48, v11
	global_load_lds_dwordx4 v[2:3], off
	v_add_u32_e32 v2, 0x7000, v12
	v_lshl_add_u64 v[4:5], v[76:77], 0, 64
	v_readfirstlane_b32 s9, v2
	s_mov_b32 m0, s9
	v_add_u32_e32 v11, 0x8000, v12
	global_load_lds_dwordx4 v[4:5], off
	v_add_u32_e32 v14, 0xb000, v12
	v_add_u32_e32 v15, 0xa000, v12
	v_add_u32_e32 v12, 0x9000, v12
	v_readfirstlane_b32 s9, v11
	s_waitcnt vmcnt(4) lgkmcnt(0)
	s_barrier
	v_lshl_add_u64 v[2:3], v[70:71], 0, s[78:79]
	s_mov_b32 m0, s9
	v_readfirstlane_b32 s9, v12
	v_lshl_add_u64 v[4:5], v[72:73], 0, s[78:79]
	global_load_lds_dwordx4 v[2:3], off
	s_mov_b32 m0, s9
	v_readfirstlane_b32 s9, v15
	v_lshl_add_u64 v[8:9], v[74:75], 0, s[78:79]
	global_load_lds_dwordx4 v[4:5], off
	s_mov_b32 m0, s9
	v_readfirstlane_b32 s9, v14
	v_lshl_add_u64 v[6:7], v[76:77], 0, s[78:79]
	global_load_lds_dwordx4 v[8:9], off
	s_mov_b32 m0, s9
	v_add3_u32 v90, 0, v10, v0
	v_lshlrev_b32_e32 v10, 6, v13
	global_load_lds_dwordx4 v[6:7], off
	v_add3_u32 v0, 0, v10, v0
	ds_read_b128 v[2:5], v90 offset:8192
	ds_read_b128 v[6:9], v90 offset:9216
	ds_read_b128 v[10:13], v0
	ds_read_b128 v[14:17], v0 offset:1024
	ds_read_b128 v[22:25], v90 offset:10240
	ds_read_b128 v[30:33], v90 offset:11264
	ds_read_b128 v[50:53], v0 offset:2048
	ds_read_b128 v[54:57], v0 offset:3072
	v_lshl_add_u64 v[70:71], v[70:71], 0, s[84:85]
	s_waitcnt vmcnt(4) lgkmcnt(0)
	s_barrier
	s_mov_b32 m0, s2
	v_lshl_add_u64 v[72:73], v[72:73], 0, s[84:85]
	global_load_lds_dwordx4 v[70:71], off
	s_mov_b32 m0, s6
	v_lshl_add_u64 v[74:75], v[74:75], 0, s[84:85]
	global_load_lds_dwordx4 v[72:73], off
	s_mov_b32 m0, s7
	v_lshl_add_u64 v[76:77], v[76:77], 0, s[84:85]
	global_load_lds_dwordx4 v[74:75], off
	s_mov_b32 m0, s8
	s_waitcnt lgkmcnt(0)
	s_setprio 1
	v_mfma_f32_16x16x32_bf16 v[18:21], v[2:5], v[10:13], 0
	global_load_lds_dwordx4 v[76:77], off
	s_setprio 0
	ds_read_b128 v[70:73], v90 offset:24576
	s_setprio 1
	v_mfma_f32_16x16x32_bf16 v[26:29], v[6:9], v[10:13], 0
	s_lshl_b32 s2, s5, 9
	v_lshl_add_u64 v[94:95], v[146:147], 0, s[2:3]
	v_readlane_b32 s2, v224, 1
	v_mfma_f32_16x16x32_bf16 v[34:37], v[22:25], v[10:13], 0
	s_add_u32 s0, s2, s0
	v_readlane_b32 s2, v224, 2
	s_addc_u32 s1, s2, s1
	v_mfma_f32_16x16x32_bf16 v[10:13], v[30:33], v[10:13], 0
	s_mov_b32 s2, 0xfffffc0
	s_add_u32 s0, s0, s4
	s_addc_u32 s1, s1, 0
	v_mfma_f32_16x16x32_bf16 v[38:41], v[2:5], v[14:17], 0
	v_mfma_f32_16x16x32_bf16 v[42:45], v[6:9], v[14:17], 0
	v_mfma_f32_16x16x32_bf16 v[46:49], v[22:25], v[14:17], 0
	v_mfma_f32_16x16x32_bf16 v[14:17], v[30:33], v[14:17], 0
	v_mfma_f32_16x16x32_bf16 v[58:61], v[2:5], v[50:53], 0
	v_mfma_f32_16x16x32_bf16 v[62:65], v[6:9], v[50:53], 0
	v_mfma_f32_16x16x32_bf16 v[66:69], v[22:25], v[50:53], 0
	v_mfma_f32_16x16x32_bf16 v[50:53], v[30:33], v[50:53], 0
	v_mfma_f32_16x16x32_bf16 v[2:5], v[2:5], v[54:57], 0
	v_mfma_f32_16x16x32_bf16 v[6:9], v[6:9], v[54:57], 0
	v_mfma_f32_16x16x32_bf16 v[22:25], v[22:25], v[54:57], 0
	v_mfma_f32_16x16x32_bf16 v[30:33], v[30:33], v[54:57], 0
	s_setprio 0
	ds_read_b128 v[54:57], v90 offset:25600
	ds_read_b128 v[74:77], v0 offset:16384
	ds_read_b128 v[78:81], v0 offset:17408
	ds_read_b128 v[82:85], v90 offset:26624
	ds_read_b128 v[86:89], v90 offset:27648
	s_waitcnt lgkmcnt(0)
	s_setprio 1
	v_mfma_f32_16x16x32_bf16 v[18:21], v[70:73], v[74:77], v[18:21]
	v_mfma_f32_16x16x32_bf16 v[26:29], v[54:57], v[74:77], v[26:29]
	v_mfma_f32_16x16x32_bf16 v[34:37], v[82:85], v[74:77], v[34:37]
	v_mfma_f32_16x16x32_bf16 v[10:13], v[86:89], v[74:77], v[10:13]
	v_mfma_f32_16x16x32_bf16 v[38:41], v[70:73], v[78:81], v[38:41]
	v_mfma_f32_16x16x32_bf16 v[42:45], v[54:57], v[78:81], v[42:45]
	v_mfma_f32_16x16x32_bf16 v[46:49], v[82:85], v[78:81], v[46:49]
	v_mfma_f32_16x16x32_bf16 v[14:17], v[86:89], v[78:81], v[14:17]
	s_setprio 0
	ds_read_b128 v[74:77], v0 offset:18432
	ds_read_b128 v[78:81], v0 offset:19456
	s_waitcnt vmcnt(4) lgkmcnt(0)
	s_barrier
	s_waitcnt lgkmcnt(0)
	s_setprio 1
	v_mfma_f32_16x16x32_bf16 v[58:61], v[70:73], v[74:77], v[58:61]
	v_mfma_f32_16x16x32_bf16 v[62:65], v[54:57], v[74:77], v[62:65]
	v_mfma_f32_16x16x32_bf16 v[66:69], v[82:85], v[74:77], v[66:69]
	v_mfma_f32_16x16x32_bf16 v[50:53], v[86:89], v[74:77], v[50:53]
	v_mfma_f32_16x16x32_bf16 v[2:5], v[70:73], v[78:81], v[2:5]
	v_mfma_f32_16x16x32_bf16 v[6:9], v[54:57], v[78:81], v[6:9]
	s_setprio 0
	ds_read_b128 v[54:57], v90 offset:40960
	s_setprio 1
	v_mfma_f32_16x16x32_bf16 v[22:25], v[82:85], v[78:81], v[22:25]
	v_mfma_f32_16x16x32_bf16 v[30:33], v[86:89], v[78:81], v[30:33]
	s_setprio 0
	ds_read_b128 v[70:73], v90 offset:41984
	ds_read_b128 v[74:77], v0 offset:32768
	ds_read_b128 v[78:81], v0 offset:33792
	ds_read_b128 v[82:85], v90 offset:43008
	ds_read_b128 v[86:89], v90 offset:44032
	s_waitcnt lgkmcnt(0)
	s_setprio 1
	v_mfma_f32_16x16x32_bf16 v[18:21], v[54:57], v[74:77], v[18:21]
	v_mfma_f32_16x16x32_bf16 v[26:29], v[70:73], v[74:77], v[26:29]
	v_mfma_f32_16x16x32_bf16 v[34:37], v[82:85], v[74:77], v[34:37]
	v_mfma_f32_16x16x32_bf16 v[10:13], v[86:89], v[74:77], v[10:13]
	v_mfma_f32_16x16x32_bf16 v[38:41], v[54:57], v[78:81], v[38:41]
	v_mfma_f32_16x16x32_bf16 v[42:45], v[70:73], v[78:81], v[42:45]
	v_mfma_f32_16x16x32_bf16 v[46:49], v[82:85], v[78:81], v[46:49]
	v_mfma_f32_16x16x32_bf16 v[14:17], v[86:89], v[78:81], v[14:17]
	s_setprio 0
	ds_read_b128 v[74:77], v0 offset:34816
	ds_read_b128 v[78:81], v0 offset:35840
	s_waitcnt vmcnt(0) lgkmcnt(0)
	s_barrier
	s_waitcnt lgkmcnt(0)
	s_setprio 1
	v_mfma_f32_16x16x32_bf16 v[58:61], v[54:57], v[74:77], v[58:61]
	v_mfma_f32_16x16x32_bf16 v[62:65], v[70:73], v[74:77], v[62:65]
	v_mfma_f32_16x16x32_bf16 v[66:69], v[82:85], v[74:77], v[66:69]
	v_mfma_f32_16x16x32_bf16 v[50:53], v[86:89], v[74:77], v[50:53]
	v_mfma_f32_16x16x32_bf16 v[2:5], v[54:57], v[78:81], v[2:5]
	s_setprio 0
	ds_read_b128 v[54:57], v90 offset:8192
	s_setprio 1
	v_mfma_f32_16x16x32_bf16 v[6:9], v[70:73], v[78:81], v[6:9]
	v_mfma_f32_16x16x32_bf16 v[22:25], v[82:85], v[78:81], v[22:25]
	v_mfma_f32_16x16x32_bf16 v[30:33], v[86:89], v[78:81], v[30:33]
	s_setprio 0
	ds_read_b128 v[70:73], v90 offset:9216
	ds_read_b128 v[74:77], v0
	ds_read_b128 v[78:81], v0 offset:1024
	ds_read_b128 v[82:85], v90 offset:10240
	ds_read_b128 v[86:89], v90 offset:11264
	s_waitcnt lgkmcnt(0)
	s_setprio 1
	v_mfma_f32_16x16x32_bf16 v[18:21], v[54:57], v[74:77], v[18:21]
	v_mfma_f32_16x16x32_bf16 v[26:29], v[70:73], v[74:77], v[26:29]
	v_mfma_f32_16x16x32_bf16 v[34:37], v[82:85], v[74:77], v[34:37]
	v_mfma_f32_16x16x32_bf16 v[10:13], v[86:89], v[74:77], v[10:13]
	v_mfma_f32_16x16x32_bf16 v[38:41], v[54:57], v[78:81], v[38:41]
	v_mfma_f32_16x16x32_bf16 v[42:45], v[70:73], v[78:81], v[42:45]
	v_mfma_f32_16x16x32_bf16 v[46:49], v[82:85], v[78:81], v[46:49]
	v_mfma_f32_16x16x32_bf16 v[14:17], v[86:89], v[78:81], v[14:17]
	s_setprio 0
	ds_read_b128 v[74:77], v0 offset:2048
	ds_read_b128 v[78:81], v0 offset:3072
	s_waitcnt vmcnt(0) lgkmcnt(0)
	s_barrier
	s_setprio 1
	v_mfma_f32_16x16x32_bf16 v[58:61], v[54:57], v[74:77], v[58:61]
	global_load_dwordx4 v[90:93], v[94:95], off
	v_mfma_f32_16x16x32_bf16 v[2:5], v[54:57], v[78:81], v[2:5]
	global_load_dwordx4 v[54:57], v[94:95], off offset:128
	v_mfma_f32_16x16x32_bf16 v[62:65], v[70:73], v[74:77], v[62:65]
	v_mfma_f32_16x16x32_bf16 v[66:69], v[82:85], v[74:77], v[66:69]
	v_mfma_f32_16x16x32_bf16 v[50:53], v[86:89], v[74:77], v[50:53]
	global_load_dwordx4 v[74:77], v[94:95], off offset:64
	s_setprio 0
	s_waitcnt vmcnt(2)
	v_pk_mul_f32 v[18:19], v[18:19], v[90:91]
	s_setprio 1
	v_mfma_f32_16x16x32_bf16 v[6:9], v[70:73], v[78:81], v[6:9]
	global_load_dwordx4 v[70:73], v[94:95], off offset:192
	s_setprio 0
	s_waitcnt vmcnt(2)
	v_pk_mul_f32 v[34:35], v[34:35], v[54:55]
	v_pk_mul_f32 v[46:47], v[46:47], v[54:55]
	s_setprio 1
	v_mfma_f32_16x16x32_bf16 v[22:25], v[82:85], v[78:81], v[22:25]
	v_mul_f32_e64 v66, v66, v54
	v_mul_f32_e64 v67, v67, v55
	v_pk_mul_f32 v[36:37], v[36:37], v[56:57]
	v_pk_mul_f32 v[48:49], v[48:49], v[56:57]
	v_mfma_f32_16x16x32_bf16 v[30:33], v[86:89], v[78:81], v[30:33]
	v_mul_f32_e64 v20, v20, v92
	v_mul_f32_e64 v21, v21, v93
	s_nop 0
	v_pk_mul_f32 v[22:23], v[22:23], v[54:55]
	v_pk_mul_f32 v[54:55], v[68:69], v[56:57]
	v_pk_mul_f32 v[24:25], v[24:25], v[56:57]
	v_mov_b32_e32 v56, v196
	s_setprio 0
	s_waitcnt vmcnt(1)
	v_pk_mul_f32 v[26:27], v[26:27], v[74:75]
	v_and_b32_e32 v57, 15, v56
	v_lshrrev_b32_e32 v68, 1, v56
	v_and_b32_e32 v0, 64, v56
	v_and_or_b32 v69, v68, s2, v57
	v_pk_mul_f32 v[28:29], v[28:29], v[76:77]
	v_lshl_add_u32 v0, v0, 1, 0
	v_and_b32_e32 v68, 24, v68
	v_mul_lo_u32 v69, v69, s30
	v_add3_u32 v0, v0, v68, v69
	v_cvt_pk_bf16_f32 v18, v18, v19
	v_cvt_pk_bf16_f32 v19, v20, v21
	v_cvt_pk_bf16_f32 v20, v26, v27
	v_cvt_pk_bf16_f32 v21, v28, v29
	v_pk_mul_f32 v[38:39], v[38:39], v[90:91]
	v_pk_mul_f32 v[40:41], v[40:41], v[92:93]
	v_pk_mul_f32 v[42:43], v[42:43], v[74:75]
	v_pk_mul_f32 v[44:45], v[44:45], v[76:77]
	ds_write2_b64 v0, v[18:19], v[20:21] offset1:4
	v_cvt_pk_bf16_f32 v18, v34, v35
	v_cvt_pk_bf16_f32 v19, v36, v37
	v_pk_mul_f32 v[2:3], v[2:3], v[90:91]
	v_pk_mul_f32 v[4:5], v[4:5], v[92:93]
	v_pk_mul_f32 v[6:7], v[6:7], v[74:75]
	v_pk_mul_f32 v[8:9], v[8:9], v[76:77]
	v_pk_mul_f32 v[58:59], v[58:59], v[90:91]
	v_pk_mul_f32 v[60:61], v[60:61], v[92:93]
	v_pk_mul_f32 v[62:63], v[62:63], v[74:75]
	v_pk_mul_f32 v[64:65], v[64:65], v[76:77]
	v_cvt_pk_bf16_f32 v2, v2, v3
	v_cvt_pk_bf16_f32 v3, v4, v5
	v_cvt_pk_bf16_f32 v4, v6, v7
	v_cvt_pk_bf16_f32 v5, v8, v9
	v_add_u32_e32 v6, 0x100, v56
	s_waitcnt vmcnt(0)
	v_pk_mul_f32 v[10:11], v[10:11], v[70:71]
	v_pk_mul_f32 v[12:13], v[12:13], v[72:73]
	v_cvt_pk_bf16_f32 v10, v10, v11
	v_cvt_pk_bf16_f32 v11, v12, v13
	v_pk_mul_f32 v[14:15], v[14:15], v[70:71]
	v_pk_mul_f32 v[16:17], v[16:17], v[72:73]
	ds_write2_b64 v0, v[18:19], v[10:11] offset0:8 offset1:12
	v_cvt_pk_bf16_f32 v10, v38, v39
	v_cvt_pk_bf16_f32 v11, v40, v41
	v_cvt_pk_bf16_f32 v12, v42, v43
	v_cvt_pk_bf16_f32 v13, v44, v45
	v_add_u32_e32 v18, 0x1000, v0
	v_pk_mul_f32 v[30:31], v[30:31], v[70:71]
	v_pk_mul_f32 v[32:33], v[32:33], v[72:73]
	ds_write2_b64 v18, v[10:11], v[12:13] offset0:32 offset1:36
	v_cvt_pk_bf16_f32 v10, v46, v47
	v_cvt_pk_bf16_f32 v11, v48, v49
	v_cvt_pk_bf16_f32 v12, v14, v15
	v_cvt_pk_bf16_f32 v13, v16, v17
	v_add_u32_e32 v14, 0x2000, v0
	v_add_u32_e32 v0, 0x3000, v0
	v_pk_mul_f32 v[50:51], v[50:51], v[70:71]
	v_pk_mul_f32 v[52:53], v[52:53], v[72:73]
	ds_write2_b64 v18, v[10:11], v[12:13] offset0:40 offset1:44
	v_cvt_pk_bf16_f32 v10, v58, v59
	v_cvt_pk_bf16_f32 v11, v60, v61
	v_cvt_pk_bf16_f32 v12, v62, v63
	v_cvt_pk_bf16_f32 v13, v64, v65
	ds_write2_b64 v0, v[2:3], v[4:5] offset0:96 offset1:100
	v_cvt_pk_bf16_f32 v2, v22, v23
	v_cvt_pk_bf16_f32 v3, v24, v25
	v_cvt_pk_bf16_f32 v4, v30, v31
	v_cvt_pk_bf16_f32 v5, v32, v33
	ds_write2_b64 v14, v[10:11], v[12:13] offset0:64 offset1:68
	v_cvt_pk_bf16_f32 v10, v66, v67
	v_cvt_pk_bf16_f32 v11, v54, v55
	v_cvt_pk_bf16_f32 v12, v50, v51
	v_cvt_pk_bf16_f32 v13, v52, v53
	ds_write2_b64 v0, v[2:3], v[4:5] offset0:104 offset1:108
	v_lshlrev_b32_e32 v0, 4, v57
	v_ashrrev_i32_e32 v2, 4, v56
	ds_write2_b64 v14, v[10:11], v[12:13] offset0:72 offset1:76
	v_lshl_add_u64 v[10:11], s[0:1], 0, v[0:1]
	v_add_u32_e32 v0, 0, v0
	v_ashrrev_i32_e32 v3, 31, v2
	v_mad_u64_u32 v[4:5], s[0:1], v2, s30, v[0:1]
	v_lshlrev_b64 v[2:3], 10, v[2:3]
	s_waitcnt lgkmcnt(0)
	s_barrier
	v_lshl_add_u64 v[12:13], v[10:11], 0, v[2:3]
	ds_read_b128 v[2:5], v4
	v_ashrrev_i32_e32 v14, 4, v6
	v_mad_u64_u32 v[6:7], s[0:1], v14, s30, v[0:1]
	ds_read_b128 v[6:9], v6
	v_ashrrev_i32_e32 v15, 31, v14
	s_waitcnt lgkmcnt(1)
	global_store_dwordx4 v[12:13], v[2:5], off
	s_nop 1
	v_lshlrev_b64 v[2:3], 10, v[14:15]
	v_lshl_add_u64 v[2:3], v[10:11], 0, v[2:3]
	s_waitcnt lgkmcnt(0)
	global_store_dwordx4 v[2:3], v[6:9], off
	v_add_u32_e32 v2, 0x200, v56
	v_ashrrev_i32_e32 v2, 4, v2
	v_ashrrev_i32_e32 v3, 31, v2
	v_mad_u64_u32 v[4:5], s[0:1], v2, s30, v[0:1]
	v_lshlrev_b64 v[2:3], 10, v[2:3]
	v_add_u32_e32 v6, 0x300, v56
	v_lshl_add_u64 v[12:13], v[10:11], 0, v[2:3]
	ds_read_b128 v[2:5], v4
	v_ashrrev_i32_e32 v14, 4, v6
	v_mad_u64_u32 v[6:7], s[0:1], v14, s30, v[0:1]
	ds_read_b128 v[6:9], v6
	v_ashrrev_i32_e32 v15, 31, v14
	s_waitcnt lgkmcnt(1)
	global_store_dwordx4 v[12:13], v[2:5], off
	s_nop 1
	v_lshlrev_b64 v[2:3], 10, v[14:15]
	v_lshl_add_u64 v[2:3], v[10:11], 0, v[2:3]
	s_waitcnt lgkmcnt(0)
	global_store_dwordx4 v[2:3], v[6:9], off
	v_add_u32_e32 v2, 0x400, v56
	v_ashrrev_i32_e32 v2, 4, v2
	v_ashrrev_i32_e32 v3, 31, v2
	v_mad_u64_u32 v[4:5], s[0:1], v2, s30, v[0:1]
	v_lshlrev_b64 v[2:3], 10, v[2:3]
	v_add_u32_e32 v6, 0x500, v56
	v_lshl_add_u64 v[12:13], v[10:11], 0, v[2:3]
	ds_read_b128 v[2:5], v4
	v_ashrrev_i32_e32 v14, 4, v6
	v_mad_u64_u32 v[6:7], s[0:1], v14, s30, v[0:1]
	ds_read_b128 v[6:9], v6
	v_ashrrev_i32_e32 v15, 31, v14
	s_waitcnt lgkmcnt(1)
	global_store_dwordx4 v[12:13], v[2:5], off
	s_nop 1
	v_lshlrev_b64 v[2:3], 10, v[14:15]
	v_lshl_add_u64 v[2:3], v[10:11], 0, v[2:3]
	s_waitcnt lgkmcnt(0)
	global_store_dwordx4 v[2:3], v[6:9], off
	v_add_u32_e32 v2, 0x600, v56
	v_ashrrev_i32_e32 v2, 4, v2
	v_ashrrev_i32_e32 v3, 31, v2
	v_mad_u64_u32 v[4:5], s[0:1], v2, s30, v[0:1]
	v_lshlrev_b64 v[2:3], 10, v[2:3]
	v_add_u32_e32 v6, 0x700, v56
	v_lshl_add_u64 v[12:13], v[10:11], 0, v[2:3]
	ds_read_b128 v[2:5], v4
	v_ashrrev_i32_e32 v14, 4, v6
	v_mad_u64_u32 v[6:7], s[0:1], v14, s30, v[0:1]
	ds_read_b128 v[6:9], v6
	v_ashrrev_i32_e32 v15, 31, v14
	s_waitcnt lgkmcnt(1)
	global_store_dwordx4 v[12:13], v[2:5], off
	s_mov_b64 s[0:1], 0
	s_nop 0
	v_lshlrev_b64 v[2:3], 10, v[14:15]
	v_lshl_add_u64 v[2:3], v[10:11], 0, v[2:3]
	s_waitcnt lgkmcnt(0)
	global_store_dwordx4 v[2:3], v[6:9], off
	s_barrier

.LBB0_355:
	s_lshl_b32 s10, s36, 7
	s_add_u32 s11, s59, s14
	v_readlane_b32 s14, v225, 54
	s_addc_u32 s18, s14, s15
	v_readlane_b32 s14, v225, 48
	v_readlane_b32 s15, v225, 49
	s_add_u32 s14, s14, s0
	s_addc_u32 s15, s15, s1
	s_mul_hi_i32 s1, s27, s25
	s_mul_i32 s0, s27, s25
	s_lshl_b64 s[0:1], s[0:1], 1
	s_add_u32 s14, s14, s0
	s_addc_u32 s15, s15, s1
	s_mul_hi_i32 s1, s10, s27
	s_mul_i32 s0, s10, s27
	s_lshl_b64 s[0:1], s[0:1], 1
	s_add_u32 s0, s11, s0
	s_addc_u32 s1, s18, s1
	s_mov_b64 s[18:19], -1
	s_and_b64 vcc, exec, s[16:17]
	s_cbranch_vccz .LBB0_365
	s_cmp_gt_i32 s36, 3
	s_mov_b64 s[16:17], -1
	s_cbranch_scc0 .LBB0_360
	v_mov_b32_e32 v16, v196
	s_movk_i32 s17, 0x1320
	v_lshrrev_b32_e32 v0, 2, v16
	v_and_b32_e32 v0, 12, v0
	v_lshrrev_b32_e64 v0, v0, s17
	v_ashrrev_i32_e32 v8, 2, v16
	v_xor_b32_e32 v0, v0, v16
	v_lshlrev_b32_e32 v0, 4, v0
	v_mad_i64_i32 v[4:5], s[18:19], v8, s27, 0
	v_add_u32_e32 v8, 64, v8
	v_and_b32_e32 v0, 48, v0
	v_mad_i64_i32 v[8:9], s[18:19], v8, s27, 0
	s_waitcnt lgkmcnt(0)
	v_lshl_add_u64 v[2:3], s[14:15], 0, v[0:1]
	v_lshlrev_b64 v[4:5], 1, v[4:5]
	v_lshlrev_b64 v[8:9], 1, v[8:9]
	v_and_b32_e32 v10, 15, v16
	v_lshl_add_u32 v142, v16, 4, 0
	v_lshrrev_b32_e32 v11, 1, v16
	s_mov_b32 s11, 0x3ffffc0
	v_lshl_add_u64 v[6:7], v[2:3], 0, v[4:5]
	v_lshl_add_u64 v[2:3], v[2:3], 0, v[8:9]
	v_lshl_add_u64 v[8:9], s[0:1], 0, v[8:9]
	v_and_or_b32 v18, v11, s11, v10
	v_readfirstlane_b32 s11, v142
	v_add_u32_e32 v12, 0x1000, v142
	v_lshl_add_u64 v[4:5], s[0:1], 0, v[4:5]
	s_mov_b32 m0, s11
	v_readfirstlane_b32 s11, v12
	v_lshl_add_u64 v[4:5], v[4:5], 0, v[0:1]
	v_lshl_add_u64 v[8:9], v[8:9], 0, v[0:1]
	v_add_u32_e32 v0, 0x2000, v142
	global_load_lds_dwordx4 v[6:7], off
	s_mov_b32 m0, s11
	v_readfirstlane_b32 s11, v0
	v_add_u32_e32 v0, 0x3000, v142
	global_load_lds_dwordx4 v[2:3], off
	s_mov_b32 m0, s11
	v_readfirstlane_b32 s11, v0
	v_add_u32_e32 v0, 0x4000, v142
	global_load_lds_dwordx4 v[4:5], off
	s_mov_b32 m0, s11
	v_readfirstlane_b32 s11, v0
	v_add_u32_e32 v0, 0x5000, v142
	v_lshl_add_u64 v[10:11], v[6:7], 0, 64
	global_load_lds_dwordx4 v[8:9], off
	s_mov_b32 m0, s11
	v_readfirstlane_b32 s11, v0
	v_add_u32_e32 v0, 0x6000, v142
	v_lshl_add_u64 v[12:13], v[2:3], 0, 64
	global_load_lds_dwordx4 v[10:11], off
	s_mov_b32 m0, s11
	v_readfirstlane_b32 s11, v0
	v_add_u32_e32 v0, 0x7000, v142
	v_lshl_add_u64 v[14:15], v[4:5], 0, 64
	global_load_lds_dwordx4 v[12:13], off
	s_mov_b32 m0, s11
	v_readfirstlane_b32 s11, v0
	v_lshl_add_u64 v[10:11], v[8:9], 0, 64
	global_load_lds_dwordx4 v[14:15], off
	s_mov_b32 m0, s11
	v_and_b32_e32 v0, 12, v16
	global_load_lds_dwordx4 v[10:11], off
	v_lshrrev_b32_e32 v17, 4, v16
	v_lshrrev_b32_e64 v0, v0, s17
	v_xor_b32_e32 v0, v0, v17
	v_lshlrev_b32_e32 v0, 4, v0
	v_lshlrev_b32_e32 v10, 6, v16
	s_lshr_b32 s11, s27, 5
	v_lshl_add_u64 v[86:87], v[2:3], 0, s[78:79]
	v_mov_b32_e32 v2, 0
	s_mov_b32 s16, 2
	v_and_b32_e32 v141, 0x13c0, v10
	v_and_b32_e32 v0, 48, v0
	v_lshlrev_b32_e32 v71, 6, v18
	v_lshl_add_u64 v[74:75], v[4:5], 0, s[78:79]
	v_lshl_add_u64 v[72:73], v[8:9], 0, s[78:79]
	v_lshl_add_u64 v[84:85], v[6:7], 0, s[78:79]
	s_add_i32 s17, s11, -2
	s_mov_b32 s11, 0
	v_mov_b32_e32 v3, v2
	v_mov_b32_e32 v4, v2
	v_mov_b32_e32 v5, v2
	v_mov_b32_e32 v6, v2
	v_mov_b32_e32 v7, v2
	v_mov_b32_e32 v8, v2
	v_mov_b32_e32 v9, v2
	v_mov_b32_e32 v10, v2
	v_mov_b32_e32 v11, v2
	v_mov_b32_e32 v12, v2
	v_mov_b32_e32 v13, v2
	v_mov_b32_e32 v14, v2
	v_mov_b32_e32 v15, v2
	v_mov_b32_e32 v16, v2
	v_mov_b32_e32 v17, v2
	v_mov_b32_e32 v18, v2
	v_mov_b32_e32 v19, v2
	v_mov_b32_e32 v20, v2
	v_mov_b32_e32 v21, v2
	v_mov_b32_e32 v22, v2
	v_mov_b32_e32 v23, v2
	v_mov_b32_e32 v24, v2
	v_mov_b32_e32 v25, v2
	v_mov_b32_e32 v26, v2
	v_mov_b32_e32 v27, v2
	v_mov_b32_e32 v28, v2
	v_mov_b32_e32 v29, v2
	v_mov_b32_e32 v30, v2
	v_mov_b32_e32 v31, v2
	v_mov_b32_e32 v32, v2
	v_mov_b32_e32 v33, v2
	v_mov_b32_e32 v34, v2
	v_mov_b32_e32 v35, v2
	v_mov_b32_e32 v36, v2
	v_mov_b32_e32 v37, v2
	v_mov_b32_e32 v38, v2
	v_mov_b32_e32 v39, v2
	v_mov_b32_e32 v40, v2
	v_mov_b32_e32 v41, v2
	v_mov_b32_e32 v42, v2
	v_mov_b32_e32 v43, v2
	v_mov_b32_e32 v44, v2
	v_mov_b32_e32 v45, v2
	v_mov_b32_e32 v46, v2
	v_mov_b32_e32 v47, v2
	v_mov_b32_e32 v48, v2
	v_mov_b32_e32 v49, v2
	v_mov_b32_e32 v50, v2
	v_mov_b32_e32 v51, v2
	v_mov_b32_e32 v52, v2
	v_mov_b32_e32 v53, v2
	v_mov_b32_e32 v54, v2
	v_mov_b32_e32 v55, v2
	v_mov_b32_e32 v56, v2
	v_mov_b32_e32 v57, v2
	v_mov_b32_e32 v58, v2
	v_mov_b32_e32 v59, v2
	v_mov_b32_e32 v60, v2
	v_mov_b32_e32 v61, v2
	v_mov_b32_e32 v62, v2
	v_mov_b32_e32 v63, v2
	v_mov_b32_e32 v64, v2
	v_mov_b32_e32 v65, v2

.LBB0_360:
	s_and_b64 vcc, exec, s[16:17]
	s_cbranch_vccz .LBB0_364
	v_mov_b32_e32 v16, v196
	s_movk_i32 s18, 0x1320
	v_lshrrev_b32_e32 v0, 2, v16
	v_and_b32_e32 v0, 12, v0
	v_lshrrev_b32_e64 v0, v0, s18
	v_ashrrev_i32_e32 v8, 2, v16
	v_xor_b32_e32 v0, v0, v16
	v_lshlrev_b32_e32 v0, 4, v0
	v_mad_i64_i32 v[4:5], s[16:17], v8, s27, 0
	v_add_u32_e32 v8, 64, v8
	v_and_b32_e32 v0, 48, v0
	v_mad_i64_i32 v[8:9], s[16:17], v8, s27, 0
	s_waitcnt lgkmcnt(0)
	v_lshl_add_u64 v[2:3], s[14:15], 0, v[0:1]
	v_lshlrev_b64 v[4:5], 1, v[4:5]
	v_lshlrev_b64 v[8:9], 1, v[8:9]
	v_and_b32_e32 v10, 15, v16
	v_lshl_add_u32 v141, v16, 4, 0
	v_lshrrev_b32_e32 v11, 1, v16
	s_mov_b32 s16, 0x3ffffc0
	v_lshl_add_u64 v[6:7], v[2:3], 0, v[4:5]
	v_lshl_add_u64 v[2:3], v[2:3], 0, v[8:9]
	v_lshl_add_u64 v[8:9], s[0:1], 0, v[8:9]
	v_and_or_b32 v18, v11, s16, v10
	v_readfirstlane_b32 s16, v141
	v_add_u32_e32 v12, 0x1000, v141
	v_lshl_add_u64 v[4:5], s[0:1], 0, v[4:5]
	s_mov_b32 m0, s16
	v_readfirstlane_b32 s16, v12
	v_lshl_add_u64 v[4:5], v[4:5], 0, v[0:1]
	v_lshl_add_u64 v[8:9], v[8:9], 0, v[0:1]
	v_add_u32_e32 v0, 0x2000, v141
	global_load_lds_dwordx4 v[6:7], off
	s_mov_b32 m0, s16
	v_readfirstlane_b32 s16, v0
	v_add_u32_e32 v0, 0x3000, v141
	global_load_lds_dwordx4 v[2:3], off
	s_mov_b32 m0, s16
	v_readfirstlane_b32 s16, v0
	v_add_u32_e32 v0, 0x4000, v141
	global_load_lds_dwordx4 v[4:5], off
	s_mov_b32 m0, s16
	v_readfirstlane_b32 s16, v0
	v_add_u32_e32 v0, 0x5000, v141
	v_lshl_add_u64 v[10:11], v[6:7], 0, 64
	global_load_lds_dwordx4 v[8:9], off
	s_mov_b32 m0, s16
	v_readfirstlane_b32 s16, v0
	v_add_u32_e32 v0, 0x6000, v141
	v_lshl_add_u64 v[12:13], v[2:3], 0, 64
	global_load_lds_dwordx4 v[10:11], off
	s_mov_b32 m0, s16
	v_readfirstlane_b32 s16, v0
	v_add_u32_e32 v0, 0x7000, v141
	v_lshl_add_u64 v[14:15], v[4:5], 0, 64
	global_load_lds_dwordx4 v[12:13], off
	s_mov_b32 m0, s16
	v_readfirstlane_b32 s16, v0
	v_lshl_add_u64 v[10:11], v[8:9], 0, 64
	global_load_lds_dwordx4 v[14:15], off
	s_mov_b32 m0, s16
	v_and_b32_e32 v0, 12, v16
	global_load_lds_dwordx4 v[10:11], off
	v_lshrrev_b32_e32 v17, 4, v16
	v_lshrrev_b32_e64 v0, v0, s18
	v_xor_b32_e32 v0, v0, v17
	v_lshlrev_b32_e32 v0, 4, v0
	v_lshlrev_b32_e32 v10, 6, v16
	s_lshr_b32 s16, s27, 5
	v_lshl_add_u64 v[86:87], v[2:3], 0, s[78:79]
	v_mov_b32_e32 v2, 0
	s_mov_b32 s11, 2
	v_and_b32_e32 v142, 0x13c0, v10
	v_and_b32_e32 v0, 48, v0
	v_lshlrev_b32_e32 v71, 6, v18
	v_lshl_add_u64 v[74:75], v[4:5], 0, s[78:79]
	v_lshl_add_u64 v[72:73], v[8:9], 0, s[78:79]
	v_lshl_add_u64 v[84:85], v[6:7], 0, s[78:79]
	s_add_i32 s17, s16, -2
	s_mov_b32 s16, 0
	v_mov_b32_e32 v3, v2
	v_mov_b32_e32 v4, v2
	v_mov_b32_e32 v5, v2
	v_mov_b32_e32 v6, v2
	v_mov_b32_e32 v7, v2
	v_mov_b32_e32 v8, v2
	v_mov_b32_e32 v9, v2
	v_mov_b32_e32 v10, v2
	v_mov_b32_e32 v11, v2
	v_mov_b32_e32 v12, v2
	v_mov_b32_e32 v13, v2
	v_mov_b32_e32 v14, v2
	v_mov_b32_e32 v15, v2
	v_mov_b32_e32 v16, v2
	v_mov_b32_e32 v17, v2
	v_mov_b32_e32 v18, v2
	v_mov_b32_e32 v19, v2
	v_mov_b32_e32 v20, v2
	v_mov_b32_e32 v21, v2
	v_mov_b32_e32 v22, v2
	v_mov_b32_e32 v23, v2
	v_mov_b32_e32 v24, v2
	v_mov_b32_e32 v25, v2
	v_mov_b32_e32 v26, v2
	v_mov_b32_e32 v27, v2
	v_mov_b32_e32 v28, v2
	v_mov_b32_e32 v29, v2
	v_mov_b32_e32 v30, v2
	v_mov_b32_e32 v31, v2
	v_mov_b32_e32 v32, v2
	v_mov_b32_e32 v33, v2
	v_mov_b32_e32 v34, v2
	v_mov_b32_e32 v35, v2
	v_mov_b32_e32 v36, v2
	v_mov_b32_e32 v37, v2
	v_mov_b32_e32 v38, v2
	v_mov_b32_e32 v39, v2
	v_mov_b32_e32 v40, v2
	v_mov_b32_e32 v41, v2
	v_mov_b32_e32 v42, v2
	v_mov_b32_e32 v43, v2
	v_mov_b32_e32 v44, v2
	v_mov_b32_e32 v45, v2
	v_mov_b32_e32 v46, v2
	v_mov_b32_e32 v47, v2
	v_mov_b32_e32 v48, v2
	v_mov_b32_e32 v49, v2
	v_mov_b32_e32 v50, v2
	v_mov_b32_e32 v51, v2
	v_mov_b32_e32 v52, v2
	v_mov_b32_e32 v53, v2
	v_mov_b32_e32 v54, v2
	v_mov_b32_e32 v55, v2
	v_mov_b32_e32 v56, v2
	v_mov_b32_e32 v57, v2
	v_mov_b32_e32 v58, v2
	v_mov_b32_e32 v59, v2
	v_mov_b32_e32 v60, v2
	v_mov_b32_e32 v61, v2
	v_mov_b32_e32 v62, v2
	v_mov_b32_e32 v63, v2
	v_mov_b32_e32 v64, v2
	v_mov_b32_e32 v65, v2

.LBB0_365:
	s_andn2_b64 vcc, exec, s[18:19]
	s_cbranch_vccnz .LBB0_313
	v_mov_b32_e32 v16, v196
	s_movk_i32 s16, 0x1320
	v_lshrrev_b32_e32 v0, 2, v16
	v_and_b32_e32 v0, 12, v0
	v_lshrrev_b32_e64 v0, v0, s16
	v_xor_b32_e32 v0, v0, v16
	v_lshlrev_b32_e32 v0, 4, v0
	v_ashrrev_i32_e32 v8, 2, v16
	v_and_b32_e32 v0, 48, v0
	s_waitcnt lgkmcnt(0)
	v_lshl_add_u64 v[2:3], s[14:15], 0, v[0:1]
	v_mad_i64_i32 v[4:5], s[14:15], v8, s27, 0
	v_add_u32_e32 v8, 64, v8
	v_mad_i64_i32 v[8:9], s[14:15], v8, s27, 0
	v_lshlrev_b64 v[4:5], 1, v[4:5]
	v_lshlrev_b64 v[8:9], 1, v[8:9]
	v_and_b32_e32 v10, 15, v16
	v_lshl_add_u32 v141, v16, 4, 0
	v_lshrrev_b32_e32 v11, 1, v16
	s_mov_b32 s14, 0x3ffffc0
	v_lshl_add_u64 v[6:7], v[2:3], 0, v[4:5]
	v_lshl_add_u64 v[2:3], v[2:3], 0, v[8:9]
	v_lshl_add_u64 v[8:9], s[0:1], 0, v[8:9]
	v_and_or_b32 v18, v11, s14, v10
	v_readfirstlane_b32 s14, v141
	v_add_u32_e32 v12, 0x1000, v141
	v_lshl_add_u64 v[4:5], s[0:1], 0, v[4:5]
	s_mov_b32 m0, s14
	v_readfirstlane_b32 s14, v12
	v_lshl_add_u64 v[4:5], v[4:5], 0, v[0:1]
	v_lshl_add_u64 v[8:9], v[8:9], 0, v[0:1]
	v_add_u32_e32 v0, 0x2000, v141
	global_load_lds_dwordx4 v[6:7], off
	s_mov_b32 m0, s14
	v_readfirstlane_b32 s0, v0
	v_add_u32_e32 v0, 0x3000, v141
	global_load_lds_dwordx4 v[2:3], off
	s_mov_b32 m0, s0
	v_readfirstlane_b32 s0, v0
	v_add_u32_e32 v0, 0x4000, v141
	global_load_lds_dwordx4 v[4:5], off
	s_mov_b32 m0, s0
	v_readfirstlane_b32 s0, v0
	v_add_u32_e32 v0, 0x5000, v141
	v_lshl_add_u64 v[10:11], v[6:7], 0, 64
	global_load_lds_dwordx4 v[8:9], off
	s_mov_b32 m0, s0
	v_readfirstlane_b32 s0, v0
	v_add_u32_e32 v0, 0x6000, v141
	v_lshl_add_u64 v[12:13], v[2:3], 0, 64
	global_load_lds_dwordx4 v[10:11], off
	s_mov_b32 m0, s0
	v_readfirstlane_b32 s0, v0
	v_add_u32_e32 v0, 0x7000, v141
	v_lshl_add_u64 v[14:15], v[4:5], 0, 64
	global_load_lds_dwordx4 v[12:13], off
	s_mov_b32 m0, s0
	v_readfirstlane_b32 s0, v0
	v_lshl_add_u64 v[10:11], v[8:9], 0, 64
	global_load_lds_dwordx4 v[14:15], off
	s_mov_b32 m0, s0
	v_and_b32_e32 v0, 12, v16
	global_load_lds_dwordx4 v[10:11], off
	v_lshrrev_b32_e32 v17, 4, v16
	v_lshrrev_b32_e64 v0, v0, s16
	v_xor_b32_e32 v0, v0, v17
	v_lshlrev_b32_e32 v0, 4, v0
	v_lshlrev_b32_e32 v10, 6, v16
	s_lshr_b32 s0, s27, 5
	v_lshl_add_u64 v[86:87], v[2:3], 0, s[78:79]
	v_mov_b32_e32 v2, 0
	s_ashr_i32 s11, s10, 31
	s_mov_b32 s2, 2
	v_and_b32_e32 v142, 0x13c0, v10
	v_and_b32_e32 v0, 48, v0
	v_lshlrev_b32_e32 v71, 6, v18
	v_lshl_add_u64 v[74:75], v[4:5], 0, s[78:79]
	v_lshl_add_u64 v[72:73], v[8:9], 0, s[78:79]
	v_lshl_add_u64 v[84:85], v[6:7], 0, s[78:79]
	s_add_i32 s1, s0, -2
	s_mov_b32 s0, 0
	v_mov_b32_e32 v3, v2
	v_mov_b32_e32 v4, v2
	v_mov_b32_e32 v5, v2
	v_mov_b32_e32 v6, v2
	v_mov_b32_e32 v7, v2
	v_mov_b32_e32 v8, v2
	v_mov_b32_e32 v9, v2
	v_mov_b32_e32 v10, v2
	v_mov_b32_e32 v11, v2
	v_mov_b32_e32 v12, v2
	v_mov_b32_e32 v13, v2
	v_mov_b32_e32 v14, v2
	v_mov_b32_e32 v15, v2
	v_mov_b32_e32 v16, v2
	v_mov_b32_e32 v17, v2
	v_mov_b32_e32 v18, v2
	v_mov_b32_e32 v19, v2
	v_mov_b32_e32 v20, v2
	v_mov_b32_e32 v21, v2
	v_mov_b32_e32 v22, v2
	v_mov_b32_e32 v23, v2
	v_mov_b32_e32 v24, v2
	v_mov_b32_e32 v25, v2
	v_mov_b32_e32 v26, v2
	v_mov_b32_e32 v27, v2
	v_mov_b32_e32 v28, v2
	v_mov_b32_e32 v29, v2
	v_mov_b32_e32 v30, v2
	v_mov_b32_e32 v31, v2
	v_mov_b32_e32 v32, v2
	v_mov_b32_e32 v33, v2
	v_mov_b32_e32 v34, v2
	v_mov_b32_e32 v35, v2
	v_mov_b32_e32 v36, v2
	v_mov_b32_e32 v37, v2
	v_mov_b32_e32 v38, v2
	v_mov_b32_e32 v39, v2
	v_mov_b32_e32 v40, v2
	v_mov_b32_e32 v41, v2
	v_mov_b32_e32 v42, v2
	v_mov_b32_e32 v43, v2
	v_mov_b32_e32 v44, v2
	v_mov_b32_e32 v45, v2
	v_mov_b32_e32 v46, v2
	v_mov_b32_e32 v47, v2
	v_mov_b32_e32 v48, v2
	v_mov_b32_e32 v49, v2
	v_mov_b32_e32 v50, v2
	v_mov_b32_e32 v51, v2
	v_mov_b32_e32 v52, v2
	v_mov_b32_e32 v53, v2
	v_mov_b32_e32 v54, v2
	v_mov_b32_e32 v55, v2
	v_mov_b32_e32 v56, v2
	v_mov_b32_e32 v57, v2
	v_mov_b32_e32 v58, v2
	v_mov_b32_e32 v59, v2
	v_mov_b32_e32 v60, v2
	v_mov_b32_e32 v61, v2
	v_mov_b32_e32 v62, v2
	v_mov_b32_e32 v63, v2
	v_mov_b32_e32 v64, v2
	v_mov_b32_e32 v65, v2

.LBB0_449:
	s_lshl_b32 s18, s42, 7
	s_and_b32 s20, s18, 0x180
	s_lshl_b64 s[18:19], s[2:3], 11
	s_add_u32 s18, s36, s18
	s_addc_u32 s19, s37, s19
	s_lshl_b32 s2, s20, 11
	s_add_u32 s2, s59, s2
	v_readlane_b32 s21, v225, 54
	v_mov_b32_e32 v16, v196
	s_addc_u32 s21, s21, 0
	s_add_u32 s22, s2, 0x200000
	v_lshrrev_b32_e32 v0, 2, v16
	v_and_b32_e32 v0, 12, v0
	s_movk_i32 s2, 0x1320
	v_lshrrev_b32_e64 v17, v0, s2
	v_xor_b32_e32 v0, v17, v16
	v_ashrrev_i32_e32 v2, 2, v16
	v_lshlrev_b32_e32 v0, 4, v0
	v_and_b32_e32 v0, 48, v0
	v_ashrrev_i32_e32 v3, 31, v2
	v_lshl_add_u64 v[4:5], s[18:19], 0, v[0:1]
	v_lshlrev_b64 v[2:3], 11, v[2:3]
	s_mov_b64 s[26:27], 0x20000
	v_and_b32_e32 v11, 15, v16
	v_lshrrev_b32_e32 v12, 1, v16
	s_mov_b32 s18, 0x3ffffc0
	s_addc_u32 s23, s21, 0
	v_lshl_add_u64 v[8:9], v[2:3], 0, s[26:27]
	v_lshl_add_u32 v122, v16, 4, 0
	v_and_or_b32 v18, v12, s18, v11
	v_and_b32_e32 v11, 12, v16
	v_lshl_add_u64 v[6:7], v[4:5], 0, v[2:3]
	v_lshl_add_u64 v[4:5], v[4:5], 0, v[8:9]
	v_lshl_add_u64 v[8:9], s[22:23], 0, v[8:9]
	v_lshrrev_b32_e64 v11, v11, s2
	v_readfirstlane_b32 s2, v122
	v_add_u32_e32 v12, 0x1000, v122
	v_lshl_add_u64 v[14:15], s[22:23], 0, v[2:3]
	s_mov_b32 m0, s2
	v_readfirstlane_b32 s2, v12
	v_lshl_add_u64 v[14:15], v[14:15], 0, v[0:1]
	v_lshl_add_u64 v[8:9], v[8:9], 0, v[0:1]
	v_add_u32_e32 v0, 0x2000, v122
	global_load_lds_dwordx4 v[6:7], off
	s_mov_b32 m0, s2
	v_readfirstlane_b32 s2, v0
	v_add_u32_e32 v0, 0x3000, v122
	global_load_lds_dwordx4 v[4:5], off
	s_mov_b32 m0, s2
	v_readfirstlane_b32 s2, v0
	v_add_u32_e32 v0, 0x4000, v122
	v_lshrrev_b32_e32 v10, 4, v16
	global_load_lds_dwordx4 v[14:15], off
	s_mov_b32 m0, s2
	v_readfirstlane_b32 s2, v0
	v_add_u32_e32 v0, 0x5000, v122
	v_xor_b32_e32 v19, v11, v10
	v_lshl_add_u64 v[10:11], v[6:7], 0, 64
	global_load_lds_dwordx4 v[8:9], off
	s_mov_b32 m0, s2
	v_readfirstlane_b32 s2, v0
	v_add_u32_e32 v0, 0x6000, v122
	v_lshl_add_u64 v[12:13], v[4:5], 0, 64
	global_load_lds_dwordx4 v[10:11], off
	s_mov_b32 m0, s2
	v_readfirstlane_b32 s2, v0
	v_add_u32_e32 v0, 0x7000, v122
	v_lshl_add_u64 v[14:15], v[14:15], 0, 64
	global_load_lds_dwordx4 v[12:13], off
	s_mov_b32 m0, s2
	v_readfirstlane_b32 s2, v0
	v_lshl_add_u64 v[8:9], v[8:9], 0, 64
	global_load_lds_dwordx4 v[14:15], off
	s_mov_b32 m0, s2
	s_and_b32 s2, s42, 3
	global_load_lds_dwordx4 v[8:9], off
	s_lshl_b32 s2, s2, 18
	v_lshl_add_u64 v[114:115], v[4:5], 0, s[78:79]
	v_lshl_add_u64 v[2:3], s[2:3], 0, v[2:3]
	v_bitop3_b32 v4, v17, 3, v16 bitop3:0x48
	v_lshl_or_b32 v2, v4, 4, v2
	v_lshlrev_b32_e32 v0, 4, v19
	v_lshlrev_b32_e32 v8, 6, v16
	v_lshl_add_u64 v[118:119], s[12:13], 0, v[2:3]
	v_mov_b32_e32 v2, 0
	s_mov_b32 s21, 2
	v_and_b32_e32 v124, 0x13c0, v8
	v_and_b32_e32 v0, 48, v0
	v_lshlrev_b32_e32 v123, 6, v18
	v_lshl_add_u64 v[116:117], v[6:7], 0, s[78:79]
	s_mov_b32 s2, 0
	s_mov_b64 s[18:19], 0
	v_mov_b32_e32 v3, v2
	v_mov_b32_e32 v4, v2
	v_mov_b32_e32 v5, v2
	v_mov_b32_e32 v6, v2
	v_mov_b32_e32 v7, v2
	v_mov_b32_e32 v8, v2
	v_mov_b32_e32 v9, v2
	v_mov_b32_e32 v10, v2
	v_mov_b32_e32 v11, v2
	v_mov_b32_e32 v12, v2
	v_mov_b32_e32 v13, v2
	v_mov_b32_e32 v14, v2
	v_mov_b32_e32 v15, v2
	v_mov_b32_e32 v16, v2
	v_mov_b32_e32 v17, v2
	v_mov_b32_e32 v18, v2
	v_mov_b32_e32 v19, v2
	v_mov_b32_e32 v20, v2
	v_mov_b32_e32 v21, v2
	v_mov_b32_e32 v22, v2
	v_mov_b32_e32 v23, v2
	v_mov_b32_e32 v24, v2
	v_mov_b32_e32 v25, v2
	v_mov_b32_e32 v26, v2
	v_mov_b32_e32 v27, v2
	v_mov_b32_e32 v28, v2
	v_mov_b32_e32 v29, v2
	v_mov_b32_e32 v42, v2
	v_mov_b32_e32 v43, v2
	v_mov_b32_e32 v44, v2
	v_mov_b32_e32 v45, v2
	v_mov_b32_e32 v46, v2
	v_mov_b32_e32 v47, v2
	v_mov_b32_e32 v48, v2
	v_mov_b32_e32 v49, v2
	v_mov_b32_e32 v50, v2
	v_mov_b32_e32 v51, v2
	v_mov_b32_e32 v52, v2
	v_mov_b32_e32 v53, v2
	v_mov_b32_e32 v54, v2
	v_mov_b32_e32 v55, v2
	v_mov_b32_e32 v56, v2
	v_mov_b32_e32 v57, v2
	v_mov_b32_e32 v58, v2
	v_mov_b32_e32 v59, v2
	v_mov_b32_e32 v60, v2
	v_mov_b32_e32 v61, v2
	v_mov_b32_e32 v62, v2
	v_mov_b32_e32 v63, v2
	v_mov_b32_e32 v64, v2
	v_mov_b32_e32 v65, v2
	v_mov_b32_e32 v66, v2
	v_mov_b32_e32 v67, v2
	v_mov_b32_e32 v68, v2
	v_mov_b32_e32 v69, v2
	v_mov_b32_e32 v70, v2
	v_mov_b32_e32 v71, v2
	v_mov_b32_e32 v72, v2
	v_mov_b32_e32 v73, v2
	v_mov_b32_e32 v74, v2
	v_mov_b32_e32 v75, v2
	v_mov_b32_e32 v76, v2
	v_mov_b32_e32 v77, v2

.LBB0_457:
	s_add_i32 s16, s2, 4
	v_mov_b32_e32 v20, v196
	s_cmp_lt_i32 s2, 8
	s_cselect_b32 s2, s2, s16
	v_lshrrev_b32_e32 v0, 2, v20
	s_lshl_b32 s16, s18, 8
	v_and_b32_e32 v0, 12, v0
	s_movk_i32 s26, 0x1320
	s_ashr_i32 s17, s16, 31
	v_lshrrev_b32_e64 v21, v0, s26
	s_lshl_b32 s18, s2, 7
	s_lshl_b64 s[20:21], s[16:17], 11
	v_xor_b32_e32 v0, v21, v20
	s_add_u32 s22, s36, s20
	v_ashrrev_i32_e32 v2, 2, v20
	v_lshlrev_b32_e32 v0, 4, v0
	s_addc_u32 s23, s37, s21
	v_and_b32_e32 v0, 48, v0
	v_ashrrev_i32_e32 v3, 31, v2
	v_lshl_add_u64 v[4:5], s[22:23], 0, v[0:1]
	v_lshlrev_b64 v[2:3], 11, v[2:3]
	s_mov_b64 s[22:23], 0x20000
	v_lshl_add_u64 v[6:7], v[2:3], 0, s[22:23]
	v_lshl_add_u64 v[8:9], v[4:5], 0, v[6:7]
	v_lshl_add_u64 v[4:5], v[4:5], 0, v[2:3]
	s_mov_b64 s[22:23], 0x40000
	v_lshl_add_u64 v[10:11], v[4:5], 0, s[22:23]
	s_mov_b64 s[22:23], 0x60000
	v_lshl_add_u32 v156, v20, 4, 0
	s_ashr_i32 s19, s18, 31
	v_lshl_add_u64 v[12:13], v[4:5], 0, s[22:23]
	v_readfirstlane_b32 s22, v156
	v_add_u32_e32 v16, 0x1000, v156
	s_lshl_b64 s[20:21], s[18:19], 11
	v_and_b32_e32 v15, 12, v20
	s_mov_b32 m0, s22
	v_readfirstlane_b32 s22, v16
	v_add_u32_e32 v18, 0x2000, v156
	s_add_u32 s24, s59, s20
	v_readlane_b32 s19, v225, 54
	v_lshrrev_b32_e32 v14, 4, v20
	v_lshrrev_b32_e64 v15, v15, s26
	global_load_lds_dwordx4 v[4:5], off
	s_mov_b32 m0, s22
	v_readfirstlane_b32 s22, v18
	s_addc_u32 s25, s19, s21
	v_xor_b32_e32 v14, v15, v14
	global_load_lds_dwordx4 v[8:9], off
	s_mov_b32 m0, s22
	s_mov_b64 s[22:23], 0x40040
	v_add_u32_e32 v18, 0x3000, v156
	v_lshl_add_u64 v[6:7], s[24:25], 0, v[6:7]
	v_lshlrev_b32_e32 v23, 4, v14
	global_load_lds_dwordx4 v[10:11], off
	v_lshl_add_u64 v[10:11], v[4:5], 0, s[22:23]
	v_readfirstlane_b32 s22, v18
	v_lshl_add_u64 v[18:19], s[24:25], 0, v[2:3]
	s_mov_b32 m0, s22
	s_mov_b64 s[22:23], 0x60040
	v_lshl_add_u64 v[18:19], v[18:19], 0, v[0:1]
	v_lshl_add_u64 v[6:7], v[6:7], 0, v[0:1]
	v_and_b32_e32 v0, 48, v23
	v_add_u32_e32 v23, 0x4000, v156
	global_load_lds_dwordx4 v[12:13], off
	v_lshl_add_u64 v[12:13], v[4:5], 0, s[22:23]
	v_readfirstlane_b32 s22, v23
	v_add_u32_e32 v23, 0x5000, v156
	s_mov_b32 m0, s22
	v_readfirstlane_b32 s22, v23
	v_add_u32_e32 v23, 0x6000, v156
	global_load_lds_dwordx4 v[18:19], off
	s_mov_b32 m0, s22
	v_readfirstlane_b32 s22, v23
	v_lshl_add_u64 v[14:15], v[4:5], 0, 64
	global_load_lds_dwordx4 v[6:7], off
	s_mov_b32 m0, s22
	v_lshl_add_u64 v[16:17], v[8:9], 0, 64
	global_load_lds_dwordx4 v[14:15], off
	v_add_u32_e32 v14, 0x7000, v156
	v_lshl_add_u64 v[18:19], v[18:19], 0, 64
	v_readfirstlane_b32 s22, v14
	v_add_u32_e32 v14, 0x8000, v156
	s_mov_b32 m0, s22
	v_readfirstlane_b32 s22, v14
	global_load_lds_dwordx4 v[16:17], off
	s_mov_b32 m0, s22
	v_lshl_add_u64 v[6:7], v[6:7], 0, 64
	global_load_lds_dwordx4 v[10:11], off
	v_add_u32_e32 v10, 0x9000, v156
	v_lshl_add_u64 v[148:149], v[4:5], 0, s[78:79]
	v_readfirstlane_b32 s22, v10
	v_add_u32_e32 v10, 0xa000, v156
	s_mov_b32 m0, s22
	v_readfirstlane_b32 s22, v10
	v_add_u32_e32 v10, 0xb000, v156
	global_load_lds_dwordx4 v[12:13], off
	s_mov_b32 m0, s22
	v_readfirstlane_b32 s22, v10
	global_load_lds_dwordx4 v[18:19], off
	s_mov_b32 m0, s22
	s_mov_b64 s[22:23], 0x60080
	global_load_lds_dwordx4 v[6:7], off
	v_lshl_add_u64 v[146:147], v[4:5], 0, s[22:23]
	s_mov_b64 s[22:23], 0x40080
	v_lshl_add_u64 v[152:153], v[4:5], 0, s[22:23]
	v_lshl_add_u64 v[2:3], v[2:3], 0, s[20:21]
	v_bitop3_b32 v4, v21, 3, v20 bitop3:0x48
	v_lshl_or_b32 v2, v4, 4, v2
	v_lshlrev_b32_e32 v22, 6, v20
	v_lshl_add_u64 v[154:155], s[14:15], 0, v[2:3]
	v_mov_b32_e32 v2, 0
	s_mov_b32 s19, 2
	v_and_b32_e32 v157, 0x13c0, v22
	v_and_b32_e32 v158, 0xffffe3c0, v22
	v_lshl_add_u64 v[150:151], v[8:9], 0, s[78:79]
	s_mov_b32 s22, 0
	s_mov_b64 s[20:21], 0
	v_mov_b32_e32 v3, v2
	v_mov_b32_e32 v4, v2
	v_mov_b32_e32 v5, v2
	v_mov_b32_e32 v6, v2
	v_mov_b32_e32 v7, v2
	v_mov_b32_e32 v8, v2
	v_mov_b32_e32 v9, v2
	v_mov_b32_e32 v10, v2
	v_mov_b32_e32 v11, v2
	v_mov_b32_e32 v12, v2
	v_mov_b32_e32 v13, v2
	v_mov_b32_e32 v14, v2
	v_mov_b32_e32 v15, v2
	v_mov_b32_e32 v16, v2
	v_mov_b32_e32 v17, v2
	v_mov_b32_e32 v18, v2
	v_mov_b32_e32 v19, v2
	v_mov_b32_e32 v20, v2
	v_mov_b32_e32 v21, v2
	v_mov_b32_e32 v22, v2
	v_mov_b32_e32 v23, v2
	v_mov_b32_e32 v24, v2
	v_mov_b32_e32 v25, v2
	v_mov_b32_e32 v26, v2
	v_mov_b32_e32 v27, v2
	v_mov_b32_e32 v28, v2
	v_mov_b32_e32 v29, v2
	v_mov_b32_e32 v34, v2
	v_mov_b32_e32 v35, v2
	v_mov_b32_e32 v36, v2
	v_mov_b32_e32 v37, v2
	v_mov_b32_e32 v30, v2
	v_mov_b32_e32 v31, v2
	v_mov_b32_e32 v32, v2
	v_mov_b32_e32 v33, v2
	v_mov_b32_e32 v38, v2
	v_mov_b32_e32 v39, v2
	v_mov_b32_e32 v40, v2
	v_mov_b32_e32 v41, v2
	v_mov_b32_e32 v42, v2
	v_mov_b32_e32 v43, v2
	v_mov_b32_e32 v44, v2
	v_mov_b32_e32 v45, v2
	v_mov_b32_e32 v46, v2
	v_mov_b32_e32 v47, v2
	v_mov_b32_e32 v48, v2
	v_mov_b32_e32 v49, v2
	v_mov_b32_e32 v50, v2
	v_mov_b32_e32 v51, v2
	v_mov_b32_e32 v52, v2
	v_mov_b32_e32 v53, v2
	v_mov_b32_e32 v54, v2
	v_mov_b32_e32 v55, v2
	v_mov_b32_e32 v56, v2
	v_mov_b32_e32 v57, v2
	v_mov_b32_e32 v58, v2
	v_mov_b32_e32 v59, v2
	v_mov_b32_e32 v60, v2
	v_mov_b32_e32 v61, v2
	v_mov_b32_e32 v66, v2
	v_mov_b32_e32 v67, v2
	v_mov_b32_e32 v68, v2
	v_mov_b32_e32 v69, v2
	v_mov_b32_e32 v62, v2
	v_mov_b32_e32 v63, v2
	v_mov_b32_e32 v64, v2
	v_mov_b32_e32 v65, v2
	v_mov_b32_e32 v70, v2
	v_mov_b32_e32 v71, v2
	v_mov_b32_e32 v72, v2
	v_mov_b32_e32 v73, v2
	v_mov_b32_e32 v74, v2
	v_mov_b32_e32 v75, v2
	v_mov_b32_e32 v76, v2
	v_mov_b32_e32 v77, v2
	v_mov_b32_e32 v78, v2
	v_mov_b32_e32 v79, v2
	v_mov_b32_e32 v80, v2
	v_mov_b32_e32 v81, v2
	v_mov_b32_e32 v82, v2
	v_mov_b32_e32 v83, v2
	v_mov_b32_e32 v84, v2
	v_mov_b32_e32 v85, v2
	v_mov_b32_e32 v86, v2
	v_mov_b32_e32 v87, v2
	v_mov_b32_e32 v88, v2
	v_mov_b32_e32 v89, v2
	v_mov_b32_e32 v90, v2
	v_mov_b32_e32 v91, v2
	v_mov_b32_e32 v92, v2
	v_mov_b32_e32 v93, v2
	v_mov_b32_e32 v94, v2
	v_mov_b32_e32 v95, v2
	v_mov_b32_e32 v96, v2
	v_mov_b32_e32 v97, v2
	v_mov_b32_e32 v98, v2
	v_mov_b32_e32 v99, v2
	v_mov_b32_e32 v100, v2
	v_mov_b32_e32 v101, v2
	v_mov_b32_e32 v102, v2
	v_mov_b32_e32 v103, v2
	v_mov_b32_e32 v104, v2
	v_mov_b32_e32 v105, v2
	v_mov_b32_e32 v106, v2
	v_mov_b32_e32 v107, v2
	v_mov_b32_e32 v108, v2
	v_mov_b32_e32 v109, v2
	v_mov_b32_e32 v110, v2
	v_mov_b32_e32 v111, v2
	v_mov_b32_e32 v112, v2
	v_mov_b32_e32 v113, v2
	v_mov_b32_e32 v114, v2
	v_mov_b32_e32 v115, v2
	v_mov_b32_e32 v116, v2
	v_mov_b32_e32 v117, v2
	v_mov_b32_e32 v118, v2
	v_mov_b32_e32 v119, v2
	v_mov_b32_e32 v120, v2
	v_mov_b32_e32 v121, v2
	v_mov_b32_e32 v122, v2
	v_mov_b32_e32 v123, v2
	v_mov_b32_e32 v124, v2
	v_mov_b32_e32 v125, v2
	v_mov_b32_e32 v126, v2
	v_mov_b32_e32 v127, v2
	v_mov_b32_e32 v128, v2
	v_mov_b32_e32 v129, v2
	s_mov_b64 s[24:25], 0x200c0
